# speedup vs baseline: 1.0131x; 1.0131x over previous
; #define WAIT_V(n) asm volatile("s_waitcnt vmcnt(" #n ")" ::: "memory")
; #define BAR __builtin_amdgcn_s_barrier()
;     ...
;     f32x4 acc[2][2][4][2] = {};
;     bf16x8 At[4][2], B0[2][2], B1[2][2];
;     STAGE(SB(0, 0), Bt, bcol, 0); STAGE(SA(0, 0), A, brow, 0);
;     STAGE(SB(0, 1), Bt, bcol + HALF, 0); STAGE(SA(0, 1), A, brow + HALF, 0);
;     if (wr == 1) BAR;
;     WAIT_V(4); BAR;
.Lp1_hdr2:
	v_mov_b64_e32 v[22:23], 0
	v_mov_b64_e32 v[24:25], 0
	v_mov_b64_e32 v[26:27], 0
	v_mov_b64_e32 v[28:29], 0
	v_mov_b64_e32 v[30:31], 0
	v_mov_b64_e32 v[32:33], 0
	v_mov_b64_e32 v[34:35], 0
	v_mov_b64_e32 v[36:37], 0
	v_mov_b64_e32 v[38:39], 0
	v_mov_b64_e32 v[40:41], 0
	v_mov_b64_e32 v[42:43], 0
	v_mov_b64_e32 v[44:45], 0
	v_mov_b64_e32 v[46:47], 0
	v_mov_b64_e32 v[48:49], 0
	v_mov_b64_e32 v[50:51], 0
	v_mov_b64_e32 v[52:53], 0
	v_mov_b64_e32 v[54:55], 0
	v_mov_b64_e32 v[56:57], 0
	v_mov_b64_e32 v[58:59], 0
	v_mov_b64_e32 v[60:61], 0
	v_mov_b64_e32 v[62:63], 0
	v_mov_b64_e32 v[64:65], 0
	v_mov_b64_e32 v[66:67], 0
	v_mov_b64_e32 v[68:69], 0
	v_mov_b64_e32 v[70:71], 0
	v_mov_b64_e32 v[72:73], 0
	v_mov_b64_e32 v[74:75], 0
	v_mov_b64_e32 v[76:77], 0
	v_mov_b64_e32 v[78:79], 0
	v_mov_b64_e32 v[80:81], 0
	v_mov_b64_e32 v[82:83], 0
	v_mov_b64_e32 v[84:85], 0
	v_mov_b64_e32 v[86:87], 0
	v_mov_b64_e32 v[88:89], 0
	v_mov_b64_e32 v[90:91], 0
	v_mov_b64_e32 v[92:93], 0
	v_mov_b64_e32 v[94:95], 0
	v_mov_b64_e32 v[96:97], 0
	v_mov_b64_e32 v[98:99], 0
	v_mov_b64_e32 v[100:101], 0
	v_mov_b64_e32 v[102:103], 0
	v_mov_b64_e32 v[104:105], 0
	v_mov_b64_e32 v[106:107], 0
	v_mov_b64_e32 v[108:109], 0
	v_mov_b64_e32 v[110:111], 0
	v_mov_b64_e32 v[112:113], 0
	v_mov_b64_e32 v[114:115], 0
	v_mov_b64_e32 v[116:117], 0
	v_mov_b64_e32 v[118:119], 0
	v_mov_b64_e32 v[120:121], 0
	v_mov_b64_e32 v[122:123], 0
	v_mov_b64_e32 v[124:125], 0
	v_mov_b64_e32 v[126:127], 0
	v_cmp_eq_u32_e32 vcc, 1, v220
	s_and_saveexec_b64 s[22:23], vcc
	s_cbranch_execz .LBB0_97
	s_setprio 1
	s_barrier

; #define WAIT_V(n) asm volatile("s_waitcnt vmcnt(" #n ")" ::: "memory")
; #define WAIT_L(n) asm volatile("s_waitcnt lgkmcnt(" #n ")" ::: "memory")
; #define BAR __builtin_amdgcn_s_barrier()
; #define SCHED __builtin_amdgcn_sched_barrier(0)
;     ...
;       LDB(B0, 0, 0); SCHED; LDA(At, 0, 0); STAGE(SA(1, 1), A, brow + HALF, t + 1);
;       WAIT_L(8); BAR; WAIT_L(0); MMA(0, 0, At, B0); BAR; SCHED;
;       LDB(B1, 0, 1); STAGE(SB(0, 0), Bt, bcol, t + 2);
;       BAR; WAIT_L(0); MMA(0, 1, At, B1); BAR;
;       LDA(At, 0, 1); STAGE(SA(0, 0), A, brow, t + 2);
;       BAR; WAIT_L(0); MMA(1, 0, At, B0); BAR; SCHED;
;       STAGE(SB(0, 1), Bt, bcol + HALF, t + 2);
;       WAIT_V(6); BAR; MMA(1, 1, At, B1); BAR;
.LBB0_98:
	v_add_u32_e32 v167, 0xc000, v153
	v_add_u32_e32 v168, 0xe000, v153
	v_add_u32_e32 v169, 0x2000, v147
	v_add_u32_e32 v169, 0x2000, v155
	ds_read_b128 v[170:173], v166
	ds_read_b128 v[174:177], v166 offset:1024
	ds_read_b128 v[178:181], v166 offset:2048
	ds_read_b128 v[182:185], v166 offset:3072
	ds_read_b128 v[186:189], v151
	ds_read_b128 v[190:193], v151 offset:1024
	ds_read_b128 v[196:199], v150
	ds_read_b128 v[200:203], v150 offset:1024
	ds_read_b128 v[204:207], v149
	ds_read_b128 v[208:211], v149 offset:1024
	ds_read_b128 v[212:215], v148
	ds_read_b128 v[216:219], v148 offset:1024
	ds_read_b128 v[220:223], v165
	ds_read_b128 v[224:227], v165 offset:1024
	ds_read_b128 v[228:231], v165 offset:2048
	ds_read_b128 v[232:235], v165 offset:3072
	v_add_u32_e32 v254, 0xc000, v153
	v_lshl_add_u64 v[250:251], v[138:139], 0, s[18:19]
	v_readfirstlane_b32 s20, v254
	v_lshl_add_u64 v[250:251], v[250:251], 0, s[2:3]
	s_mov_b32 m0, s20
	s_nop 0
	global_load_lds_dwordx4 v[250:251], off
	v_add_u32_e32 v254, 0xe000, v153
	v_lshl_add_u64 v[252:253], v[140:141], 0, s[18:19]
	v_readfirstlane_b32 s20, v254
	v_lshl_add_u64 v[252:253], v[252:253], 0, s[2:3]
	s_mov_b32 m0, s20
	s_nop 0
	global_load_lds_dwordx4 v[252:253], off
	s_waitcnt lgkmcnt(0)
	s_barrier
	v_mfma_f32_16x16x32_bf16 v[124:127], v[170:173], v[186:189], v[124:127]
	v_mfma_f32_16x16x32_bf16 v[120:123], v[178:181], v[186:189], v[120:123]
	v_mfma_f32_16x16x32_bf16 v[116:119], v[170:173], v[196:199], v[116:119]
	v_mfma_f32_16x16x32_bf16 v[112:115], v[178:181], v[196:199], v[112:115]
	v_mfma_f32_16x16x32_bf16 v[108:111], v[170:173], v[204:207], v[108:111]
	v_mfma_f32_16x16x32_bf16 v[104:107], v[178:181], v[204:207], v[104:107]
	v_mfma_f32_16x16x32_bf16 v[100:103], v[170:173], v[212:215], v[100:103]
	v_mfma_f32_16x16x32_bf16 v[96:99], v[178:181], v[212:215], v[96:99]
	v_mfma_f32_16x16x32_bf16 v[124:127], v[174:177], v[190:193], v[124:127]
	v_mfma_f32_16x16x32_bf16 v[120:123], v[182:185], v[190:193], v[120:123]
	v_mfma_f32_16x16x32_bf16 v[116:119], v[174:177], v[200:203], v[116:119]
	v_mfma_f32_16x16x32_bf16 v[112:115], v[182:185], v[200:203], v[112:115]
	v_mfma_f32_16x16x32_bf16 v[108:111], v[174:177], v[208:211], v[108:111]
	v_mfma_f32_16x16x32_bf16 v[104:107], v[182:185], v[208:211], v[104:107]
	v_mfma_f32_16x16x32_bf16 v[100:103], v[174:177], v[216:219], v[100:103]
	v_mfma_f32_16x16x32_bf16 v[96:99], v[182:185], v[216:219], v[96:99]
	v_mfma_f32_16x16x32_bf16 v[92:95], v[220:223], v[186:189], v[92:95]
	v_mfma_f32_16x16x32_bf16 v[88:91], v[228:231], v[186:189], v[88:91]
	v_mfma_f32_16x16x32_bf16 v[84:87], v[220:223], v[196:199], v[84:87]
	v_mfma_f32_16x16x32_bf16 v[80:83], v[228:231], v[196:199], v[80:83]
	v_mfma_f32_16x16x32_bf16 v[76:79], v[220:223], v[204:207], v[76:79]
	v_mfma_f32_16x16x32_bf16 v[72:75], v[228:231], v[204:207], v[72:75]
	v_mfma_f32_16x16x32_bf16 v[68:71], v[220:223], v[212:215], v[68:71]
	v_mfma_f32_16x16x32_bf16 v[64:67], v[228:231], v[212:215], v[64:67]
	v_mfma_f32_16x16x32_bf16 v[92:95], v[224:227], v[190:193], v[92:95]
	v_mfma_f32_16x16x32_bf16 v[88:91], v[232:235], v[190:193], v[88:91]
	v_mfma_f32_16x16x32_bf16 v[84:87], v[224:227], v[200:203], v[84:87]
	v_mfma_f32_16x16x32_bf16 v[80:83], v[232:235], v[200:203], v[80:83]
	v_mfma_f32_16x16x32_bf16 v[76:79], v[224:227], v[208:211], v[76:79]
	v_mfma_f32_16x16x32_bf16 v[72:75], v[232:235], v[208:211], v[72:75]
	v_mfma_f32_16x16x32_bf16 v[68:71], v[224:227], v[216:219], v[68:71]
	v_mfma_f32_16x16x32_bf16 v[64:67], v[232:235], v[216:219], v[64:67]
	s_barrier
	ds_read_b128 v[186:189], v151 offset:16384
	ds_read_b128 v[190:193], v151 offset:17408
	ds_read_b128 v[196:199], v150 offset:16384
	ds_read_b128 v[200:203], v150 offset:17408
	ds_read_b128 v[204:207], v149 offset:16384
	ds_read_b128 v[208:211], v149 offset:17408
	ds_read_b128 v[212:215], v148 offset:16384
	ds_read_b128 v[216:219], v148 offset:17408
	v_lshl_add_u64 v[250:251], v[134:135], 0, s[18:19]
	v_readfirstlane_b32 s20, v147
	v_lshl_add_u64 v[250:251], v[250:251], 0, s[4:5]
	s_mov_b32 m0, s20
	s_nop 0
	global_load_lds_dwordx4 v[250:251], off
	v_add_u32_e32 v254, 0x2000, v147
	v_lshl_add_u64 v[252:253], v[136:137], 0, s[18:19]
	v_readfirstlane_b32 s20, v254
	v_lshl_add_u64 v[252:253], v[252:253], 0, s[4:5]
	s_mov_b32 m0, s20
	s_nop 0
	global_load_lds_dwordx4 v[252:253], off
	v_lshl_add_u64 v[250:251], v[138:139], 0, s[18:19]
	v_readfirstlane_b32 s20, v153
	v_lshl_add_u64 v[250:251], v[250:251], 0, s[4:5]
	s_mov_b32 m0, s20
	s_nop 0
	global_load_lds_dwordx4 v[250:251], off
	v_lshl_add_u64 v[252:253], v[140:141], 0, s[18:19]
	v_readfirstlane_b32 s20, v154
	v_lshl_add_u64 v[252:253], v[252:253], 0, s[4:5]
	s_mov_b32 m0, s20
	s_nop 0
	global_load_lds_dwordx4 v[252:253], off
	v_lshl_add_u64 v[250:251], v[134:135], 0, s[18:19]
	v_readfirstlane_b32 s20, v155
	v_lshl_add_u64 v[250:251], v[250:251], 0, s[6:7]
	s_mov_b32 m0, s20
	s_nop 0
	global_load_lds_dwordx4 v[250:251], off
	v_add_u32_e32 v254, 0x2000, v155
	v_lshl_add_u64 v[252:253], v[136:137], 0, s[18:19]
	v_readfirstlane_b32 s20, v254
	v_lshl_add_u64 v[252:253], v[252:253], 0, s[6:7]
	s_mov_b32 m0, s20
	s_nop 0
	global_load_lds_dwordx4 v[252:253], off
	s_waitcnt vmcnt(6)
	s_waitcnt lgkmcnt(0)
	s_barrier
; #define WAIT_V(n) asm volatile("s_waitcnt vmcnt(" #n ")" ::: "memory")
; #define WAIT_L(n) asm volatile("s_waitcnt lgkmcnt(" #n ")" ::: "memory")
; #define BAR __builtin_amdgcn_s_barrier()
; #define SCHED __builtin_amdgcn_sched_barrier(0)
;     ...
;       WAIT_V(6); BAR; MMA(1, 1, At, B1); BAR;
;       LDB(B0, 1, 0); SCHED; LDA(At, 1, 0); STAGE(SA(0, 1), A, brow + HALF, t + 2);
;       WAIT_L(8); BAR; WAIT_L(0); MMA(0, 0, At, B0); BAR; SCHED;
;       LDB(B1, 1, 1); STAGE(SB(1, 0), Bt, bcol, t + 3);
;       BAR; WAIT_L(0); MMA(0, 1, At, B1); BAR;
;       LDA(At, 1, 1); STAGE(SA(1, 0), A, brow, t + 3);
;       BAR; WAIT_L(0); MMA(1, 0, At, B0); BAR; SCHED;
;       STAGE(SB(1, 1), Bt, bcol + HALF, t + 3);
	v_mfma_f32_16x16x32_bf16 v[60:63], v[170:173], v[186:189], v[60:63]
	v_mfma_f32_16x16x32_bf16 v[56:59], v[178:181], v[186:189], v[56:59]
	v_mfma_f32_16x16x32_bf16 v[52:55], v[170:173], v[196:199], v[52:55]
	v_mfma_f32_16x16x32_bf16 v[48:51], v[178:181], v[196:199], v[48:51]
	v_mfma_f32_16x16x32_bf16 v[44:47], v[170:173], v[204:207], v[44:47]
	v_mfma_f32_16x16x32_bf16 v[40:43], v[178:181], v[204:207], v[40:43]
	v_mfma_f32_16x16x32_bf16 v[36:39], v[170:173], v[212:215], v[36:39]
	v_mfma_f32_16x16x32_bf16 v[32:35], v[178:181], v[212:215], v[32:35]
	v_mfma_f32_16x16x32_bf16 v[60:63], v[174:177], v[190:193], v[60:63]
	v_mfma_f32_16x16x32_bf16 v[56:59], v[182:185], v[190:193], v[56:59]
	v_mfma_f32_16x16x32_bf16 v[52:55], v[174:177], v[200:203], v[52:55]
	v_mfma_f32_16x16x32_bf16 v[48:51], v[182:185], v[200:203], v[48:51]
	v_mfma_f32_16x16x32_bf16 v[44:47], v[174:177], v[208:211], v[44:47]
	v_mfma_f32_16x16x32_bf16 v[40:43], v[182:185], v[208:211], v[40:43]
	v_mfma_f32_16x16x32_bf16 v[36:39], v[174:177], v[216:219], v[36:39]
	v_mfma_f32_16x16x32_bf16 v[32:35], v[182:185], v[216:219], v[32:35]
	v_mfma_f32_16x16x32_bf16 v[28:31], v[220:223], v[186:189], v[28:31]
	v_mfma_f32_16x16x32_bf16 v[24:27], v[228:231], v[186:189], v[24:27]
	v_mfma_f32_16x16x32_bf16 v[20:23], v[220:223], v[196:199], v[20:23]
	v_mfma_f32_16x16x32_bf16 v[16:19], v[228:231], v[196:199], v[16:19]
	v_mfma_f32_16x16x32_bf16 v[12:15], v[220:223], v[204:207], v[12:15]
	v_mfma_f32_16x16x32_bf16 v[8:11], v[228:231], v[204:207], v[8:11]
	v_mfma_f32_16x16x32_bf16 v[4:7], v[220:223], v[212:215], v[4:7]
	v_mfma_f32_16x16x32_bf16 v[0:3], v[228:231], v[212:215], v[0:3]
	v_mfma_f32_16x16x32_bf16 v[28:31], v[224:227], v[190:193], v[28:31]
	v_mfma_f32_16x16x32_bf16 v[24:27], v[232:235], v[190:193], v[24:27]
	v_mfma_f32_16x16x32_bf16 v[20:23], v[224:227], v[200:203], v[20:23]
	v_mfma_f32_16x16x32_bf16 v[16:19], v[232:235], v[200:203], v[16:19]
	v_mfma_f32_16x16x32_bf16 v[12:15], v[224:227], v[208:211], v[12:15]
	v_mfma_f32_16x16x32_bf16 v[8:11], v[232:235], v[208:211], v[8:11]
	v_mfma_f32_16x16x32_bf16 v[4:7], v[224:227], v[216:219], v[4:7]
	v_mfma_f32_16x16x32_bf16 v[0:3], v[232:235], v[216:219], v[0:3]
	s_barrier
	ds_read_b128 v[170:173], v156
	ds_read_b128 v[174:177], v156 offset:1024
	ds_read_b128 v[178:181], v156 offset:2048
	ds_read_b128 v[182:185], v156 offset:3072
	ds_read_b128 v[186:189], v151 offset:32768
	ds_read_b128 v[190:193], v151 offset:33792
	ds_read_b128 v[196:199], v150 offset:32768
	ds_read_b128 v[200:203], v150 offset:33792
	ds_read_b128 v[204:207], v149 offset:32768
	ds_read_b128 v[208:211], v149 offset:33792
	ds_read_b128 v[212:215], v148 offset:32768
	ds_read_b128 v[216:219], v148 offset:33792
	ds_read_b128 v[220:223], v152
	ds_read_b128 v[224:227], v152 offset:1024
	ds_read_b128 v[228:231], v152 offset:2048
	ds_read_b128 v[232:235], v152 offset:3072
	v_lshl_add_u64 v[250:251], v[138:139], 0, s[18:19]
	v_readfirstlane_b32 s20, v157
	v_lshl_add_u64 v[250:251], v[250:251], 0, s[6:7]
	s_mov_b32 m0, s20
	s_nop 0
	global_load_lds_dwordx4 v[250:251], off
	v_lshl_add_u64 v[252:253], v[140:141], 0, s[18:19]
	v_readfirstlane_b32 s20, v158
	v_lshl_add_u64 v[252:253], v[252:253], 0, s[6:7]
	s_mov_b32 m0, s20
	s_nop 0
	global_load_lds_dwordx4 v[252:253], off
	s_waitcnt lgkmcnt(0)
	s_barrier
	v_mfma_f32_16x16x32_bf16 v[124:127], v[170:173], v[186:189], v[124:127]
	v_mfma_f32_16x16x32_bf16 v[120:123], v[178:181], v[186:189], v[120:123]
	v_mfma_f32_16x16x32_bf16 v[116:119], v[170:173], v[196:199], v[116:119]
	v_mfma_f32_16x16x32_bf16 v[112:115], v[178:181], v[196:199], v[112:115]
	v_mfma_f32_16x16x32_bf16 v[108:111], v[170:173], v[204:207], v[108:111]
	v_mfma_f32_16x16x32_bf16 v[104:107], v[178:181], v[204:207], v[104:107]
	v_mfma_f32_16x16x32_bf16 v[100:103], v[170:173], v[212:215], v[100:103]
	v_mfma_f32_16x16x32_bf16 v[96:99], v[178:181], v[212:215], v[96:99]
	v_mfma_f32_16x16x32_bf16 v[124:127], v[174:177], v[190:193], v[124:127]
	v_mfma_f32_16x16x32_bf16 v[120:123], v[182:185], v[190:193], v[120:123]
	v_mfma_f32_16x16x32_bf16 v[116:119], v[174:177], v[200:203], v[116:119]
	v_mfma_f32_16x16x32_bf16 v[112:115], v[182:185], v[200:203], v[112:115]
	v_mfma_f32_16x16x32_bf16 v[108:111], v[174:177], v[208:211], v[108:111]
	v_mfma_f32_16x16x32_bf16 v[104:107], v[182:185], v[208:211], v[104:107]
	v_mfma_f32_16x16x32_bf16 v[100:103], v[174:177], v[216:219], v[100:103]
	v_mfma_f32_16x16x32_bf16 v[96:99], v[182:185], v[216:219], v[96:99]
	v_mfma_f32_16x16x32_bf16 v[92:95], v[220:223], v[186:189], v[92:95]
	v_mfma_f32_16x16x32_bf16 v[88:91], v[228:231], v[186:189], v[88:91]
	v_mfma_f32_16x16x32_bf16 v[84:87], v[220:223], v[196:199], v[84:87]
	v_mfma_f32_16x16x32_bf16 v[80:83], v[228:231], v[196:199], v[80:83]
	v_mfma_f32_16x16x32_bf16 v[76:79], v[220:223], v[204:207], v[76:79]
	v_mfma_f32_16x16x32_bf16 v[72:75], v[228:231], v[204:207], v[72:75]
	v_mfma_f32_16x16x32_bf16 v[68:71], v[220:223], v[212:215], v[68:71]
	v_mfma_f32_16x16x32_bf16 v[64:67], v[228:231], v[212:215], v[64:67]
	v_mfma_f32_16x16x32_bf16 v[92:95], v[224:227], v[190:193], v[92:95]
	v_mfma_f32_16x16x32_bf16 v[88:91], v[232:235], v[190:193], v[88:91]
	v_mfma_f32_16x16x32_bf16 v[84:87], v[224:227], v[200:203], v[84:87]
	v_mfma_f32_16x16x32_bf16 v[80:83], v[232:235], v[200:203], v[80:83]
	v_mfma_f32_16x16x32_bf16 v[76:79], v[224:227], v[208:211], v[76:79]
	v_mfma_f32_16x16x32_bf16 v[72:75], v[232:235], v[208:211], v[72:75]
	v_mfma_f32_16x16x32_bf16 v[68:71], v[224:227], v[216:219], v[68:71]
	v_mfma_f32_16x16x32_bf16 v[64:67], v[232:235], v[216:219], v[64:67]
	s_barrier
; #define WAIT_V(n) asm volatile("s_waitcnt vmcnt(" #n ")" ::: "memory")
; #define WAIT_L(n) asm volatile("s_waitcnt lgkmcnt(" #n ")" ::: "memory")
; #define BAR __builtin_amdgcn_s_barrier()
; #define SCHED __builtin_amdgcn_sched_barrier(0)
;     ...
;       LDA(At, 1, 1); STAGE(SA(1, 0), A, brow, t + 3);
;       BAR; WAIT_L(0); MMA(1, 0, At, B0); BAR; SCHED;
;       STAGE(SB(1, 1), Bt, bcol + HALF, t + 3);
;       WAIT_V(6); BAR; MMA(1, 1, At, B1); BAR;
;     }
;     { LDB(B0, 0, 0); LDA(At, 0, 0); STAGE(SA(1, 1), A, brow + HALF, nt - 1);
;       BAR; WAIT_L(0); MMA(0, 0, At, B0); BAR;
;       LDB(B1, 0, 1); BAR; WAIT_L(0); MMA(0, 1, At, B1); BAR;
;       LDA(At, 0, 1); WAIT_V(4); BAR; WAIT_L(0); MMA(1, 0, At, B0); MMA(1, 1, At, B1); BAR; }
	ds_read_b128 v[186:189], v151 offset:49152
	ds_read_b128 v[190:193], v151 offset:50176
	ds_read_b128 v[196:199], v150 offset:49152
	ds_read_b128 v[200:203], v150 offset:50176
	ds_read_b128 v[204:207], v149 offset:49152
	ds_read_b128 v[208:211], v149 offset:50176
	ds_read_b128 v[212:215], v148 offset:49152
	ds_read_b128 v[216:219], v148 offset:50176
	v_lshl_add_u64 v[250:251], v[134:135], 0, s[18:19]
	v_readfirstlane_b32 s20, v159
	v_lshl_add_u64 v[250:251], v[250:251], 0, s[8:9]
	s_mov_b32 m0, s20
	s_nop 0
	global_load_lds_dwordx4 v[250:251], off
	v_lshl_add_u64 v[252:253], v[136:137], 0, s[18:19]
	v_readfirstlane_b32 s20, v160
	v_lshl_add_u64 v[252:253], v[252:253], 0, s[8:9]
	s_mov_b32 m0, s20
	s_nop 0
	global_load_lds_dwordx4 v[252:253], off
	v_lshl_add_u64 v[250:251], v[138:139], 0, s[18:19]
	v_readfirstlane_b32 s20, v161
	v_lshl_add_u64 v[250:251], v[250:251], 0, s[8:9]
	s_mov_b32 m0, s20
	s_nop 0
	global_load_lds_dwordx4 v[250:251], off
	v_lshl_add_u64 v[252:253], v[140:141], 0, s[18:19]
	v_readfirstlane_b32 s20, v162
	v_lshl_add_u64 v[252:253], v[252:253], 0, s[8:9]
	s_mov_b32 m0, s20
	s_nop 0
	global_load_lds_dwordx4 v[252:253], off
	v_lshl_add_u64 v[250:251], v[134:135], 0, s[18:19]
	v_readfirstlane_b32 s20, v163
	v_lshl_add_u64 v[250:251], v[250:251], 0, s[10:11]
	s_mov_b32 m0, s20
	s_nop 0
	global_load_lds_dwordx4 v[250:251], off
	v_lshl_add_u64 v[252:253], v[136:137], 0, s[18:19]
	v_readfirstlane_b32 s20, v164
	v_lshl_add_u64 v[252:253], v[252:253], 0, s[10:11]
	s_mov_b32 m0, s20
	s_nop 0
	global_load_lds_dwordx4 v[252:253], off
	s_waitcnt vmcnt(6)
	s_waitcnt lgkmcnt(0)
	s_barrier
	v_mfma_f32_16x16x32_bf16 v[60:63], v[170:173], v[186:189], v[60:63]
	v_mfma_f32_16x16x32_bf16 v[56:59], v[178:181], v[186:189], v[56:59]
	v_mfma_f32_16x16x32_bf16 v[52:55], v[170:173], v[196:199], v[52:55]
	v_mfma_f32_16x16x32_bf16 v[48:51], v[178:181], v[196:199], v[48:51]
	v_mfma_f32_16x16x32_bf16 v[44:47], v[170:173], v[204:207], v[44:47]
	v_mfma_f32_16x16x32_bf16 v[40:43], v[178:181], v[204:207], v[40:43]
	v_mfma_f32_16x16x32_bf16 v[36:39], v[170:173], v[212:215], v[36:39]
	v_mfma_f32_16x16x32_bf16 v[32:35], v[178:181], v[212:215], v[32:35]
	v_mfma_f32_16x16x32_bf16 v[60:63], v[174:177], v[190:193], v[60:63]
	v_mfma_f32_16x16x32_bf16 v[56:59], v[182:185], v[190:193], v[56:59]
	v_mfma_f32_16x16x32_bf16 v[52:55], v[174:177], v[200:203], v[52:55]
	v_mfma_f32_16x16x32_bf16 v[48:51], v[182:185], v[200:203], v[48:51]
	v_mfma_f32_16x16x32_bf16 v[44:47], v[174:177], v[208:211], v[44:47]
	v_mfma_f32_16x16x32_bf16 v[40:43], v[182:185], v[208:211], v[40:43]
	v_mfma_f32_16x16x32_bf16 v[36:39], v[174:177], v[216:219], v[36:39]
	v_mfma_f32_16x16x32_bf16 v[32:35], v[182:185], v[216:219], v[32:35]
	v_mfma_f32_16x16x32_bf16 v[28:31], v[220:223], v[186:189], v[28:31]
	v_mfma_f32_16x16x32_bf16 v[24:27], v[228:231], v[186:189], v[24:27]
	v_mfma_f32_16x16x32_bf16 v[20:23], v[220:223], v[196:199], v[20:23]
	v_mfma_f32_16x16x32_bf16 v[16:19], v[228:231], v[196:199], v[16:19]
	v_mfma_f32_16x16x32_bf16 v[12:15], v[220:223], v[204:207], v[12:15]
	v_mfma_f32_16x16x32_bf16 v[8:11], v[228:231], v[204:207], v[8:11]
	v_mfma_f32_16x16x32_bf16 v[4:7], v[220:223], v[212:215], v[4:7]
	v_mfma_f32_16x16x32_bf16 v[0:3], v[228:231], v[212:215], v[0:3]
	v_mfma_f32_16x16x32_bf16 v[28:31], v[224:227], v[190:193], v[28:31]
	v_mfma_f32_16x16x32_bf16 v[24:27], v[232:235], v[190:193], v[24:27]
	v_mfma_f32_16x16x32_bf16 v[20:23], v[224:227], v[200:203], v[20:23]
	v_mfma_f32_16x16x32_bf16 v[16:19], v[232:235], v[200:203], v[16:19]
	v_mfma_f32_16x16x32_bf16 v[12:15], v[224:227], v[208:211], v[12:15]
	v_mfma_f32_16x16x32_bf16 v[8:11], v[232:235], v[208:211], v[8:11]
	v_mfma_f32_16x16x32_bf16 v[4:7], v[224:227], v[216:219], v[4:7]
	v_mfma_f32_16x16x32_bf16 v[0:3], v[232:235], v[216:219], v[0:3]
	s_add_i32 s17, s17, 2
	s_add_u32 s18, s18, 0x100
	s_addc_u32 s19, s19, 0
	s_cmp_gt_u32 s17, 27
	s_barrier
	s_cbranch_scc0 .LBB0_98
	v_readfirstlane_b32 s17, v167
	v_lshl_add_u64 v[130:131], v[130:131], 0, s[12:13]
	s_mov_b32 m0, s17
	v_readfirstlane_b32 s17, v168
	ds_read_b128 v[134:137], v166
	ds_read_b128 v[138:141], v166 offset:1024
	ds_read_b128 v[158:161], v166 offset:2048
	ds_read_b128 v[170:173], v166 offset:3072
	ds_read_b128 v[174:177], v151
	ds_read_b128 v[178:181], v151 offset:1024
	ds_read_b128 v[182:185], v150
	ds_read_b128 v[186:189], v150 offset:1024
	ds_read_b128 v[190:193], v149
	ds_read_b128 v[196:199], v149 offset:1024
	ds_read_b128 v[200:203], v148
	ds_read_b128 v[204:207], v148 offset:1024
	global_load_lds_dwordx4 v[130:131], off
	v_lshl_add_u64 v[130:131], v[132:133], 0, s[12:13]
	s_mov_b32 m0, s17
	s_nop 0
	global_load_lds_dwordx4 v[130:131], off
	s_barrier
	s_waitcnt lgkmcnt(0)
	s_waitcnt lgkmcnt(0)
	v_mfma_f32_16x16x32_bf16 v[124:127], v[134:137], v[174:177], v[124:127]
	v_mfma_f32_16x16x32_bf16 v[120:123], v[158:161], v[174:177], v[120:123]
	v_mfma_f32_16x16x32_bf16 v[116:119], v[134:137], v[182:185], v[116:119]
	v_mfma_f32_16x16x32_bf16 v[112:115], v[158:161], v[182:185], v[112:115]
	v_mfma_f32_16x16x32_bf16 v[100:103], v[134:137], v[200:203], v[100:103]
	v_mfma_f32_16x16x32_bf16 v[124:127], v[138:141], v[178:181], v[124:127]
	v_mfma_f32_16x16x32_bf16 v[120:123], v[170:173], v[178:181], v[120:123]
	v_mfma_f32_16x16x32_bf16 v[116:119], v[138:141], v[186:189], v[116:119]
	v_mfma_f32_16x16x32_bf16 v[112:115], v[170:173], v[186:189], v[112:115]
	v_mfma_f32_16x16x32_bf16 v[108:111], v[134:137], v[190:193], v[108:111]
	v_mfma_f32_16x16x32_bf16 v[104:107], v[158:161], v[190:193], v[104:107]
	v_mfma_f32_16x16x32_bf16 v[100:103], v[138:141], v[204:207], v[100:103]
	v_mfma_f32_16x16x32_bf16 v[96:99], v[158:161], v[200:203], v[96:99]
	v_mfma_f32_16x16x32_bf16 v[130:133], v[138:141], v[196:199], v[108:111]
	v_mfma_f32_16x16x32_bf16 v[166:169], v[170:173], v[196:199], v[104:107]
	v_mfma_f32_16x16x32_bf16 v[208:211], v[170:173], v[204:207], v[96:99]
	s_barrier
; #define WAIT_V(n) asm volatile("s_waitcnt vmcnt(" #n ")" ::: "memory")
; #define WAIT_L(n) asm volatile("s_waitcnt lgkmcnt(" #n ")" ::: "memory")
; #define BAR __builtin_amdgcn_s_barrier()
;     ...
;     { LDB(B0, 0, 0); LDA(At, 0, 0); STAGE(SA(1, 1), A, brow + HALF, nt - 1);
;       BAR; WAIT_L(0); MMA(0, 0, At, B0); BAR;
;       LDB(B1, 0, 1); BAR; WAIT_L(0); MMA(0, 1, At, B1); BAR;
;       LDA(At, 0, 1); WAIT_V(4); BAR; WAIT_L(0); MMA(1, 0, At, B0); MMA(1, 1, At, B1); BAR; }
;     { LDB(B0, 1, 0); LDA(At, 1, 0); WAIT_V(2); BAR; WAIT_L(0); MMA(0, 0, At, B0); BAR;
;       LDB(B1, 1, 1); WAIT_V(0); BAR; WAIT_L(0); MMA(0, 1, At, B1); BAR;
	s_nop 2
	ds_read_b128 v[96:99], v165
	ds_read_b128 v[104:107], v165 offset:1024
	ds_read_b128 v[108:111], v165 offset:2048
	ds_read_b128 v[162:165], v165 offset:3072
	s_barrier
	s_waitcnt lgkmcnt(0)
	s_waitcnt lgkmcnt(0)
	v_mfma_f32_16x16x32_bf16 v[92:95], v[96:99], v[174:177], v[92:95]
	v_mfma_f32_16x16x32_bf16 v[88:91], v[108:111], v[174:177], v[88:91]
	v_mfma_f32_16x16x32_bf16 v[80:83], v[108:111], v[182:185], v[80:83]
	v_mfma_f32_16x16x32_bf16 v[76:79], v[96:99], v[190:193], v[76:79]
	v_mfma_f32_16x16x32_bf16 v[72:75], v[108:111], v[190:193], v[72:75]
	v_mfma_f32_16x16x32_bf16 v[68:71], v[96:99], v[200:203], v[68:71]
	v_mfma_f32_16x16x32_bf16 v[92:95], v[104:107], v[178:181], v[92:95]
	v_mfma_f32_16x16x32_bf16 v[88:91], v[162:165], v[178:181], v[88:91]
	v_mfma_f32_16x16x32_bf16 v[84:87], v[96:99], v[182:185], v[84:87]
	v_mfma_f32_16x16x32_bf16 v[80:83], v[162:165], v[186:189], v[80:83]
	v_mfma_f32_16x16x32_bf16 v[76:79], v[104:107], v[196:199], v[76:79]
	v_mfma_f32_16x16x32_bf16 v[72:75], v[162:165], v[196:199], v[72:75]
	v_mfma_f32_16x16x32_bf16 v[68:71], v[104:107], v[204:207], v[68:71]
	v_mfma_f32_16x16x32_bf16 v[64:67], v[108:111], v[200:203], v[64:67]
	v_mfma_f32_16x16x32_bf16 v[174:177], v[104:107], v[186:189], v[84:87]
	v_mfma_f32_16x16x32_bf16 v[178:181], v[162:165], v[204:207], v[64:67]
	s_barrier
	s_nop 3
	ds_read_b128 v[64:67], v151 offset:16384
	ds_read_b128 v[84:87], v151 offset:17408
	ds_read_b128 v[182:185], v150 offset:16384
	ds_read_b128 v[186:189], v150 offset:17408
	ds_read_b128 v[190:193], v149 offset:16384
	ds_read_b128 v[196:199], v149 offset:17408
	ds_read_b128 v[200:203], v148 offset:16384
	ds_read_b128 v[204:207], v148 offset:17408
	s_waitcnt vmcnt(4)
	s_barrier
	s_waitcnt lgkmcnt(0)
	s_waitcnt lgkmcnt(0)
	v_mfma_f32_16x16x32_bf16 v[52:55], v[134:137], v[182:185], v[52:55]
	v_mfma_f32_16x16x32_bf16 v[48:51], v[158:161], v[182:185], v[48:51]
	v_mfma_f32_16x16x32_bf16 v[60:63], v[134:137], v[64:67], v[60:63]
	v_mfma_f32_16x16x32_bf16 v[56:59], v[158:161], v[64:67], v[56:59]
	v_mfma_f32_16x16x32_bf16 v[52:55], v[138:141], v[186:189], v[52:55]
	v_mfma_f32_16x16x32_bf16 v[48:51], v[170:173], v[186:189], v[48:51]
	v_mfma_f32_16x16x32_bf16 v[44:47], v[134:137], v[190:193], v[44:47]
	v_mfma_f32_16x16x32_bf16 v[40:43], v[158:161], v[190:193], v[40:43]
	v_mfma_f32_16x16x32_bf16 v[36:39], v[134:137], v[200:203], v[36:39]
	v_mfma_f32_16x16x32_bf16 v[32:35], v[158:161], v[200:203], v[32:35]
	v_mfma_f32_16x16x32_bf16 v[212:215], v[138:141], v[84:87], v[60:63]
	v_mfma_f32_16x16x32_bf16 v[216:219], v[170:173], v[84:87], v[56:59]
	v_mfma_f32_16x16x32_bf16 v[220:223], v[138:141], v[196:199], v[44:47]
	v_mfma_f32_16x16x32_bf16 v[224:227], v[170:173], v[196:199], v[40:43]
	v_mfma_f32_16x16x32_bf16 v[134:137], v[138:141], v[204:207], v[36:39]
	v_mfma_f32_16x16x32_bf16 v[138:141], v[170:173], v[204:207], v[32:35]
	v_mfma_f32_16x16x32_bf16 v[28:31], v[96:99], v[64:67], v[28:31]
	v_mfma_f32_16x16x32_bf16 v[24:27], v[108:111], v[64:67], v[24:27]
	v_mfma_f32_16x16x32_bf16 v[12:15], v[96:99], v[190:193], v[12:15]
	v_mfma_f32_16x16x32_bf16 v[8:11], v[108:111], v[190:193], v[8:11]
	v_mfma_f32_16x16x32_bf16 v[28:31], v[104:107], v[84:87], v[28:31]
	v_mfma_f32_16x16x32_bf16 v[24:27], v[162:165], v[84:87], v[24:27]
	v_mfma_f32_16x16x32_bf16 v[20:23], v[96:99], v[182:185], v[20:23]
	v_mfma_f32_16x16x32_bf16 v[16:19], v[108:111], v[182:185], v[16:19]
	v_mfma_f32_16x16x32_bf16 v[12:15], v[104:107], v[196:199], v[12:15]
	v_mfma_f32_16x16x32_bf16 v[8:11], v[162:165], v[196:199], v[8:11]
	v_mfma_f32_16x16x32_bf16 v[4:7], v[96:99], v[200:203], v[4:7]
	v_mfma_f32_16x16x32_bf16 v[0:3], v[108:111], v[200:203], v[0:3]
	v_mfma_f32_16x16x32_bf16 v[158:161], v[104:107], v[186:189], v[20:23]
	v_mfma_f32_16x16x32_bf16 v[170:173], v[162:165], v[186:189], v[16:19]
	v_mfma_f32_16x16x32_bf16 v[182:185], v[104:107], v[204:207], v[4:7]
	v_mfma_f32_16x16x32_bf16 v[162:165], v[162:165], v[204:207], v[0:3]
	s_barrier
	s_nop 1
	ds_read_b128 v[0:3], v156
	ds_read_b128 v[4:7], v156 offset:1024
	ds_read_b128 v[186:189], v156 offset:2048
	ds_read_b128 v[154:157], v156 offset:3072
	ds_read_b128 v[16:19], v151 offset:32768
	ds_read_b128 v[20:23], v151 offset:33792
	ds_read_b128 v[40:43], v150 offset:32768
	ds_read_b128 v[44:47], v150 offset:33792
	ds_read_b128 v[60:63], v149 offset:32768
	ds_read_b128 v[190:193], v149 offset:33792
	ds_read_b128 v[196:199], v148 offset:32768
	ds_read_b128 v[200:203], v148 offset:33792
	s_waitcnt vmcnt(2)
	s_barrier
; #define WAIT_V(n) asm volatile("s_waitcnt vmcnt(" #n ")" ::: "memory")
; #define WAIT_L(n) asm volatile("s_waitcnt lgkmcnt(" #n ")" ::: "memory")
; #define BAR __builtin_amdgcn_s_barrier()
;     ...
;       LDA(At, 0, 1); WAIT_V(4); BAR; WAIT_L(0); MMA(1, 0, At, B0); MMA(1, 1, At, B1); BAR; }
;     { LDB(B0, 1, 0); LDA(At, 1, 0); WAIT_V(2); BAR; WAIT_L(0); MMA(0, 0, At, B0); BAR;
;       LDB(B1, 1, 1); WAIT_V(0); BAR; WAIT_L(0); MMA(0, 1, At, B1); BAR;
;       LDA(At, 1, 1); BAR; WAIT_L(0); MMA(1, 0, At, B0); MMA(1, 1, At, B1); BAR; }
;     if (wr == 0) BAR;
	s_waitcnt lgkmcnt(0)
	s_waitcnt lgkmcnt(0)
	v_mfma_f32_16x16x32_bf16 v[32:35], v[0:3], v[16:19], v[124:127]
	v_mfma_f32_16x16x32_bf16 v[108:111], v[4:7], v[20:23], v[32:35]
	v_mfma_f32_16x16x32_bf16 v[32:35], v[186:189], v[16:19], v[120:123]
	v_mfma_f32_16x16x32_bf16 v[104:107], v[154:157], v[20:23], v[32:35]
	v_mfma_f32_16x16x32_bf16 v[32:35], v[0:3], v[40:43], v[116:119]
	v_mfma_f32_16x16x32_bf16 v[96:99], v[4:7], v[44:47], v[32:35]
	v_mfma_f32_16x16x32_bf16 v[32:35], v[186:189], v[40:43], v[112:115]
	v_mfma_f32_16x16x32_bf16 v[84:87], v[154:157], v[44:47], v[32:35]
	v_mfma_f32_16x16x32_bf16 v[32:35], v[0:3], v[60:63], v[130:133]
	v_mfma_f32_16x16x32_bf16 v[64:67], v[4:7], v[190:193], v[32:35]
	v_mfma_f32_16x16x32_bf16 v[32:35], v[186:189], v[60:63], v[166:169]
	v_mfma_f32_16x16x32_bf16 v[56:59], v[154:157], v[190:193], v[32:35]
	v_mfma_f32_16x16x32_bf16 v[32:35], v[0:3], v[196:199], v[100:103]
	v_mfma_f32_16x16x32_bf16 v[36:39], v[4:7], v[200:203], v[32:35]
	v_mfma_f32_16x16x32_bf16 v[32:35], v[186:189], v[196:199], v[208:211]
	v_mfma_f32_16x16x32_bf16 v[32:35], v[154:157], v[200:203], v[32:35]
	s_barrier
	ds_read_b128 v[130:133], v152
	ds_read_b128 v[166:169], v152 offset:1024
	ds_read_b128 v[204:207], v152 offset:2048
	ds_read_b128 v[208:211], v152 offset:3072
	s_waitcnt vmcnt(0)
	s_barrier
	s_waitcnt lgkmcnt(0)
	s_waitcnt lgkmcnt(0)
	v_mfma_f32_16x16x32_bf16 v[92:95], v[130:133], v[16:19], v[92:95]
	v_mfma_f32_16x16x32_bf16 v[16:19], v[204:207], v[16:19], v[88:91]
	v_mfma_f32_16x16x32_bf16 v[120:123], v[208:211], v[20:23], v[16:19]
	v_mfma_f32_16x16x32_bf16 v[16:19], v[130:133], v[40:43], v[174:177]
	v_mfma_f32_16x16x32_bf16 v[116:119], v[166:169], v[44:47], v[16:19]
	v_mfma_f32_16x16x32_bf16 v[16:19], v[204:207], v[40:43], v[80:83]
	v_mfma_f32_16x16x32_bf16 v[112:115], v[208:211], v[44:47], v[16:19]
	v_mfma_f32_16x16x32_bf16 v[16:19], v[130:133], v[60:63], v[76:79]
	v_mfma_f32_16x16x32_bf16 v[100:103], v[166:169], v[190:193], v[16:19]
	v_mfma_f32_16x16x32_bf16 v[16:19], v[204:207], v[60:63], v[72:75]
	v_mfma_f32_16x16x32_bf16 v[88:91], v[208:211], v[190:193], v[16:19]
	v_mfma_f32_16x16x32_bf16 v[16:19], v[130:133], v[196:199], v[68:71]
	v_mfma_f32_16x16x32_bf16 v[68:71], v[166:169], v[200:203], v[16:19]
	v_mfma_f32_16x16x32_bf16 v[16:19], v[204:207], v[196:199], v[178:181]
	v_mfma_f32_16x16x32_bf16 v[124:127], v[166:169], v[20:23], v[92:95]
	v_mfma_f32_16x16x32_bf16 v[60:63], v[208:211], v[200:203], v[16:19]
	s_barrier
	ds_read_b128 v[80:83], v151 offset:49152
	ds_read_b128 v[174:177], v151 offset:50176
	ds_read_b128 v[178:181], v150 offset:49152
	ds_read_b128 v[150:153], v150 offset:50176
	ds_read_b128 v[190:193], v149 offset:49152
	ds_read_b128 v[196:199], v149 offset:50176
	ds_read_b128 v[200:203], v148 offset:49152
	ds_read_b128 v[228:231], v148 offset:50176
	s_barrier
	s_waitcnt lgkmcnt(0)
	s_waitcnt lgkmcnt(0)
	v_mfma_f32_16x16x32_bf16 v[16:19], v[0:3], v[80:83], v[212:215]
	v_mfma_f32_16x16x32_bf16 v[76:79], v[4:7], v[174:177], v[16:19]
	v_mfma_f32_16x16x32_bf16 v[16:19], v[186:189], v[80:83], v[216:219]
	v_mfma_f32_16x16x32_bf16 v[72:75], v[154:157], v[174:177], v[16:19]
	v_mfma_f32_16x16x32_bf16 v[16:19], v[0:3], v[178:181], v[52:55]
	v_mfma_f32_16x16x32_bf16 v[44:47], v[4:7], v[150:153], v[16:19]
	v_mfma_f32_16x16x32_bf16 v[16:19], v[186:189], v[178:181], v[48:51]
	v_mfma_f32_16x16x32_bf16 v[40:43], v[154:157], v[150:153], v[16:19]
	v_mfma_f32_16x16x32_bf16 v[16:19], v[0:3], v[190:193], v[220:223]
	v_mfma_f32_16x16x32_bf16 v[0:3], v[0:3], v[200:203], v[134:137]
	v_mfma_f32_16x16x32_bf16 v[20:23], v[4:7], v[196:199], v[16:19]
	v_mfma_f32_16x16x32_bf16 v[16:19], v[186:189], v[190:193], v[224:227]
	v_mfma_f32_16x16x32_bf16 v[4:7], v[4:7], v[228:231], v[0:3]
	v_mfma_f32_16x16x32_bf16 v[0:3], v[186:189], v[200:203], v[138:141]
	v_mfma_f32_16x16x32_bf16 v[16:19], v[154:157], v[196:199], v[16:19]
	v_mfma_f32_16x16x32_bf16 v[0:3], v[154:157], v[228:231], v[0:3]
	v_mfma_f32_16x16x32_bf16 v[24:27], v[204:207], v[80:83], v[24:27]
	v_mfma_f32_16x16x32_bf16 v[28:31], v[130:133], v[80:83], v[28:31]
	v_mfma_f32_16x16x32_bf16 v[80:83], v[208:211], v[174:177], v[24:27]
	v_mfma_f32_16x16x32_bf16 v[24:27], v[130:133], v[178:181], v[158:161]
	v_mfma_f32_16x16x32_bf16 v[52:55], v[166:169], v[150:153], v[24:27]
	v_mfma_f32_16x16x32_bf16 v[24:27], v[204:207], v[178:181], v[170:173]
	v_mfma_f32_16x16x32_bf16 v[8:11], v[204:207], v[190:193], v[8:11]
	v_mfma_f32_16x16x32_bf16 v[48:51], v[208:211], v[150:153], v[24:27]
	v_mfma_f32_16x16x32_bf16 v[12:15], v[130:133], v[190:193], v[12:15]
	v_mfma_f32_16x16x32_bf16 v[24:27], v[208:211], v[196:199], v[8:11]
	v_mfma_f32_16x16x32_bf16 v[8:11], v[130:133], v[200:203], v[182:185]
	v_mfma_f32_16x16x32_bf16 v[92:95], v[166:169], v[174:177], v[28:31]
	v_mfma_f32_16x16x32_bf16 v[28:31], v[166:169], v[196:199], v[12:15]
	v_mfma_f32_16x16x32_bf16 v[12:15], v[166:169], v[228:231], v[8:11]
	v_mfma_f32_16x16x32_bf16 v[8:11], v[204:207], v[200:203], v[162:165]
	v_mfma_f32_16x16x32_bf16 v[8:11], v[208:211], v[228:231], v[8:11]
	s_setprio 0
	s_movk_i32 s17, 0x100
	v_cmp_gt_u32_e32 vcc, s17, v128
	s_barrier
	s_and_saveexec_b64 s[18:19], vcc
	s_cbranch_execz .LBB0_94
	s_barrier
	s_branch .LBB0_94

; #define WAIT_V(n) asm volatile("s_waitcnt vmcnt(" #n ")" ::: "memory")
; #define BAR __builtin_amdgcn_s_barrier()
;     ...
;   for (int vw = blockIdx.x; vw < nwg; vw += gridDim.x) {
;     int tid_ = threadIdx.x;
;     asm volatile("" : "+v"(tid_));
;     const int wid = tid_ >> 6, lane = tid_ & 63, wr = wid >> 2, wc = wid & 3, fr = lane & 15, fq = lane >> 4;
;     int brow, bcol;
;     TILE_COORDS(vw, brow, bcol);
;     f32x4 acc[2][2][4][2] = {};
;     bf16x8 At[4][2], B0[2][2], B1[2][2];
;     STAGE(SB(0, 0), Bt, bcol, 0); STAGE(SA(0, 0), A, brow, 0);
;     STAGE(SB(0, 1), Bt, bcol + HALF, 0); STAGE(SA(0, 1), A, brow + HALF, 0);
;     if (wr == 1) BAR;
;     WAIT_V(4); BAR;
;     STAGE(SB(1, 0), Bt, bcol, 1); STAGE(SA(1, 0), A, brow, 1); STAGE(SB(1, 1), Bt, bcol + HALF, 1);
;     WAIT_V(6); BAR;
.LBB0_432:
	v_ashrrev_i32_e32 v0, 31, v152
	s_add_i32 s16, s19, s16
	v_lshrrev_b32_e32 v0, 26, v0
	s_ashr_i32 s17, s16, 31
	v_add_u32_e32 v0, v152, v0
	s_lshr_b32 s17, s17, 27
	v_ashrrev_i32_e32 v1, 6, v0
	v_bfe_i32 v0, v152, 27, 1
	s_add_i32 s18, s16, s17
	v_lshlrev_b32_e32 v20, 4, v152
	v_lshrrev_b32_e32 v0, 22, v0
	s_and_b32 s17, s18, 0xffe0
	v_add_u32_e32 v0, v20, v0
	s_sub_i32 s16, s16, s17
	v_and_b32_e32 v0, 0xfffffc00, v0
	s_bfe_i32 s17, s16, 0x80000
	v_sub_u32_e32 v0, v20, v0
	s_bfe_u32 s17, s17, 0x2000d
	v_lshrrev_b32_e32 v2, 4, v0
	s_add_i32 s17, s16, s17
	v_bitop3_b32 v2, v2, v0, 32 bitop3:0x6c
	s_bfe_i32 s19, s17, 0x80000
	v_ashrrev_i32_e32 v3, 31, v2
	s_sext_i32_i16 s19, s19
	v_lshrrev_b32_e32 v3, 26, v3
	s_lshr_b32 s37, s19, 2
	s_and_b32 s17, s17, 0xfc
	v_add_u32_e32 v3, v2, v3
	s_sub_i32 s16, s16, s17
	s_lshl_b32 s20, s37, 8
	v_lshlrev_b32_e32 v0, 3, v1
	v_ashrrev_i32_e32 v4, 6, v3
	v_and_b32_e32 v3, 0xc0, v3
	s_sext_i32_i8 s16, s16
	s_ashr_i32 s21, s20, 31
	v_and_b32_e32 v0, -16, v0
	v_lshlrev_b32_e32 v1, 5, v1
	v_sub_u32_e32 v2, v2, v3
	s_lshl_b32 s19, s16, 8
	s_lshl_b64 s[22:23], s[20:21], 12
	v_readlane_b32 s40, v248, 10
	v_add_u32_e32 v0, v4, v0
	v_and_b32_e32 v1, 32, v1
	v_ashrrev_i16_sdwa v2, v159, sext(v2) dst_sel:DWORD dst_unused:UNUSED_PAD src0_sel:DWORD src1_sel:BYTE_0
	v_readlane_b32 s41, v248, 11
	s_add_u32 s16, s40, s22
	v_add_u32_sdwa v2, v1, sext(v2) dst_sel:DWORD dst_unused:UNUSED_PAD src0_sel:DWORD src1_sel:WORD_0
	v_ashrrev_i32_e32 v1, 31, v0
	s_addc_u32 s17, s41, s23
	v_lshlrev_b64 v[0:1], 12, v[0:1]
	v_ashrrev_i32_e32 v3, 31, v2
	v_lshl_add_u64 v[4:5], s[16:17], 0, v[0:1]
	v_lshlrev_b64 v[2:3], 1, v[2:3]
	v_add_u32_e32 v21, 0x2000, v20
	v_lshl_add_u64 v[8:9], v[4:5], 0, v[2:3]
	v_ashrrev_i32_e32 v4, 31, v21
	v_lshrrev_b32_e32 v4, 22, v4
	v_add_u32_e32 v4, v21, v4
	v_ashrrev_i32_e32 v5, 10, v4
	v_mul_i32_i24_e32 v4, 0x400, v5
	v_sub_u32_e32 v4, v21, v4
	v_lshrrev_b32_e32 v6, 4, v4
	v_bitop3_b32 v6, v6, v4, 32 bitop3:0x6c
	v_ashrrev_i32_e32 v7, 31, v6
	v_lshrrev_b32_e32 v7, 26, v7
	v_add_u32_e32 v7, v6, v7
	v_lshlrev_b32_e32 v4, 3, v5
	v_ashrrev_i32_e32 v10, 6, v7
	v_and_b32_e32 v7, 0xc0, v7
	v_and_b32_e32 v4, -16, v4
	v_lshlrev_b32_e32 v5, 5, v5
	v_sub_u32_e32 v6, v6, v7
	v_add_u32_e32 v4, v10, v4
	v_and_b32_e32 v5, 32, v5
	v_ashrrev_i16_sdwa v6, v159, sext(v6) dst_sel:DWORD dst_unused:UNUSED_PAD src0_sel:DWORD src1_sel:BYTE_0
	v_add_u32_e32 v140, s28, v20
	v_add_u32_sdwa v6, v5, sext(v6) dst_sel:DWORD dst_unused:UNUSED_PAD src0_sel:DWORD src1_sel:WORD_0
	v_ashrrev_i32_e32 v5, 31, v4
	v_readfirstlane_b32 s24, v140
	v_lshlrev_b64 v[4:5], 12, v[4:5]
	v_add_u32_e32 v12, s28, v21
	s_mov_b32 m0, s24
	v_lshl_add_u64 v[10:11], s[16:17], 0, v[4:5]
	v_readfirstlane_b32 s16, v12
	global_load_lds_dwordx4 v[8:9], off
	s_mov_b32 m0, s16
	s_lshl_b32 s16, s18, 5
	s_and_b32 s16, s16, 0xfffffc00
	s_add_i32 s18, s19, s16
	s_ashr_i32 s19, s18, 31
	s_lshl_b64 s[24:25], s[18:19], 12
	v_ashrrev_i32_e32 v7, 31, v6
	s_add_u32 s16, s92, s24
	v_lshlrev_b64 v[6:7], 1, v[6:7]
	s_addc_u32 s17, s93, s25
	v_add_u32_e32 v141, 0, v20
	v_lshl_add_u64 v[10:11], v[10:11], 0, v[6:7]
	v_lshl_add_u64 v[12:13], s[16:17], 0, v[0:1]
	v_readfirstlane_b32 s19, v141
	v_add_u32_e32 v142, 0x2000, v141
	global_load_lds_dwordx4 v[10:11], off
	v_lshl_add_u64 v[12:13], v[12:13], 0, v[2:3]
	s_mov_b32 m0, s19
	v_lshl_add_u64 v[14:15], s[16:17], 0, v[4:5]
	v_readfirstlane_b32 s16, v142
	global_load_lds_dwordx4 v[12:13], off
	s_mov_b32 m0, s16
	s_or_b32 s16, s20, 0x80
	s_ashr_i32 s17, s16, 31
	s_lshl_b64 s[16:17], s[16:17], 12
	s_add_u32 s16, s40, s16
	s_addc_u32 s17, s41, s17
	v_add_u32_e32 v144, s29, v20
	v_lshl_add_u64 v[14:15], v[14:15], 0, v[6:7]
	v_lshl_add_u64 v[16:17], s[16:17], 0, v[0:1]
	v_readfirstlane_b32 s19, v144
	v_add_u32_e32 v21, s29, v21
	global_load_lds_dwordx4 v[14:15], off
	v_lshl_add_u64 v[16:17], v[16:17], 0, v[2:3]
	s_mov_b32 m0, s19
	v_lshl_add_u64 v[18:19], s[16:17], 0, v[4:5]
	v_readfirstlane_b32 s16, v21
	global_load_lds_dwordx4 v[16:17], off
	s_mov_b32 m0, s16
	s_or_b32 s16, s18, 0x80
	s_ashr_i32 s17, s16, 31
	s_lshl_b64 s[26:27], s[16:17], 12
	s_add_u32 s26, s92, s26
	s_addc_u32 s27, s93, s27
	v_add_u32_e32 v146, 0x4000, v141
	v_lshl_add_u64 v[18:19], v[18:19], 0, v[6:7]
	v_lshl_add_u64 v[22:23], s[26:27], 0, v[0:1]
	v_readfirstlane_b32 s17, v146
	v_add_u32_e32 v147, 0x6000, v141
	global_load_lds_dwordx4 v[18:19], off
	v_lshl_add_u64 v[128:129], v[22:23], 0, v[2:3]
	s_mov_b32 m0, s17
	v_lshl_add_u64 v[22:23], s[26:27], 0, v[4:5]
	v_readfirstlane_b32 s17, v147
	global_load_lds_dwordx4 v[128:129], off
	v_lshl_add_u64 v[130:131], v[22:23], 0, v[6:7]
	s_mov_b32 m0, s17
	v_ashrrev_i32_e32 v21, 8, v152
	global_load_lds_dwordx4 v[130:131], off
	v_mov_b64_e32 v[24:25], 0
	v_mov_b64_e32 v[26:27], 0
	v_mov_b64_e32 v[28:29], 0
	v_mov_b64_e32 v[30:31], 0
	v_mov_b64_e32 v[32:33], 0
	v_mov_b64_e32 v[34:35], 0
	v_mov_b64_e32 v[36:37], 0
	v_mov_b64_e32 v[38:39], 0
	v_mov_b64_e32 v[40:41], 0
	v_mov_b64_e32 v[42:43], 0
	v_mov_b64_e32 v[44:45], 0
	v_mov_b64_e32 v[46:47], 0
	v_mov_b64_e32 v[48:49], 0
	v_mov_b64_e32 v[50:51], 0
	v_mov_b64_e32 v[52:53], 0
	v_mov_b64_e32 v[54:55], 0
	v_mov_b64_e32 v[56:57], 0
	v_mov_b64_e32 v[58:59], 0
	v_mov_b64_e32 v[60:61], 0
	v_mov_b64_e32 v[62:63], 0
	v_mov_b64_e32 v[64:65], 0
	v_mov_b64_e32 v[66:67], 0
	v_mov_b64_e32 v[68:69], 0
	v_mov_b64_e32 v[70:71], 0
	v_mov_b64_e32 v[72:73], 0
	v_mov_b64_e32 v[74:75], 0
	v_mov_b64_e32 v[76:77], 0
	v_mov_b64_e32 v[78:79], 0
	v_mov_b64_e32 v[80:81], 0
	v_mov_b64_e32 v[82:83], 0
	v_mov_b64_e32 v[84:85], 0
	v_mov_b64_e32 v[86:87], 0
	v_mov_b64_e32 v[88:89], 0
	v_mov_b64_e32 v[90:91], 0
	v_mov_b64_e32 v[92:93], 0
	v_mov_b64_e32 v[94:95], 0
	v_mov_b64_e32 v[96:97], 0
	v_mov_b64_e32 v[98:99], 0
	v_mov_b64_e32 v[100:101], 0
	v_mov_b64_e32 v[102:103], 0
	v_mov_b64_e32 v[104:105], 0
	v_mov_b64_e32 v[106:107], 0
	v_mov_b64_e32 v[108:109], 0
	v_mov_b64_e32 v[110:111], 0
	v_mov_b64_e32 v[112:113], 0
	v_mov_b64_e32 v[114:115], 0
	v_mov_b64_e32 v[116:117], 0
	v_mov_b64_e32 v[118:119], 0
	v_mov_b64_e32 v[120:121], 0
	v_mov_b64_e32 v[122:123], 0
	v_mov_b64_e32 v[124:125], 0
	v_mov_b64_e32 v[126:127], 0
	v_cmp_eq_u32_e32 vcc, 1, v21
	v_readlane_b32 s42, v248, 12
	v_readlane_b32 s43, v248, 13
	v_readlane_b32 s44, v248, 14
	v_readlane_b32 s45, v248, 15
	v_readlane_b32 s46, v248, 16
	v_readlane_b32 s47, v248, 17
	v_readlane_b32 s48, v248, 18
	v_readlane_b32 s49, v248, 19
	v_readlane_b32 s50, v248, 20
	v_readlane_b32 s51, v248, 21
	v_readlane_b32 s52, v248, 22
	v_readlane_b32 s53, v248, 23
	v_readlane_b32 s54, v248, 24
	v_readlane_b32 s55, v248, 25
	s_and_saveexec_b64 s[26:27], vcc
	s_cbranch_execz .LBB0_434
	s_setprio 1
	s_barrier

; #define WAIT_V(n) asm volatile("s_waitcnt vmcnt(" #n ")" ::: "memory")
; #define WAIT_L(n) asm volatile("s_waitcnt lgkmcnt(" #n ")" ::: "memory")
; #define BAR __builtin_amdgcn_s_barrier()
; #define SCHED __builtin_amdgcn_sched_barrier(0)
;     ...
;       LDB(B0, 0, 0); SCHED; LDA(At, 0, 0); STAGE(SA(1, 1), A, brow + HALF, t + 1);
;       WAIT_L(8); BAR; WAIT_L(0); MMA(0, 0, At, B0); BAR; SCHED;
;       LDB(B1, 0, 1); STAGE(SB(0, 0), Bt, bcol, t + 2);
;       BAR; WAIT_L(0); MMA(0, 1, At, B1); BAR;
;       LDA(At, 0, 1); STAGE(SA(0, 0), A, brow, t + 2);
;       BAR; WAIT_L(0); MMA(1, 0, At, B0); BAR; SCHED;
;       STAGE(SB(0, 1), Bt, bcol + HALF, t + 2);
;       WAIT_V(6); BAR; MMA(1, 1, At, B1); BAR;
.LBB0_435:
	v_add_u32_e32 v168, 0xc000, v141
	v_add_u32_e32 v169, 0xe000, v141
	v_add_u32_e32 v246, 0x2000, v140
	v_add_u32_e32 v172, 0x2000, v144
	ds_read_b128 v[170:173], v167
	ds_read_b128 v[174:177], v167 offset:1024
	ds_read_b128 v[178:181], v167 offset:2048
	ds_read_b128 v[182:185], v167 offset:3072
	ds_read_b128 v[186:189], v157
	ds_read_b128 v[190:193], v157 offset:1024
	ds_read_b128 v[196:199], v156
	ds_read_b128 v[200:203], v156 offset:1024
	ds_read_b128 v[204:207], v155
	ds_read_b128 v[208:211], v155 offset:1024
	ds_read_b128 v[212:215], v154
	ds_read_b128 v[216:219], v154 offset:1024
	ds_read_b128 v[220:223], v166
	ds_read_b128 v[224:227], v166 offset:1024
	ds_read_b128 v[228:231], v166 offset:2048
	ds_read_b128 v[232:235], v166 offset:3072
	v_add_u32_e32 v254, 0xc000, v141
	v_lshl_add_u64 v[250:251], v[136:137], 0, s[22:23]
	v_readfirstlane_b32 s19, v254
	v_lshl_add_u64 v[250:251], v[250:251], 0, s[4:5]
	s_mov_b32 m0, s19
	s_nop 0
	global_load_lds_dwordx4 v[250:251], off
	v_add_u32_e32 v254, 0xe000, v141
	v_lshl_add_u64 v[252:253], v[138:139], 0, s[22:23]
	v_readfirstlane_b32 s19, v254
	v_lshl_add_u64 v[252:253], v[252:253], 0, s[4:5]
	s_mov_b32 m0, s19
	s_nop 0
	global_load_lds_dwordx4 v[252:253], off
	s_waitcnt lgkmcnt(0)
	s_barrier
	v_mfma_f32_16x16x32_bf16 v[124:127], v[170:173], v[186:189], v[124:127]
	v_mfma_f32_16x16x32_bf16 v[120:123], v[178:181], v[186:189], v[120:123]
	v_mfma_f32_16x16x32_bf16 v[116:119], v[170:173], v[196:199], v[116:119]
	v_mfma_f32_16x16x32_bf16 v[112:115], v[178:181], v[196:199], v[112:115]
	v_mfma_f32_16x16x32_bf16 v[108:111], v[170:173], v[204:207], v[108:111]
	v_mfma_f32_16x16x32_bf16 v[104:107], v[178:181], v[204:207], v[104:107]
	v_mfma_f32_16x16x32_bf16 v[100:103], v[170:173], v[212:215], v[100:103]
	v_mfma_f32_16x16x32_bf16 v[96:99], v[178:181], v[212:215], v[96:99]
	v_mfma_f32_16x16x32_bf16 v[124:127], v[174:177], v[190:193], v[124:127]
	v_mfma_f32_16x16x32_bf16 v[120:123], v[182:185], v[190:193], v[120:123]
	v_mfma_f32_16x16x32_bf16 v[116:119], v[174:177], v[200:203], v[116:119]
	v_mfma_f32_16x16x32_bf16 v[112:115], v[182:185], v[200:203], v[112:115]
	v_mfma_f32_16x16x32_bf16 v[108:111], v[174:177], v[208:211], v[108:111]
	v_mfma_f32_16x16x32_bf16 v[104:107], v[182:185], v[208:211], v[104:107]
	v_mfma_f32_16x16x32_bf16 v[100:103], v[174:177], v[216:219], v[100:103]
	v_mfma_f32_16x16x32_bf16 v[96:99], v[182:185], v[216:219], v[96:99]
	v_mfma_f32_16x16x32_bf16 v[92:95], v[220:223], v[186:189], v[92:95]
	v_mfma_f32_16x16x32_bf16 v[88:91], v[228:231], v[186:189], v[88:91]
	v_mfma_f32_16x16x32_bf16 v[84:87], v[220:223], v[196:199], v[84:87]
	v_mfma_f32_16x16x32_bf16 v[80:83], v[228:231], v[196:199], v[80:83]
	v_mfma_f32_16x16x32_bf16 v[76:79], v[220:223], v[204:207], v[76:79]
	v_mfma_f32_16x16x32_bf16 v[72:75], v[228:231], v[204:207], v[72:75]
	v_mfma_f32_16x16x32_bf16 v[68:71], v[220:223], v[212:215], v[68:71]
	v_mfma_f32_16x16x32_bf16 v[64:67], v[228:231], v[212:215], v[64:67]
	v_mfma_f32_16x16x32_bf16 v[92:95], v[224:227], v[190:193], v[92:95]
	v_mfma_f32_16x16x32_bf16 v[88:91], v[232:235], v[190:193], v[88:91]
	v_mfma_f32_16x16x32_bf16 v[84:87], v[224:227], v[200:203], v[84:87]
	v_mfma_f32_16x16x32_bf16 v[80:83], v[232:235], v[200:203], v[80:83]
	v_mfma_f32_16x16x32_bf16 v[76:79], v[224:227], v[208:211], v[76:79]
	v_mfma_f32_16x16x32_bf16 v[72:75], v[232:235], v[208:211], v[72:75]
	v_mfma_f32_16x16x32_bf16 v[68:71], v[224:227], v[216:219], v[68:71]
	v_mfma_f32_16x16x32_bf16 v[64:67], v[232:235], v[216:219], v[64:67]
	s_barrier
	ds_read_b128 v[186:189], v157 offset:16384
	ds_read_b128 v[190:193], v157 offset:17408
	ds_read_b128 v[196:199], v156 offset:16384
	ds_read_b128 v[200:203], v156 offset:17408
	ds_read_b128 v[204:207], v155 offset:16384
	ds_read_b128 v[208:211], v155 offset:17408
	ds_read_b128 v[212:215], v154 offset:16384
	ds_read_b128 v[216:219], v154 offset:17408
	v_lshl_add_u64 v[250:251], v[132:133], 0, s[22:23]
	v_readfirstlane_b32 s19, v140
	v_lshl_add_u64 v[250:251], v[250:251], 0, s[6:7]
	s_mov_b32 m0, s19
	s_nop 0
	global_load_lds_dwordx4 v[250:251], off
	v_add_u32_e32 v254, 0x2000, v140
	v_lshl_add_u64 v[252:253], v[134:135], 0, s[22:23]
	v_readfirstlane_b32 s19, v254
	v_lshl_add_u64 v[252:253], v[252:253], 0, s[6:7]
	s_mov_b32 m0, s19
	s_nop 0
	global_load_lds_dwordx4 v[252:253], off
	v_lshl_add_u64 v[250:251], v[136:137], 0, s[22:23]
	v_readfirstlane_b32 s19, v141
	v_lshl_add_u64 v[250:251], v[250:251], 0, s[6:7]
	s_mov_b32 m0, s19
	s_nop 0
	global_load_lds_dwordx4 v[250:251], off
	v_lshl_add_u64 v[252:253], v[138:139], 0, s[22:23]
	v_readfirstlane_b32 s19, v142
	v_lshl_add_u64 v[252:253], v[252:253], 0, s[6:7]
	s_mov_b32 m0, s19
	s_nop 0
	global_load_lds_dwordx4 v[252:253], off
	v_lshl_add_u64 v[250:251], v[132:133], 0, s[22:23]
	v_readfirstlane_b32 s19, v144
	v_lshl_add_u64 v[250:251], v[250:251], 0, s[8:9]
	s_mov_b32 m0, s19
	s_nop 0
	global_load_lds_dwordx4 v[250:251], off
	v_add_u32_e32 v254, 0x2000, v144
	v_lshl_add_u64 v[252:253], v[134:135], 0, s[22:23]
	v_readfirstlane_b32 s19, v254
	v_lshl_add_u64 v[252:253], v[252:253], 0, s[8:9]
	s_mov_b32 m0, s19
	s_nop 0
	global_load_lds_dwordx4 v[252:253], off
	s_waitcnt vmcnt(6)
	s_waitcnt lgkmcnt(0)
	s_barrier
; #define WAIT_V(n) asm volatile("s_waitcnt vmcnt(" #n ")" ::: "memory")
; #define WAIT_L(n) asm volatile("s_waitcnt lgkmcnt(" #n ")" ::: "memory")
; #define BAR __builtin_amdgcn_s_barrier()
; #define SCHED __builtin_amdgcn_sched_barrier(0)
;     ...
;       WAIT_V(6); BAR; MMA(1, 1, At, B1); BAR;
;       LDB(B0, 1, 0); SCHED; LDA(At, 1, 0); STAGE(SA(0, 1), A, brow + HALF, t + 2);
;       WAIT_L(8); BAR; WAIT_L(0); MMA(0, 0, At, B0); BAR; SCHED;
;       LDB(B1, 1, 1); STAGE(SB(1, 0), Bt, bcol, t + 3);
;       BAR; WAIT_L(0); MMA(0, 1, At, B1); BAR;
;       LDA(At, 1, 1); STAGE(SA(1, 0), A, brow, t + 3);
;       BAR; WAIT_L(0); MMA(1, 0, At, B0); BAR; SCHED;
;       STAGE(SB(1, 1), Bt, bcol + HALF, t + 3);
	v_mfma_f32_16x16x32_bf16 v[60:63], v[170:173], v[186:189], v[60:63]
	v_mfma_f32_16x16x32_bf16 v[56:59], v[178:181], v[186:189], v[56:59]
	v_mfma_f32_16x16x32_bf16 v[52:55], v[170:173], v[196:199], v[52:55]
	v_mfma_f32_16x16x32_bf16 v[48:51], v[178:181], v[196:199], v[48:51]
	v_mfma_f32_16x16x32_bf16 v[44:47], v[170:173], v[204:207], v[44:47]
	v_mfma_f32_16x16x32_bf16 v[40:43], v[178:181], v[204:207], v[40:43]
	v_mfma_f32_16x16x32_bf16 v[36:39], v[170:173], v[212:215], v[36:39]
	v_mfma_f32_16x16x32_bf16 v[32:35], v[178:181], v[212:215], v[32:35]
	v_mfma_f32_16x16x32_bf16 v[60:63], v[174:177], v[190:193], v[60:63]
	v_mfma_f32_16x16x32_bf16 v[56:59], v[182:185], v[190:193], v[56:59]
	v_mfma_f32_16x16x32_bf16 v[52:55], v[174:177], v[200:203], v[52:55]
	v_mfma_f32_16x16x32_bf16 v[48:51], v[182:185], v[200:203], v[48:51]
	v_mfma_f32_16x16x32_bf16 v[44:47], v[174:177], v[208:211], v[44:47]
	v_mfma_f32_16x16x32_bf16 v[40:43], v[182:185], v[208:211], v[40:43]
	v_mfma_f32_16x16x32_bf16 v[36:39], v[174:177], v[216:219], v[36:39]
	v_mfma_f32_16x16x32_bf16 v[32:35], v[182:185], v[216:219], v[32:35]
	v_mfma_f32_16x16x32_bf16 v[28:31], v[220:223], v[186:189], v[28:31]
	v_mfma_f32_16x16x32_bf16 v[24:27], v[228:231], v[186:189], v[24:27]
	v_mfma_f32_16x16x32_bf16 v[20:23], v[220:223], v[196:199], v[20:23]
	v_mfma_f32_16x16x32_bf16 v[16:19], v[228:231], v[196:199], v[16:19]
	v_mfma_f32_16x16x32_bf16 v[12:15], v[220:223], v[204:207], v[12:15]
	v_mfma_f32_16x16x32_bf16 v[8:11], v[228:231], v[204:207], v[8:11]
	v_mfma_f32_16x16x32_bf16 v[4:7], v[220:223], v[212:215], v[4:7]
	v_mfma_f32_16x16x32_bf16 v[0:3], v[228:231], v[212:215], v[0:3]
	v_mfma_f32_16x16x32_bf16 v[28:31], v[224:227], v[190:193], v[28:31]
	v_mfma_f32_16x16x32_bf16 v[24:27], v[232:235], v[190:193], v[24:27]
	v_mfma_f32_16x16x32_bf16 v[20:23], v[224:227], v[200:203], v[20:23]
	v_mfma_f32_16x16x32_bf16 v[16:19], v[232:235], v[200:203], v[16:19]
	v_mfma_f32_16x16x32_bf16 v[12:15], v[224:227], v[208:211], v[12:15]
	v_mfma_f32_16x16x32_bf16 v[8:11], v[232:235], v[208:211], v[8:11]
	v_mfma_f32_16x16x32_bf16 v[4:7], v[224:227], v[216:219], v[4:7]
	v_mfma_f32_16x16x32_bf16 v[0:3], v[232:235], v[216:219], v[0:3]
	s_barrier
	ds_read_b128 v[170:173], v145
	ds_read_b128 v[174:177], v145 offset:1024
	ds_read_b128 v[178:181], v145 offset:2048
	ds_read_b128 v[182:185], v145 offset:3072
	ds_read_b128 v[186:189], v157 offset:32768
	ds_read_b128 v[190:193], v157 offset:33792
	ds_read_b128 v[196:199], v156 offset:32768
	ds_read_b128 v[200:203], v156 offset:33792
	ds_read_b128 v[204:207], v155 offset:32768
	ds_read_b128 v[208:211], v155 offset:33792
	ds_read_b128 v[212:215], v154 offset:32768
	ds_read_b128 v[216:219], v154 offset:33792
	ds_read_b128 v[220:223], v143
	ds_read_b128 v[224:227], v143 offset:1024
	ds_read_b128 v[228:231], v143 offset:2048
	ds_read_b128 v[232:235], v143 offset:3072
	v_lshl_add_u64 v[250:251], v[136:137], 0, s[22:23]
	v_readfirstlane_b32 s19, v146
	v_lshl_add_u64 v[250:251], v[250:251], 0, s[8:9]
	s_mov_b32 m0, s19
	s_nop 0
	global_load_lds_dwordx4 v[250:251], off
	v_lshl_add_u64 v[252:253], v[138:139], 0, s[22:23]
	v_readfirstlane_b32 s19, v147
	v_lshl_add_u64 v[252:253], v[252:253], 0, s[8:9]
	s_mov_b32 m0, s19
	s_nop 0
	global_load_lds_dwordx4 v[252:253], off
	s_waitcnt lgkmcnt(0)
	s_barrier
	v_mfma_f32_16x16x32_bf16 v[124:127], v[170:173], v[186:189], v[124:127]
	v_mfma_f32_16x16x32_bf16 v[120:123], v[178:181], v[186:189], v[120:123]
	v_mfma_f32_16x16x32_bf16 v[116:119], v[170:173], v[196:199], v[116:119]
	v_mfma_f32_16x16x32_bf16 v[112:115], v[178:181], v[196:199], v[112:115]
	v_mfma_f32_16x16x32_bf16 v[108:111], v[170:173], v[204:207], v[108:111]
	v_mfma_f32_16x16x32_bf16 v[104:107], v[178:181], v[204:207], v[104:107]
	v_mfma_f32_16x16x32_bf16 v[100:103], v[170:173], v[212:215], v[100:103]
	v_mfma_f32_16x16x32_bf16 v[96:99], v[178:181], v[212:215], v[96:99]
	v_mfma_f32_16x16x32_bf16 v[124:127], v[174:177], v[190:193], v[124:127]
	v_mfma_f32_16x16x32_bf16 v[120:123], v[182:185], v[190:193], v[120:123]
	v_mfma_f32_16x16x32_bf16 v[116:119], v[174:177], v[200:203], v[116:119]
	v_mfma_f32_16x16x32_bf16 v[112:115], v[182:185], v[200:203], v[112:115]
	v_mfma_f32_16x16x32_bf16 v[108:111], v[174:177], v[208:211], v[108:111]
	v_mfma_f32_16x16x32_bf16 v[104:107], v[182:185], v[208:211], v[104:107]
	v_mfma_f32_16x16x32_bf16 v[100:103], v[174:177], v[216:219], v[100:103]
	v_mfma_f32_16x16x32_bf16 v[96:99], v[182:185], v[216:219], v[96:99]
	v_mfma_f32_16x16x32_bf16 v[92:95], v[220:223], v[186:189], v[92:95]
	v_mfma_f32_16x16x32_bf16 v[88:91], v[228:231], v[186:189], v[88:91]
	v_mfma_f32_16x16x32_bf16 v[84:87], v[220:223], v[196:199], v[84:87]
	v_mfma_f32_16x16x32_bf16 v[80:83], v[228:231], v[196:199], v[80:83]
	v_mfma_f32_16x16x32_bf16 v[76:79], v[220:223], v[204:207], v[76:79]
	v_mfma_f32_16x16x32_bf16 v[72:75], v[228:231], v[204:207], v[72:75]
	v_mfma_f32_16x16x32_bf16 v[68:71], v[220:223], v[212:215], v[68:71]
	v_mfma_f32_16x16x32_bf16 v[64:67], v[228:231], v[212:215], v[64:67]
	v_mfma_f32_16x16x32_bf16 v[92:95], v[224:227], v[190:193], v[92:95]
	v_mfma_f32_16x16x32_bf16 v[88:91], v[232:235], v[190:193], v[88:91]
	v_mfma_f32_16x16x32_bf16 v[84:87], v[224:227], v[200:203], v[84:87]
	v_mfma_f32_16x16x32_bf16 v[80:83], v[232:235], v[200:203], v[80:83]
	v_mfma_f32_16x16x32_bf16 v[76:79], v[224:227], v[208:211], v[76:79]
	v_mfma_f32_16x16x32_bf16 v[72:75], v[232:235], v[208:211], v[72:75]
	v_mfma_f32_16x16x32_bf16 v[68:71], v[224:227], v[216:219], v[68:71]
	v_mfma_f32_16x16x32_bf16 v[64:67], v[232:235], v[216:219], v[64:67]
	s_barrier
; #define WAIT_V(n) asm volatile("s_waitcnt vmcnt(" #n ")" ::: "memory")
; #define WAIT_L(n) asm volatile("s_waitcnt lgkmcnt(" #n ")" ::: "memory")
; #define BAR __builtin_amdgcn_s_barrier()
; #define SCHED __builtin_amdgcn_sched_barrier(0)
;     ...
;       LDA(At, 1, 1); STAGE(SA(1, 0), A, brow, t + 3);
;       BAR; WAIT_L(0); MMA(1, 0, At, B0); BAR; SCHED;
;       STAGE(SB(1, 1), Bt, bcol + HALF, t + 3);
;       WAIT_V(6); BAR; MMA(1, 1, At, B1); BAR;
;     }
;     { LDB(B0, 0, 0); LDA(At, 0, 0); STAGE(SA(1, 1), A, brow + HALF, nt - 1);
;       BAR; WAIT_L(0); MMA(0, 0, At, B0); BAR;
;       LDB(B1, 0, 1); BAR; WAIT_L(0); MMA(0, 1, At, B1); BAR;
;       LDA(At, 0, 1); WAIT_V(4); BAR; WAIT_L(0); MMA(1, 0, At, B0); MMA(1, 1, At, B1); BAR; }
	ds_read_b128 v[186:189], v157 offset:49152
	ds_read_b128 v[190:193], v157 offset:50176
	ds_read_b128 v[196:199], v156 offset:49152
	ds_read_b128 v[200:203], v156 offset:50176
	ds_read_b128 v[204:207], v155 offset:49152
	ds_read_b128 v[208:211], v155 offset:50176
	ds_read_b128 v[212:215], v154 offset:49152
	ds_read_b128 v[216:219], v154 offset:50176
	v_lshl_add_u64 v[250:251], v[132:133], 0, s[22:23]
	v_readfirstlane_b32 s19, v148
	v_lshl_add_u64 v[250:251], v[250:251], 0, s[10:11]
	s_mov_b32 m0, s19
	s_nop 0
	global_load_lds_dwordx4 v[250:251], off
	v_lshl_add_u64 v[252:253], v[134:135], 0, s[22:23]
	v_readfirstlane_b32 s19, v149
	v_lshl_add_u64 v[252:253], v[252:253], 0, s[10:11]
	s_mov_b32 m0, s19
	s_nop 0
	global_load_lds_dwordx4 v[252:253], off
	v_lshl_add_u64 v[250:251], v[136:137], 0, s[22:23]
	v_readfirstlane_b32 s19, v150
	v_lshl_add_u64 v[250:251], v[250:251], 0, s[10:11]
	s_mov_b32 m0, s19
	s_nop 0
	global_load_lds_dwordx4 v[250:251], off
	v_lshl_add_u64 v[252:253], v[138:139], 0, s[22:23]
	v_readfirstlane_b32 s19, v151
	v_lshl_add_u64 v[252:253], v[252:253], 0, s[10:11]
	s_mov_b32 m0, s19
	s_nop 0
	global_load_lds_dwordx4 v[252:253], off
	v_lshl_add_u64 v[250:251], v[132:133], 0, s[22:23]
	v_readfirstlane_b32 s19, v164
	v_lshl_add_u64 v[250:251], v[250:251], 0, s[12:13]
	s_mov_b32 m0, s19
	s_nop 0
	global_load_lds_dwordx4 v[250:251], off
	v_lshl_add_u64 v[252:253], v[134:135], 0, s[22:23]
	v_readfirstlane_b32 s19, v165
	v_lshl_add_u64 v[252:253], v[252:253], 0, s[12:13]
	s_mov_b32 m0, s19
	s_nop 0
	global_load_lds_dwordx4 v[252:253], off
	s_waitcnt vmcnt(6)
	s_waitcnt lgkmcnt(0)
	s_barrier
	v_mfma_f32_16x16x32_bf16 v[60:63], v[170:173], v[186:189], v[60:63]
	v_mfma_f32_16x16x32_bf16 v[56:59], v[178:181], v[186:189], v[56:59]
	v_mfma_f32_16x16x32_bf16 v[52:55], v[170:173], v[196:199], v[52:55]
	v_mfma_f32_16x16x32_bf16 v[48:51], v[178:181], v[196:199], v[48:51]
	v_mfma_f32_16x16x32_bf16 v[44:47], v[170:173], v[204:207], v[44:47]
	v_mfma_f32_16x16x32_bf16 v[40:43], v[178:181], v[204:207], v[40:43]
	v_mfma_f32_16x16x32_bf16 v[36:39], v[170:173], v[212:215], v[36:39]
	v_mfma_f32_16x16x32_bf16 v[32:35], v[178:181], v[212:215], v[32:35]
	v_mfma_f32_16x16x32_bf16 v[60:63], v[174:177], v[190:193], v[60:63]
	v_mfma_f32_16x16x32_bf16 v[56:59], v[182:185], v[190:193], v[56:59]
	v_mfma_f32_16x16x32_bf16 v[52:55], v[174:177], v[200:203], v[52:55]
	v_mfma_f32_16x16x32_bf16 v[48:51], v[182:185], v[200:203], v[48:51]
	v_mfma_f32_16x16x32_bf16 v[44:47], v[174:177], v[208:211], v[44:47]
	v_mfma_f32_16x16x32_bf16 v[40:43], v[182:185], v[208:211], v[40:43]
	v_mfma_f32_16x16x32_bf16 v[36:39], v[174:177], v[216:219], v[36:39]
	v_mfma_f32_16x16x32_bf16 v[32:35], v[182:185], v[216:219], v[32:35]
	v_mfma_f32_16x16x32_bf16 v[28:31], v[220:223], v[186:189], v[28:31]
	v_mfma_f32_16x16x32_bf16 v[24:27], v[228:231], v[186:189], v[24:27]
	v_mfma_f32_16x16x32_bf16 v[20:23], v[220:223], v[196:199], v[20:23]
	v_mfma_f32_16x16x32_bf16 v[16:19], v[228:231], v[196:199], v[16:19]
	v_mfma_f32_16x16x32_bf16 v[12:15], v[220:223], v[204:207], v[12:15]
	v_mfma_f32_16x16x32_bf16 v[8:11], v[228:231], v[204:207], v[8:11]
	v_mfma_f32_16x16x32_bf16 v[4:7], v[220:223], v[212:215], v[4:7]
	v_mfma_f32_16x16x32_bf16 v[0:3], v[228:231], v[212:215], v[0:3]
	v_mfma_f32_16x16x32_bf16 v[28:31], v[224:227], v[190:193], v[28:31]
	v_mfma_f32_16x16x32_bf16 v[24:27], v[232:235], v[190:193], v[24:27]
	v_mfma_f32_16x16x32_bf16 v[20:23], v[224:227], v[200:203], v[20:23]
	v_mfma_f32_16x16x32_bf16 v[16:19], v[232:235], v[200:203], v[16:19]
	v_mfma_f32_16x16x32_bf16 v[12:15], v[224:227], v[208:211], v[12:15]
	v_mfma_f32_16x16x32_bf16 v[8:11], v[232:235], v[208:211], v[8:11]
	v_mfma_f32_16x16x32_bf16 v[4:7], v[224:227], v[216:219], v[4:7]
	v_mfma_f32_16x16x32_bf16 v[0:3], v[232:235], v[216:219], v[0:3]
	s_add_i32 s17, s17, 2
	s_add_u32 s22, s22, 0x100
	s_addc_u32 s23, s23, 0
	s_cmp_gt_u32 s17, 27
	s_barrier
	s_cbranch_scc0 .LBB0_435
	v_readfirstlane_b32 s17, v168
	v_lshl_add_u64 v[128:129], v[128:129], 0, s[14:15]
	s_mov_b32 m0, s17
	v_readfirstlane_b32 s17, v169
	ds_read_b128 v[132:135], v167
	ds_read_b128 v[136:139], v167 offset:1024
	ds_read_b128 v[146:149], v167 offset:2048
	ds_read_b128 v[170:173], v167 offset:3072
	ds_read_b128 v[174:177], v157
	ds_read_b128 v[178:181], v157 offset:1024
	ds_read_b128 v[182:185], v156
	ds_read_b128 v[186:189], v156 offset:1024
	ds_read_b128 v[190:193], v155
	ds_read_b128 v[196:199], v155 offset:1024
	ds_read_b128 v[200:203], v154
	ds_read_b128 v[204:207], v154 offset:1024
	global_load_lds_dwordx4 v[128:129], off
	v_lshl_add_u64 v[128:129], v[130:131], 0, s[14:15]
	s_mov_b32 m0, s17
	s_nop 0
	global_load_lds_dwordx4 v[128:129], off
	s_barrier
	s_waitcnt lgkmcnt(0)
	s_waitcnt lgkmcnt(0)
	v_mfma_f32_16x16x32_bf16 v[124:127], v[132:135], v[174:177], v[124:127]
	v_mfma_f32_16x16x32_bf16 v[120:123], v[146:149], v[174:177], v[120:123]
	v_mfma_f32_16x16x32_bf16 v[116:119], v[132:135], v[182:185], v[116:119]
	v_mfma_f32_16x16x32_bf16 v[112:115], v[146:149], v[182:185], v[112:115]
	v_mfma_f32_16x16x32_bf16 v[104:107], v[146:149], v[190:193], v[104:107]
	v_mfma_f32_16x16x32_bf16 v[124:127], v[136:139], v[178:181], v[124:127]
	v_mfma_f32_16x16x32_bf16 v[120:123], v[170:173], v[178:181], v[120:123]
	v_mfma_f32_16x16x32_bf16 v[116:119], v[136:139], v[186:189], v[116:119]
	v_mfma_f32_16x16x32_bf16 v[112:115], v[170:173], v[186:189], v[112:115]
	v_mfma_f32_16x16x32_bf16 v[108:111], v[132:135], v[190:193], v[108:111]
	v_mfma_f32_16x16x32_bf16 v[128:131], v[170:173], v[196:199], v[104:107]
	v_mfma_f32_16x16x32_bf16 v[100:103], v[132:135], v[200:203], v[100:103]
	v_mfma_f32_16x16x32_bf16 v[96:99], v[146:149], v[200:203], v[96:99]
	v_mfma_f32_16x16x32_bf16 v[108:111], v[136:139], v[196:199], v[108:111]
	v_mfma_f32_16x16x32_bf16 v[100:103], v[136:139], v[204:207], v[100:103]
	v_mfma_f32_16x16x32_bf16 v[208:211], v[170:173], v[204:207], v[96:99]
	s_barrier
; #define WAIT_V(n) asm volatile("s_waitcnt vmcnt(" #n ")" ::: "memory")
; #define WAIT_L(n) asm volatile("s_waitcnt lgkmcnt(" #n ")" ::: "memory")
; #define BAR __builtin_amdgcn_s_barrier()
;     ...
;     { LDB(B0, 0, 0); LDA(At, 0, 0); STAGE(SA(1, 1), A, brow + HALF, nt - 1);
;       BAR; WAIT_L(0); MMA(0, 0, At, B0); BAR;
;       LDB(B1, 0, 1); BAR; WAIT_L(0); MMA(0, 1, At, B1); BAR;
;       LDA(At, 0, 1); WAIT_V(4); BAR; WAIT_L(0); MMA(1, 0, At, B0); MMA(1, 1, At, B1); BAR; }
;     { LDB(B0, 1, 0); LDA(At, 1, 0); WAIT_V(2); BAR; WAIT_L(0); MMA(0, 0, At, B0); BAR;
;       LDB(B1, 1, 1); WAIT_V(0); BAR; WAIT_L(0); MMA(0, 1, At, B1); BAR;
	s_nop 2
	ds_read_b128 v[96:99], v166
	ds_read_b128 v[104:107], v166 offset:1024
	ds_read_b128 v[212:215], v166 offset:2048
	ds_read_b128 v[164:167], v166 offset:3072
	s_barrier
	s_waitcnt lgkmcnt(0)
	s_waitcnt lgkmcnt(0)
	v_mfma_f32_16x16x32_bf16 v[92:95], v[96:99], v[174:177], v[92:95]
	v_mfma_f32_16x16x32_bf16 v[88:91], v[212:215], v[174:177], v[88:91]
	v_mfma_f32_16x16x32_bf16 v[84:87], v[96:99], v[182:185], v[84:87]
	v_mfma_f32_16x16x32_bf16 v[80:83], v[212:215], v[182:185], v[80:83]
	v_mfma_f32_16x16x32_bf16 v[76:79], v[96:99], v[190:193], v[76:79]
	v_mfma_f32_16x16x32_bf16 v[72:75], v[212:215], v[190:193], v[72:75]
	v_mfma_f32_16x16x32_bf16 v[68:71], v[96:99], v[200:203], v[68:71]
	v_mfma_f32_16x16x32_bf16 v[64:67], v[212:215], v[200:203], v[64:67]
	v_mfma_f32_16x16x32_bf16 v[92:95], v[104:107], v[178:181], v[92:95]
	v_mfma_f32_16x16x32_bf16 v[174:177], v[164:167], v[178:181], v[88:91]
	v_mfma_f32_16x16x32_bf16 v[84:87], v[104:107], v[186:189], v[84:87]
	v_mfma_f32_16x16x32_bf16 v[178:181], v[164:167], v[186:189], v[80:83]
	v_mfma_f32_16x16x32_bf16 v[76:79], v[104:107], v[196:199], v[76:79]
	v_mfma_f32_16x16x32_bf16 v[182:185], v[164:167], v[196:199], v[72:75]
	v_mfma_f32_16x16x32_bf16 v[68:71], v[104:107], v[204:207], v[68:71]
	v_mfma_f32_16x16x32_bf16 v[186:189], v[164:167], v[204:207], v[64:67]
	s_barrier
	s_nop 0
	ds_read_b128 v[64:67], v157 offset:16384
	ds_read_b128 v[72:75], v157 offset:17408
	ds_read_b128 v[80:83], v156 offset:16384
	ds_read_b128 v[88:91], v156 offset:17408
	ds_read_b128 v[190:193], v155 offset:16384
	ds_read_b128 v[196:199], v155 offset:17408
	ds_read_b128 v[200:203], v154 offset:16384
	ds_read_b128 v[204:207], v154 offset:17408
	s_waitcnt vmcnt(4)
	s_barrier
	s_waitcnt lgkmcnt(0)
	s_waitcnt lgkmcnt(0)
	v_mfma_f32_16x16x32_bf16 v[60:63], v[132:135], v[64:67], v[60:63]
	v_mfma_f32_16x16x32_bf16 v[56:59], v[146:149], v[64:67], v[56:59]
	v_mfma_f32_16x16x32_bf16 v[52:55], v[132:135], v[80:83], v[52:55]
	v_mfma_f32_16x16x32_bf16 v[48:51], v[146:149], v[80:83], v[48:51]
	v_mfma_f32_16x16x32_bf16 v[44:47], v[132:135], v[190:193], v[44:47]
	v_mfma_f32_16x16x32_bf16 v[40:43], v[146:149], v[190:193], v[40:43]
	v_mfma_f32_16x16x32_bf16 v[36:39], v[132:135], v[200:203], v[36:39]
	v_mfma_f32_16x16x32_bf16 v[32:35], v[146:149], v[200:203], v[32:35]
	v_mfma_f32_16x16x32_bf16 v[60:63], v[136:139], v[72:75], v[60:63]
	v_mfma_f32_16x16x32_bf16 v[56:59], v[170:173], v[72:75], v[56:59]
	v_mfma_f32_16x16x32_bf16 v[52:55], v[136:139], v[88:91], v[52:55]
	v_mfma_f32_16x16x32_bf16 v[48:51], v[170:173], v[88:91], v[48:51]
	v_mfma_f32_16x16x32_bf16 v[44:47], v[136:139], v[196:199], v[44:47]
	v_mfma_f32_16x16x32_bf16 v[40:43], v[170:173], v[196:199], v[40:43]
	v_mfma_f32_16x16x32_bf16 v[36:39], v[136:139], v[204:207], v[36:39]
	v_mfma_f32_16x16x32_bf16 v[32:35], v[170:173], v[204:207], v[32:35]
	v_mfma_f32_16x16x32_bf16 v[28:31], v[96:99], v[64:67], v[28:31]
	v_mfma_f32_16x16x32_bf16 v[24:27], v[212:215], v[64:67], v[24:27]
	v_mfma_f32_16x16x32_bf16 v[20:23], v[96:99], v[80:83], v[20:23]
	v_mfma_f32_16x16x32_bf16 v[16:19], v[212:215], v[80:83], v[16:19]
	v_mfma_f32_16x16x32_bf16 v[12:15], v[96:99], v[190:193], v[12:15]
	v_mfma_f32_16x16x32_bf16 v[8:11], v[212:215], v[190:193], v[8:11]
	v_mfma_f32_16x16x32_bf16 v[4:7], v[96:99], v[200:203], v[4:7]
	v_mfma_f32_16x16x32_bf16 v[0:3], v[212:215], v[200:203], v[0:3]
	v_mfma_f32_16x16x32_bf16 v[168:171], v[104:107], v[72:75], v[28:31]
	v_mfma_f32_16x16x32_bf16 v[216:219], v[164:167], v[72:75], v[24:27]
	v_mfma_f32_16x16x32_bf16 v[220:223], v[104:107], v[88:91], v[20:23]
	v_mfma_f32_16x16x32_bf16 v[224:227], v[164:167], v[88:91], v[16:19]
	v_mfma_f32_16x16x32_bf16 v[228:231], v[104:107], v[196:199], v[12:15]
	v_mfma_f32_16x16x32_bf16 v[190:193], v[164:167], v[196:199], v[8:11]
	v_mfma_f32_16x16x32_bf16 v[196:199], v[104:107], v[204:207], v[4:7]
	v_mfma_f32_16x16x32_bf16 v[164:167], v[164:167], v[204:207], v[0:3]
	s_barrier
	ds_read_b128 v[12:15], v145
	ds_read_b128 v[28:31], v145 offset:1024
	ds_read_b128 v[200:203], v145 offset:2048
	ds_read_b128 v[204:207], v145 offset:3072
	ds_read_b128 v[0:3], v157 offset:32768
	ds_read_b128 v[4:7], v157 offset:33792
	ds_read_b128 v[8:11], v156 offset:32768
	ds_read_b128 v[16:19], v156 offset:33792
	ds_read_b128 v[20:23], v155 offset:32768
	ds_read_b128 v[24:27], v155 offset:33792
	ds_read_b128 v[148:151], v154 offset:32768
	ds_read_b128 v[212:215], v154 offset:33792
	s_waitcnt vmcnt(2)
	s_barrier
; #define WAIT_V(n) asm volatile("s_waitcnt vmcnt(" #n ")" ::: "memory")
; #define WAIT_L(n) asm volatile("s_waitcnt lgkmcnt(" #n ")" ::: "memory")
; #define BAR __builtin_amdgcn_s_barrier()
;     ...
;       LDA(At, 0, 1); WAIT_V(4); BAR; WAIT_L(0); MMA(1, 0, At, B0); MMA(1, 1, At, B1); BAR; }
;     { LDB(B0, 1, 0); LDA(At, 1, 0); WAIT_V(2); BAR; WAIT_L(0); MMA(0, 0, At, B0); BAR;
;       LDB(B1, 1, 1); WAIT_V(0); BAR; WAIT_L(0); MMA(0, 1, At, B1); BAR;
;       LDA(At, 1, 1); BAR; WAIT_L(0); MMA(1, 0, At, B0); MMA(1, 1, At, B1); BAR; }
;     if (wr == 0) BAR;
	s_waitcnt lgkmcnt(0)
	s_waitcnt lgkmcnt(0)
	v_mfma_f32_16x16x32_bf16 v[72:75], v[200:203], v[0:3], v[120:123]
	v_mfma_f32_16x16x32_bf16 v[80:83], v[200:203], v[8:11], v[112:115]
	v_mfma_f32_16x16x32_bf16 v[88:91], v[200:203], v[20:23], v[128:131]
	v_mfma_f32_16x16x32_bf16 v[64:67], v[12:15], v[0:3], v[124:127]
	v_mfma_f32_16x16x32_bf16 v[96:99], v[204:207], v[4:7], v[72:75]
	v_mfma_f32_16x16x32_bf16 v[72:75], v[12:15], v[8:11], v[116:119]
	v_mfma_f32_16x16x32_bf16 v[104:107], v[204:207], v[16:19], v[80:83]
	v_mfma_f32_16x16x32_bf16 v[80:83], v[12:15], v[20:23], v[108:111]
	v_mfma_f32_16x16x32_bf16 v[112:115], v[204:207], v[24:27], v[88:91]
	v_mfma_f32_16x16x32_bf16 v[88:91], v[12:15], v[148:151], v[100:103]
	v_mfma_f32_16x16x32_bf16 v[100:103], v[200:203], v[148:151], v[208:211]
	v_mfma_f32_16x16x32_bf16 v[64:67], v[28:31], v[4:7], v[64:67]
	v_mfma_f32_16x16x32_bf16 v[72:75], v[28:31], v[16:19], v[72:75]
	v_mfma_f32_16x16x32_bf16 v[80:83], v[28:31], v[24:27], v[80:83]
	v_mfma_f32_16x16x32_bf16 v[88:91], v[28:31], v[212:215], v[88:91]
	v_mfma_f32_16x16x32_bf16 v[116:119], v[204:207], v[212:215], v[100:103]
	s_barrier
	s_nop 0
	ds_read_b128 v[100:103], v143
	ds_read_b128 v[108:111], v143 offset:1024
	ds_read_b128 v[208:211], v143 offset:2048
	ds_read_b128 v[232:235], v143 offset:3072
	s_waitcnt vmcnt(0)
	s_barrier
	s_waitcnt lgkmcnt(0)
	s_waitcnt lgkmcnt(0)
	v_mfma_f32_16x16x32_bf16 v[92:95], v[100:103], v[0:3], v[92:95]
	v_mfma_f32_16x16x32_bf16 v[0:3], v[208:211], v[0:3], v[174:177]
	v_mfma_f32_16x16x32_bf16 v[136:139], v[232:235], v[4:7], v[0:3]
	v_mfma_f32_16x16x32_bf16 v[0:3], v[100:103], v[8:11], v[84:87]
	v_mfma_f32_16x16x32_bf16 v[124:127], v[108:111], v[16:19], v[0:3]
	v_mfma_f32_16x16x32_bf16 v[0:3], v[208:211], v[8:11], v[178:181]
	v_mfma_f32_16x16x32_bf16 v[140:143], v[232:235], v[16:19], v[0:3]
	v_mfma_f32_16x16x32_bf16 v[0:3], v[100:103], v[20:23], v[76:79]
	v_mfma_f32_16x16x32_bf16 v[128:131], v[108:111], v[24:27], v[0:3]
	v_mfma_f32_16x16x32_bf16 v[0:3], v[208:211], v[20:23], v[182:185]
	v_mfma_f32_16x16x32_bf16 v[144:147], v[232:235], v[24:27], v[0:3]
	v_mfma_f32_16x16x32_bf16 v[0:3], v[100:103], v[148:151], v[68:71]
	v_mfma_f32_16x16x32_bf16 v[132:135], v[108:111], v[212:215], v[0:3]
	v_mfma_f32_16x16x32_bf16 v[0:3], v[208:211], v[148:151], v[186:189]
	v_mfma_f32_16x16x32_bf16 v[120:123], v[108:111], v[4:7], v[92:95]
	v_mfma_f32_16x16x32_bf16 v[148:151], v[232:235], v[212:215], v[0:3]
	s_barrier
	ds_read_b128 v[68:71], v157 offset:49152
	ds_read_b128 v[76:79], v157 offset:50176
	ds_read_b128 v[84:87], v156 offset:49152
	ds_read_b128 v[92:95], v156 offset:50176
	ds_read_b128 v[172:175], v155 offset:49152
	ds_read_b128 v[176:179], v155 offset:50176
	ds_read_b128 v[180:183], v154 offset:49152
	ds_read_b128 v[154:157], v154 offset:50176
	s_barrier
	s_waitcnt lgkmcnt(0)
	s_waitcnt lgkmcnt(0)
	v_mfma_f32_16x16x32_bf16 v[4:7], v[200:203], v[68:71], v[56:59]
	v_mfma_f32_16x16x32_bf16 v[8:11], v[200:203], v[84:87], v[48:51]
	v_mfma_f32_16x16x32_bf16 v[0:3], v[12:15], v[68:71], v[60:63]
	v_mfma_f32_16x16x32_bf16 v[16:19], v[204:207], v[76:79], v[4:7]
	v_mfma_f32_16x16x32_bf16 v[4:7], v[12:15], v[84:87], v[52:55]
	v_mfma_f32_16x16x32_bf16 v[20:23], v[204:207], v[92:95], v[8:11]
	v_mfma_f32_16x16x32_bf16 v[8:11], v[12:15], v[172:175], v[44:47]
	v_mfma_f32_16x16x32_bf16 v[12:15], v[12:15], v[180:183], v[36:39]
	v_mfma_f32_16x16x32_bf16 v[0:3], v[28:31], v[76:79], v[0:3]
	v_mfma_f32_16x16x32_bf16 v[4:7], v[28:31], v[92:95], v[4:7]
	v_mfma_f32_16x16x32_bf16 v[8:11], v[28:31], v[176:179], v[8:11]
	v_mfma_f32_16x16x32_bf16 v[24:27], v[200:203], v[172:175], v[40:43]
	v_mfma_f32_16x16x32_bf16 v[12:15], v[28:31], v[154:157], v[12:15]
	v_mfma_f32_16x16x32_bf16 v[28:31], v[200:203], v[180:183], v[32:35]
	v_mfma_f32_16x16x32_bf16 v[24:27], v[204:207], v[176:179], v[24:27]
	v_mfma_f32_16x16x32_bf16 v[28:31], v[204:207], v[154:157], v[28:31]
	v_mfma_f32_16x16x32_bf16 v[36:39], v[208:211], v[68:71], v[216:219]
	v_mfma_f32_16x16x32_bf16 v[40:43], v[208:211], v[84:87], v[224:227]
	v_mfma_f32_16x16x32_bf16 v[44:47], v[208:211], v[172:175], v[190:193]
	v_mfma_f32_16x16x32_bf16 v[32:35], v[100:103], v[68:71], v[168:171]
	v_mfma_f32_16x16x32_bf16 v[48:51], v[232:235], v[76:79], v[36:39]
	v_mfma_f32_16x16x32_bf16 v[36:39], v[100:103], v[84:87], v[220:223]
	v_mfma_f32_16x16x32_bf16 v[52:55], v[232:235], v[92:95], v[40:43]
	v_mfma_f32_16x16x32_bf16 v[40:43], v[100:103], v[172:175], v[228:231]
	v_mfma_f32_16x16x32_bf16 v[56:59], v[232:235], v[176:179], v[44:47]
	v_mfma_f32_16x16x32_bf16 v[44:47], v[100:103], v[180:183], v[196:199]
	v_mfma_f32_16x16x32_bf16 v[60:63], v[208:211], v[180:183], v[164:167]
	v_mfma_f32_16x16x32_bf16 v[32:35], v[108:111], v[76:79], v[32:35]
	v_mfma_f32_16x16x32_bf16 v[36:39], v[108:111], v[92:95], v[36:39]
	v_mfma_f32_16x16x32_bf16 v[40:43], v[108:111], v[176:179], v[40:43]
	v_mfma_f32_16x16x32_bf16 v[44:47], v[108:111], v[154:157], v[44:47]
	v_mfma_f32_16x16x32_bf16 v[60:63], v[232:235], v[154:157], v[60:63]
	s_setprio 0
	v_cmp_gt_u32_e32 vcc, s34, v152
	s_barrier
	s_and_saveexec_b64 s[22:23], vcc
	s_cbranch_execz .LBB0_438
	s_barrier

; #define WAIT_V(n) asm volatile("s_waitcnt vmcnt(" #n ")" ::: "memory")
; #define BAR __builtin_amdgcn_s_barrier()
;     ...
;     f32x4 acc[2][2][4][2] = {};
;     bf16x8 At[4][2], B0[2][2], B1[2][2];
;     STAGE(SB(0, 0), Bt, bcol, 0); STAGE(SA(0, 0), A, brow, 0);
;     STAGE(SB(0, 1), Bt, bcol + HALF, 0); STAGE(SA(0, 1), A, brow + HALF, 0);
;     if (wr == 1) BAR;
;     WAIT_V(4); BAR;
.Lp6_hdr2:
	v_mov_b64_e32 v[22:23], 0
	v_mov_b64_e32 v[24:25], 0
	v_mov_b64_e32 v[26:27], 0
	v_mov_b64_e32 v[28:29], 0
	v_mov_b64_e32 v[30:31], 0
	v_mov_b64_e32 v[32:33], 0
	v_mov_b64_e32 v[34:35], 0
	v_mov_b64_e32 v[36:37], 0
	v_mov_b64_e32 v[38:39], 0
	v_mov_b64_e32 v[40:41], 0
	v_mov_b64_e32 v[42:43], 0
	v_mov_b64_e32 v[44:45], 0
	v_mov_b64_e32 v[46:47], 0
	v_mov_b64_e32 v[48:49], 0
	v_mov_b64_e32 v[50:51], 0
	v_mov_b64_e32 v[52:53], 0
	v_mov_b64_e32 v[54:55], 0
	v_mov_b64_e32 v[56:57], 0
	v_mov_b64_e32 v[58:59], 0
	v_mov_b64_e32 v[60:61], 0
	v_mov_b64_e32 v[62:63], 0
	v_mov_b64_e32 v[64:65], 0
	v_mov_b64_e32 v[66:67], 0
	v_mov_b64_e32 v[68:69], 0
	v_mov_b64_e32 v[70:71], 0
	v_mov_b64_e32 v[72:73], 0
	v_mov_b64_e32 v[74:75], 0
	v_mov_b64_e32 v[76:77], 0
	v_mov_b64_e32 v[78:79], 0
	v_mov_b64_e32 v[80:81], 0
	v_mov_b64_e32 v[82:83], 0
	v_mov_b64_e32 v[84:85], 0
	v_mov_b64_e32 v[86:87], 0
	v_mov_b64_e32 v[88:89], 0
	v_mov_b64_e32 v[90:91], 0
	v_mov_b64_e32 v[92:93], 0
	v_mov_b64_e32 v[94:95], 0
	v_mov_b64_e32 v[96:97], 0
	v_mov_b64_e32 v[98:99], 0
	v_mov_b64_e32 v[100:101], 0
	v_mov_b64_e32 v[102:103], 0
	v_mov_b64_e32 v[104:105], 0
	v_mov_b64_e32 v[106:107], 0
	v_mov_b64_e32 v[108:109], 0
	v_mov_b64_e32 v[110:111], 0
	v_mov_b64_e32 v[112:113], 0
	v_mov_b64_e32 v[114:115], 0
	v_mov_b64_e32 v[116:117], 0
	v_mov_b64_e32 v[118:119], 0
	v_mov_b64_e32 v[120:121], 0
	v_mov_b64_e32 v[122:123], 0
	v_mov_b64_e32 v[124:125], 0
	v_mov_b64_e32 v[126:127], 0
	v_cmp_eq_u32_e32 vcc, 1, v220
	v_readlane_b32 s41, v248, 11
	v_readlane_b32 s44, v248, 14
	v_readlane_b32 s45, v248, 15
	v_readlane_b32 s46, v248, 16
	v_readlane_b32 s47, v248, 17
	v_readlane_b32 s48, v248, 18
	v_readlane_b32 s49, v248, 19
	v_readlane_b32 s50, v248, 20
	v_readlane_b32 s51, v248, 21
	v_readlane_b32 s52, v248, 22
	v_readlane_b32 s53, v248, 23
	v_readlane_b32 s54, v248, 24
	v_readlane_b32 s55, v248, 25
	s_and_saveexec_b64 s[28:29], vcc
	s_cbranch_execz .LBB0_549
	s_setprio 1
	s_barrier

; #define WAIT_V(n) asm volatile("s_waitcnt vmcnt(" #n ")" ::: "memory")
; #define WAIT_L(n) asm volatile("s_waitcnt lgkmcnt(" #n ")" ::: "memory")
; #define BAR __builtin_amdgcn_s_barrier()
; #define SCHED __builtin_amdgcn_sched_barrier(0)
;     ...
;       LDB(B0, 0, 0); SCHED; LDA(At, 0, 0); STAGE(SA(1, 1), A, brow + HALF, t + 1);
;       WAIT_L(8); BAR; WAIT_L(0); MMA(0, 0, At, B0); BAR; SCHED;
;       LDB(B1, 0, 1); STAGE(SB(0, 0), Bt, bcol, t + 2);
;       BAR; WAIT_L(0); MMA(0, 1, At, B1); BAR;
;       LDA(At, 0, 1); STAGE(SA(0, 0), A, brow, t + 2);
;       BAR; WAIT_L(0); MMA(1, 0, At, B0); BAR; SCHED;
;       STAGE(SB(0, 1), Bt, bcol + HALF, t + 2);
;       WAIT_V(6); BAR; MMA(1, 1, At, B1); BAR;
.LBB0_550:
	v_add_u32_e32 v167, 0xc000, v147
	v_add_u32_e32 v168, 0xe000, v147
	v_add_u32_e32 v169, 0x2000, v140
	v_add_u32_e32 v169, 0x2000, v155
	ds_read_b128 v[170:173], v166
	ds_read_b128 v[174:177], v166 offset:1024
	ds_read_b128 v[178:181], v166 offset:2048
	ds_read_b128 v[182:185], v166 offset:3072
	ds_read_b128 v[186:189], v146
	ds_read_b128 v[190:193], v146 offset:1024
	ds_read_b128 v[196:199], v143
	ds_read_b128 v[200:203], v143 offset:1024
	ds_read_b128 v[204:207], v142
	ds_read_b128 v[208:211], v142 offset:1024
	ds_read_b128 v[212:215], v141
	ds_read_b128 v[216:219], v141 offset:1024
	ds_read_b128 v[220:223], v165
	ds_read_b128 v[224:227], v165 offset:1024
	ds_read_b128 v[228:231], v165 offset:2048
	ds_read_b128 v[232:235], v165 offset:3072
	v_add_u32_e32 v254, 0xc000, v147
	v_lshl_add_u64 v[250:251], v[136:137], 0, s[4:5]
	v_readfirstlane_b32 s26, v254
	v_lshl_add_u64 v[250:251], v[250:251], 0, s[6:7]
	s_mov_b32 m0, s26
	s_nop 0
	global_load_lds_dwordx4 v[250:251], off
	v_add_u32_e32 v254, 0xe000, v147
	v_lshl_add_u64 v[252:253], v[138:139], 0, s[4:5]
	v_readfirstlane_b32 s26, v254
	v_lshl_add_u64 v[252:253], v[252:253], 0, s[6:7]
	s_mov_b32 m0, s26
	s_nop 0
	global_load_lds_dwordx4 v[252:253], off
	s_waitcnt lgkmcnt(0)
	s_barrier
	v_mfma_f32_16x16x32_bf16 v[124:127], v[170:173], v[186:189], v[124:127]
	v_mfma_f32_16x16x32_bf16 v[120:123], v[178:181], v[186:189], v[120:123]
	v_mfma_f32_16x16x32_bf16 v[116:119], v[170:173], v[196:199], v[116:119]
	v_mfma_f32_16x16x32_bf16 v[112:115], v[178:181], v[196:199], v[112:115]
	v_mfma_f32_16x16x32_bf16 v[108:111], v[170:173], v[204:207], v[108:111]
	v_mfma_f32_16x16x32_bf16 v[104:107], v[178:181], v[204:207], v[104:107]
	v_mfma_f32_16x16x32_bf16 v[100:103], v[170:173], v[212:215], v[100:103]
	v_mfma_f32_16x16x32_bf16 v[96:99], v[178:181], v[212:215], v[96:99]
	v_mfma_f32_16x16x32_bf16 v[124:127], v[174:177], v[190:193], v[124:127]
	v_mfma_f32_16x16x32_bf16 v[120:123], v[182:185], v[190:193], v[120:123]
	v_mfma_f32_16x16x32_bf16 v[116:119], v[174:177], v[200:203], v[116:119]
	v_mfma_f32_16x16x32_bf16 v[112:115], v[182:185], v[200:203], v[112:115]
	v_mfma_f32_16x16x32_bf16 v[108:111], v[174:177], v[208:211], v[108:111]
	v_mfma_f32_16x16x32_bf16 v[104:107], v[182:185], v[208:211], v[104:107]
	v_mfma_f32_16x16x32_bf16 v[100:103], v[174:177], v[216:219], v[100:103]
	v_mfma_f32_16x16x32_bf16 v[96:99], v[182:185], v[216:219], v[96:99]
	v_mfma_f32_16x16x32_bf16 v[92:95], v[220:223], v[186:189], v[92:95]
	v_mfma_f32_16x16x32_bf16 v[88:91], v[228:231], v[186:189], v[88:91]
	v_mfma_f32_16x16x32_bf16 v[84:87], v[220:223], v[196:199], v[84:87]
	v_mfma_f32_16x16x32_bf16 v[80:83], v[228:231], v[196:199], v[80:83]
	v_mfma_f32_16x16x32_bf16 v[76:79], v[220:223], v[204:207], v[76:79]
	v_mfma_f32_16x16x32_bf16 v[72:75], v[228:231], v[204:207], v[72:75]
	v_mfma_f32_16x16x32_bf16 v[68:71], v[220:223], v[212:215], v[68:71]
	v_mfma_f32_16x16x32_bf16 v[64:67], v[228:231], v[212:215], v[64:67]
	v_mfma_f32_16x16x32_bf16 v[92:95], v[224:227], v[190:193], v[92:95]
	v_mfma_f32_16x16x32_bf16 v[88:91], v[232:235], v[190:193], v[88:91]
	v_mfma_f32_16x16x32_bf16 v[84:87], v[224:227], v[200:203], v[84:87]
	v_mfma_f32_16x16x32_bf16 v[80:83], v[232:235], v[200:203], v[80:83]
	v_mfma_f32_16x16x32_bf16 v[76:79], v[224:227], v[208:211], v[76:79]
	v_mfma_f32_16x16x32_bf16 v[72:75], v[232:235], v[208:211], v[72:75]
	v_mfma_f32_16x16x32_bf16 v[68:71], v[224:227], v[216:219], v[68:71]
	v_mfma_f32_16x16x32_bf16 v[64:67], v[232:235], v[216:219], v[64:67]
	s_barrier
	ds_read_b128 v[186:189], v146 offset:16384
	ds_read_b128 v[190:193], v146 offset:17408
	ds_read_b128 v[196:199], v143 offset:16384
	ds_read_b128 v[200:203], v143 offset:17408
	ds_read_b128 v[204:207], v142 offset:16384
	ds_read_b128 v[208:211], v142 offset:17408
	ds_read_b128 v[212:215], v141 offset:16384
	ds_read_b128 v[216:219], v141 offset:17408
	v_lshl_add_u64 v[250:251], v[132:133], 0, s[4:5]
	v_readfirstlane_b32 s26, v140
	v_lshl_add_u64 v[250:251], v[250:251], 0, s[8:9]
	s_mov_b32 m0, s26
	s_nop 0
	global_load_lds_dwordx4 v[250:251], off
	v_add_u32_e32 v254, 0x2000, v140
	v_lshl_add_u64 v[252:253], v[134:135], 0, s[4:5]
	v_readfirstlane_b32 s26, v254
	v_lshl_add_u64 v[252:253], v[252:253], 0, s[8:9]
	s_mov_b32 m0, s26
	s_nop 0
	global_load_lds_dwordx4 v[252:253], off
	v_lshl_add_u64 v[250:251], v[136:137], 0, s[4:5]
	v_readfirstlane_b32 s26, v147
	v_lshl_add_u64 v[250:251], v[250:251], 0, s[8:9]
	s_mov_b32 m0, s26
	s_nop 0
	global_load_lds_dwordx4 v[250:251], off
	v_lshl_add_u64 v[252:253], v[138:139], 0, s[4:5]
	v_readfirstlane_b32 s26, v153
	v_lshl_add_u64 v[252:253], v[252:253], 0, s[8:9]
	s_mov_b32 m0, s26
	s_nop 0
	global_load_lds_dwordx4 v[252:253], off
	v_lshl_add_u64 v[250:251], v[132:133], 0, s[4:5]
	v_readfirstlane_b32 s26, v155
	v_lshl_add_u64 v[250:251], v[250:251], 0, s[10:11]
	s_mov_b32 m0, s26
	s_nop 0
	global_load_lds_dwordx4 v[250:251], off
	v_add_u32_e32 v254, 0x2000, v155
	v_lshl_add_u64 v[252:253], v[134:135], 0, s[4:5]
	v_readfirstlane_b32 s26, v254
	v_lshl_add_u64 v[252:253], v[252:253], 0, s[10:11]
	s_mov_b32 m0, s26
	s_nop 0
	global_load_lds_dwordx4 v[252:253], off
	s_waitcnt vmcnt(6)
	s_waitcnt lgkmcnt(0)
	s_barrier
; #define WAIT_V(n) asm volatile("s_waitcnt vmcnt(" #n ")" ::: "memory")
; #define WAIT_L(n) asm volatile("s_waitcnt lgkmcnt(" #n ")" ::: "memory")
; #define BAR __builtin_amdgcn_s_barrier()
; #define SCHED __builtin_amdgcn_sched_barrier(0)
;     ...
;       WAIT_V(6); BAR; MMA(1, 1, At, B1); BAR;
;       LDB(B0, 1, 0); SCHED; LDA(At, 1, 0); STAGE(SA(0, 1), A, brow + HALF, t + 2);
;       WAIT_L(8); BAR; WAIT_L(0); MMA(0, 0, At, B0); BAR; SCHED;
;       LDB(B1, 1, 1); STAGE(SB(1, 0), Bt, bcol, t + 3);
;       BAR; WAIT_L(0); MMA(0, 1, At, B1); BAR;
;       LDA(At, 1, 1); STAGE(SA(1, 0), A, brow, t + 3);
;       BAR; WAIT_L(0); MMA(1, 0, At, B0); BAR; SCHED;
;       STAGE(SB(1, 1), Bt, bcol + HALF, t + 3);
	v_mfma_f32_16x16x32_bf16 v[60:63], v[170:173], v[186:189], v[60:63]
	v_mfma_f32_16x16x32_bf16 v[56:59], v[178:181], v[186:189], v[56:59]
	v_mfma_f32_16x16x32_bf16 v[52:55], v[170:173], v[196:199], v[52:55]
	v_mfma_f32_16x16x32_bf16 v[48:51], v[178:181], v[196:199], v[48:51]
	v_mfma_f32_16x16x32_bf16 v[44:47], v[170:173], v[204:207], v[44:47]
	v_mfma_f32_16x16x32_bf16 v[40:43], v[178:181], v[204:207], v[40:43]
	v_mfma_f32_16x16x32_bf16 v[36:39], v[170:173], v[212:215], v[36:39]
	v_mfma_f32_16x16x32_bf16 v[32:35], v[178:181], v[212:215], v[32:35]
	v_mfma_f32_16x16x32_bf16 v[60:63], v[174:177], v[190:193], v[60:63]
	v_mfma_f32_16x16x32_bf16 v[56:59], v[182:185], v[190:193], v[56:59]
	v_mfma_f32_16x16x32_bf16 v[52:55], v[174:177], v[200:203], v[52:55]
	v_mfma_f32_16x16x32_bf16 v[48:51], v[182:185], v[200:203], v[48:51]
	v_mfma_f32_16x16x32_bf16 v[44:47], v[174:177], v[208:211], v[44:47]
	v_mfma_f32_16x16x32_bf16 v[40:43], v[182:185], v[208:211], v[40:43]
	v_mfma_f32_16x16x32_bf16 v[36:39], v[174:177], v[216:219], v[36:39]
	v_mfma_f32_16x16x32_bf16 v[32:35], v[182:185], v[216:219], v[32:35]
	v_mfma_f32_16x16x32_bf16 v[28:31], v[220:223], v[186:189], v[28:31]
	v_mfma_f32_16x16x32_bf16 v[24:27], v[228:231], v[186:189], v[24:27]
	v_mfma_f32_16x16x32_bf16 v[20:23], v[220:223], v[196:199], v[20:23]
	v_mfma_f32_16x16x32_bf16 v[16:19], v[228:231], v[196:199], v[16:19]
	v_mfma_f32_16x16x32_bf16 v[12:15], v[220:223], v[204:207], v[12:15]
	v_mfma_f32_16x16x32_bf16 v[8:11], v[228:231], v[204:207], v[8:11]
	v_mfma_f32_16x16x32_bf16 v[4:7], v[220:223], v[212:215], v[4:7]
	v_mfma_f32_16x16x32_bf16 v[0:3], v[228:231], v[212:215], v[0:3]
	v_mfma_f32_16x16x32_bf16 v[28:31], v[224:227], v[190:193], v[28:31]
	v_mfma_f32_16x16x32_bf16 v[24:27], v[232:235], v[190:193], v[24:27]
	v_mfma_f32_16x16x32_bf16 v[20:23], v[224:227], v[200:203], v[20:23]
	v_mfma_f32_16x16x32_bf16 v[16:19], v[232:235], v[200:203], v[16:19]
	v_mfma_f32_16x16x32_bf16 v[12:15], v[224:227], v[208:211], v[12:15]
	v_mfma_f32_16x16x32_bf16 v[8:11], v[232:235], v[208:211], v[8:11]
	v_mfma_f32_16x16x32_bf16 v[4:7], v[224:227], v[216:219], v[4:7]
	v_mfma_f32_16x16x32_bf16 v[0:3], v[232:235], v[216:219], v[0:3]
	s_barrier
	ds_read_b128 v[170:173], v156
	ds_read_b128 v[174:177], v156 offset:1024
	ds_read_b128 v[178:181], v156 offset:2048
	ds_read_b128 v[182:185], v156 offset:3072
	ds_read_b128 v[186:189], v146 offset:32768
	ds_read_b128 v[190:193], v146 offset:33792
	ds_read_b128 v[196:199], v143 offset:32768
	ds_read_b128 v[200:203], v143 offset:33792
	ds_read_b128 v[204:207], v142 offset:32768
	ds_read_b128 v[208:211], v142 offset:33792
	ds_read_b128 v[212:215], v141 offset:32768
	ds_read_b128 v[216:219], v141 offset:33792
	ds_read_b128 v[220:223], v154
	ds_read_b128 v[224:227], v154 offset:1024
	ds_read_b128 v[228:231], v154 offset:2048
	ds_read_b128 v[232:235], v154 offset:3072
	v_lshl_add_u64 v[250:251], v[136:137], 0, s[4:5]
	v_readfirstlane_b32 s26, v157
	v_lshl_add_u64 v[250:251], v[250:251], 0, s[10:11]
	s_mov_b32 m0, s26
	s_nop 0
	global_load_lds_dwordx4 v[250:251], off
	v_lshl_add_u64 v[252:253], v[138:139], 0, s[4:5]
	v_readfirstlane_b32 s26, v158
	v_lshl_add_u64 v[252:253], v[252:253], 0, s[10:11]
	s_mov_b32 m0, s26
	s_nop 0
	global_load_lds_dwordx4 v[252:253], off
	s_waitcnt lgkmcnt(0)
	s_barrier
	v_mfma_f32_16x16x32_bf16 v[124:127], v[170:173], v[186:189], v[124:127]
	v_mfma_f32_16x16x32_bf16 v[120:123], v[178:181], v[186:189], v[120:123]
	v_mfma_f32_16x16x32_bf16 v[116:119], v[170:173], v[196:199], v[116:119]
	v_mfma_f32_16x16x32_bf16 v[112:115], v[178:181], v[196:199], v[112:115]
	v_mfma_f32_16x16x32_bf16 v[108:111], v[170:173], v[204:207], v[108:111]
	v_mfma_f32_16x16x32_bf16 v[104:107], v[178:181], v[204:207], v[104:107]
	v_mfma_f32_16x16x32_bf16 v[100:103], v[170:173], v[212:215], v[100:103]
	v_mfma_f32_16x16x32_bf16 v[96:99], v[178:181], v[212:215], v[96:99]
	v_mfma_f32_16x16x32_bf16 v[124:127], v[174:177], v[190:193], v[124:127]
	v_mfma_f32_16x16x32_bf16 v[120:123], v[182:185], v[190:193], v[120:123]
	v_mfma_f32_16x16x32_bf16 v[116:119], v[174:177], v[200:203], v[116:119]
	v_mfma_f32_16x16x32_bf16 v[112:115], v[182:185], v[200:203], v[112:115]
	v_mfma_f32_16x16x32_bf16 v[108:111], v[174:177], v[208:211], v[108:111]
	v_mfma_f32_16x16x32_bf16 v[104:107], v[182:185], v[208:211], v[104:107]
	v_mfma_f32_16x16x32_bf16 v[100:103], v[174:177], v[216:219], v[100:103]
	v_mfma_f32_16x16x32_bf16 v[96:99], v[182:185], v[216:219], v[96:99]
	v_mfma_f32_16x16x32_bf16 v[92:95], v[220:223], v[186:189], v[92:95]
	v_mfma_f32_16x16x32_bf16 v[88:91], v[228:231], v[186:189], v[88:91]
	v_mfma_f32_16x16x32_bf16 v[84:87], v[220:223], v[196:199], v[84:87]
	v_mfma_f32_16x16x32_bf16 v[80:83], v[228:231], v[196:199], v[80:83]
	v_mfma_f32_16x16x32_bf16 v[76:79], v[220:223], v[204:207], v[76:79]
	v_mfma_f32_16x16x32_bf16 v[72:75], v[228:231], v[204:207], v[72:75]
	v_mfma_f32_16x16x32_bf16 v[68:71], v[220:223], v[212:215], v[68:71]
	v_mfma_f32_16x16x32_bf16 v[64:67], v[228:231], v[212:215], v[64:67]
	v_mfma_f32_16x16x32_bf16 v[92:95], v[224:227], v[190:193], v[92:95]
	v_mfma_f32_16x16x32_bf16 v[88:91], v[232:235], v[190:193], v[88:91]
	v_mfma_f32_16x16x32_bf16 v[84:87], v[224:227], v[200:203], v[84:87]
	v_mfma_f32_16x16x32_bf16 v[80:83], v[232:235], v[200:203], v[80:83]
	v_mfma_f32_16x16x32_bf16 v[76:79], v[224:227], v[208:211], v[76:79]
	v_mfma_f32_16x16x32_bf16 v[72:75], v[232:235], v[208:211], v[72:75]
	v_mfma_f32_16x16x32_bf16 v[68:71], v[224:227], v[216:219], v[68:71]
	v_mfma_f32_16x16x32_bf16 v[64:67], v[232:235], v[216:219], v[64:67]
	s_barrier
; #define WAIT_V(n) asm volatile("s_waitcnt vmcnt(" #n ")" ::: "memory")
; #define WAIT_L(n) asm volatile("s_waitcnt lgkmcnt(" #n ")" ::: "memory")
; #define BAR __builtin_amdgcn_s_barrier()
; #define SCHED __builtin_amdgcn_sched_barrier(0)
;     ...
;       LDA(At, 1, 1); STAGE(SA(1, 0), A, brow, t + 3);
;       BAR; WAIT_L(0); MMA(1, 0, At, B0); BAR; SCHED;
;       STAGE(SB(1, 1), Bt, bcol + HALF, t + 3);
;       WAIT_V(6); BAR; MMA(1, 1, At, B1); BAR;
;     }
;     { LDB(B0, 0, 0); LDA(At, 0, 0); STAGE(SA(1, 1), A, brow + HALF, nt - 1);
;       BAR; WAIT_L(0); MMA(0, 0, At, B0); BAR;
;       LDB(B1, 0, 1); BAR; WAIT_L(0); MMA(0, 1, At, B1); BAR;
;       LDA(At, 0, 1); WAIT_V(4); BAR; WAIT_L(0); MMA(1, 0, At, B0); MMA(1, 1, At, B1); BAR; }
	ds_read_b128 v[186:189], v146 offset:49152
	ds_read_b128 v[190:193], v146 offset:50176
	ds_read_b128 v[196:199], v143 offset:49152
	ds_read_b128 v[200:203], v143 offset:50176
	ds_read_b128 v[204:207], v142 offset:49152
	ds_read_b128 v[208:211], v142 offset:50176
	ds_read_b128 v[212:215], v141 offset:49152
	ds_read_b128 v[216:219], v141 offset:50176
	v_lshl_add_u64 v[250:251], v[132:133], 0, s[4:5]
	v_readfirstlane_b32 s26, v159
	v_lshl_add_u64 v[250:251], v[250:251], 0, s[12:13]
	s_mov_b32 m0, s26
	s_nop 0
	global_load_lds_dwordx4 v[250:251], off
	v_lshl_add_u64 v[252:253], v[134:135], 0, s[4:5]
	v_readfirstlane_b32 s26, v160
	v_lshl_add_u64 v[252:253], v[252:253], 0, s[12:13]
	s_mov_b32 m0, s26
	s_nop 0
	global_load_lds_dwordx4 v[252:253], off
	v_lshl_add_u64 v[250:251], v[136:137], 0, s[4:5]
	v_readfirstlane_b32 s26, v161
	v_lshl_add_u64 v[250:251], v[250:251], 0, s[12:13]
	s_mov_b32 m0, s26
	s_nop 0
	global_load_lds_dwordx4 v[250:251], off
	v_lshl_add_u64 v[252:253], v[138:139], 0, s[4:5]
	v_readfirstlane_b32 s26, v162
	v_lshl_add_u64 v[252:253], v[252:253], 0, s[12:13]
	s_mov_b32 m0, s26
	s_nop 0
	global_load_lds_dwordx4 v[252:253], off
	v_lshl_add_u64 v[250:251], v[132:133], 0, s[4:5]
	v_readfirstlane_b32 s26, v163
	v_lshl_add_u64 v[250:251], v[250:251], 0, s[14:15]
	s_mov_b32 m0, s26
	s_nop 0
	global_load_lds_dwordx4 v[250:251], off
	v_lshl_add_u64 v[252:253], v[134:135], 0, s[4:5]
	v_readfirstlane_b32 s26, v164
	v_lshl_add_u64 v[252:253], v[252:253], 0, s[14:15]
	s_mov_b32 m0, s26
	s_nop 0
	global_load_lds_dwordx4 v[252:253], off
	s_waitcnt vmcnt(6)
	s_waitcnt lgkmcnt(0)
	s_barrier
	v_mfma_f32_16x16x32_bf16 v[60:63], v[170:173], v[186:189], v[60:63]
	v_mfma_f32_16x16x32_bf16 v[56:59], v[178:181], v[186:189], v[56:59]
	v_mfma_f32_16x16x32_bf16 v[52:55], v[170:173], v[196:199], v[52:55]
	v_mfma_f32_16x16x32_bf16 v[48:51], v[178:181], v[196:199], v[48:51]
	v_mfma_f32_16x16x32_bf16 v[44:47], v[170:173], v[204:207], v[44:47]
	v_mfma_f32_16x16x32_bf16 v[40:43], v[178:181], v[204:207], v[40:43]
	v_mfma_f32_16x16x32_bf16 v[36:39], v[170:173], v[212:215], v[36:39]
	v_mfma_f32_16x16x32_bf16 v[32:35], v[178:181], v[212:215], v[32:35]
	v_mfma_f32_16x16x32_bf16 v[60:63], v[174:177], v[190:193], v[60:63]
	v_mfma_f32_16x16x32_bf16 v[56:59], v[182:185], v[190:193], v[56:59]
	v_mfma_f32_16x16x32_bf16 v[52:55], v[174:177], v[200:203], v[52:55]
	v_mfma_f32_16x16x32_bf16 v[48:51], v[182:185], v[200:203], v[48:51]
	v_mfma_f32_16x16x32_bf16 v[44:47], v[174:177], v[208:211], v[44:47]
	v_mfma_f32_16x16x32_bf16 v[40:43], v[182:185], v[208:211], v[40:43]
	v_mfma_f32_16x16x32_bf16 v[36:39], v[174:177], v[216:219], v[36:39]
	v_mfma_f32_16x16x32_bf16 v[32:35], v[182:185], v[216:219], v[32:35]
	v_mfma_f32_16x16x32_bf16 v[28:31], v[220:223], v[186:189], v[28:31]
	v_mfma_f32_16x16x32_bf16 v[24:27], v[228:231], v[186:189], v[24:27]
	v_mfma_f32_16x16x32_bf16 v[20:23], v[220:223], v[196:199], v[20:23]
	v_mfma_f32_16x16x32_bf16 v[16:19], v[228:231], v[196:199], v[16:19]
	v_mfma_f32_16x16x32_bf16 v[12:15], v[220:223], v[204:207], v[12:15]
	v_mfma_f32_16x16x32_bf16 v[8:11], v[228:231], v[204:207], v[8:11]
	v_mfma_f32_16x16x32_bf16 v[4:7], v[220:223], v[212:215], v[4:7]
	v_mfma_f32_16x16x32_bf16 v[0:3], v[228:231], v[212:215], v[0:3]
	v_mfma_f32_16x16x32_bf16 v[28:31], v[224:227], v[190:193], v[28:31]
	v_mfma_f32_16x16x32_bf16 v[24:27], v[232:235], v[190:193], v[24:27]
	v_mfma_f32_16x16x32_bf16 v[20:23], v[224:227], v[200:203], v[20:23]
	v_mfma_f32_16x16x32_bf16 v[16:19], v[232:235], v[200:203], v[16:19]
	v_mfma_f32_16x16x32_bf16 v[12:15], v[224:227], v[208:211], v[12:15]
	v_mfma_f32_16x16x32_bf16 v[8:11], v[232:235], v[208:211], v[8:11]
	v_mfma_f32_16x16x32_bf16 v[4:7], v[224:227], v[216:219], v[4:7]
	v_mfma_f32_16x16x32_bf16 v[0:3], v[232:235], v[216:219], v[0:3]
	s_add_i32 s25, s25, 2
	s_add_u32 s4, s4, 0x100
	s_addc_u32 s5, s5, 0
	s_cmp_gt_u32 s25, 27
	s_barrier
	s_cbranch_scc0 .LBB0_550
	v_readfirstlane_b32 s4, v167
	v_lshl_add_u64 v[128:129], v[128:129], 0, s[16:17]
	s_mov_b32 m0, s4
	v_readfirstlane_b32 s4, v168
	ds_read_b128 v[132:135], v166
	ds_read_b128 v[136:139], v166 offset:1024
	ds_read_b128 v[158:161], v166 offset:2048
	ds_read_b128 v[170:173], v166 offset:3072
	ds_read_b128 v[174:177], v146
	ds_read_b128 v[178:181], v146 offset:1024
	ds_read_b128 v[182:185], v143
	ds_read_b128 v[186:189], v143 offset:1024
	ds_read_b128 v[190:193], v142
	ds_read_b128 v[196:199], v142 offset:1024
	ds_read_b128 v[200:203], v141
	ds_read_b128 v[204:207], v141 offset:1024
	global_load_lds_dwordx4 v[128:129], off
	v_lshl_add_u64 v[128:129], v[130:131], 0, s[16:17]
	s_mov_b32 m0, s4
	s_nop 0
	global_load_lds_dwordx4 v[128:129], off
	s_barrier
	s_waitcnt lgkmcnt(0)
	s_waitcnt lgkmcnt(0)
	v_mfma_f32_16x16x32_bf16 v[124:127], v[132:135], v[174:177], v[124:127]
	v_mfma_f32_16x16x32_bf16 v[120:123], v[158:161], v[174:177], v[120:123]
	v_mfma_f32_16x16x32_bf16 v[116:119], v[132:135], v[182:185], v[116:119]
	v_mfma_f32_16x16x32_bf16 v[112:115], v[158:161], v[182:185], v[112:115]
	v_mfma_f32_16x16x32_bf16 v[124:127], v[136:139], v[178:181], v[124:127]
	v_mfma_f32_16x16x32_bf16 v[120:123], v[170:173], v[178:181], v[120:123]
	v_mfma_f32_16x16x32_bf16 v[116:119], v[136:139], v[186:189], v[116:119]
	v_mfma_f32_16x16x32_bf16 v[112:115], v[170:173], v[186:189], v[112:115]
	v_mfma_f32_16x16x32_bf16 v[108:111], v[132:135], v[190:193], v[108:111]
	v_mfma_f32_16x16x32_bf16 v[104:107], v[158:161], v[190:193], v[104:107]
	v_mfma_f32_16x16x32_bf16 v[100:103], v[132:135], v[200:203], v[100:103]
	v_mfma_f32_16x16x32_bf16 v[96:99], v[158:161], v[200:203], v[96:99]
	v_mfma_f32_16x16x32_bf16 v[128:131], v[136:139], v[196:199], v[108:111]
	v_mfma_f32_16x16x32_bf16 v[166:169], v[170:173], v[196:199], v[104:107]
	v_mfma_f32_16x16x32_bf16 v[208:211], v[136:139], v[204:207], v[100:103]
	v_mfma_f32_16x16x32_bf16 v[212:215], v[170:173], v[204:207], v[96:99]
	s_barrier
; #define WAIT_V(n) asm volatile("s_waitcnt vmcnt(" #n ")" ::: "memory")
; #define WAIT_L(n) asm volatile("s_waitcnt lgkmcnt(" #n ")" ::: "memory")
; #define BAR __builtin_amdgcn_s_barrier()
;     ...
;     { LDB(B0, 0, 0); LDA(At, 0, 0); STAGE(SA(1, 1), A, brow + HALF, nt - 1);
;       BAR; WAIT_L(0); MMA(0, 0, At, B0); BAR;
;       LDB(B1, 0, 1); BAR; WAIT_L(0); MMA(0, 1, At, B1); BAR;
;       LDA(At, 0, 1); WAIT_V(4); BAR; WAIT_L(0); MMA(1, 0, At, B0); MMA(1, 1, At, B1); BAR; }
;     { LDB(B0, 1, 0); LDA(At, 1, 0); WAIT_V(2); BAR; WAIT_L(0); MMA(0, 0, At, B0); BAR;
	s_nop 1
	ds_read_b128 v[96:99], v165
	ds_read_b128 v[100:103], v165 offset:1024
	ds_read_b128 v[104:107], v165 offset:2048
	ds_read_b128 v[108:111], v165 offset:3072
	s_barrier
	s_waitcnt lgkmcnt(0)
	s_waitcnt lgkmcnt(0)
	v_mfma_f32_16x16x32_bf16 v[92:95], v[96:99], v[174:177], v[92:95]
	v_mfma_f32_16x16x32_bf16 v[88:91], v[104:107], v[174:177], v[88:91]
	v_mfma_f32_16x16x32_bf16 v[68:71], v[96:99], v[200:203], v[68:71]
	v_mfma_f32_16x16x32_bf16 v[64:67], v[104:107], v[200:203], v[64:67]
	v_mfma_f32_16x16x32_bf16 v[92:95], v[100:103], v[178:181], v[92:95]
	v_mfma_f32_16x16x32_bf16 v[88:91], v[108:111], v[178:181], v[88:91]
	v_mfma_f32_16x16x32_bf16 v[84:87], v[96:99], v[182:185], v[84:87]
	v_mfma_f32_16x16x32_bf16 v[80:83], v[104:107], v[182:185], v[80:83]
	v_mfma_f32_16x16x32_bf16 v[76:79], v[96:99], v[190:193], v[76:79]
	v_mfma_f32_16x16x32_bf16 v[72:75], v[104:107], v[190:193], v[72:75]
	v_mfma_f32_16x16x32_bf16 v[68:71], v[100:103], v[204:207], v[68:71]
	v_mfma_f32_16x16x32_bf16 v[64:67], v[108:111], v[204:207], v[64:67]
	v_mfma_f32_16x16x32_bf16 v[162:165], v[100:103], v[186:189], v[84:87]
	v_mfma_f32_16x16x32_bf16 v[174:177], v[108:111], v[186:189], v[80:83]
	v_mfma_f32_16x16x32_bf16 v[178:181], v[100:103], v[196:199], v[76:79]
	v_mfma_f32_16x16x32_bf16 v[182:185], v[108:111], v[196:199], v[72:75]
	s_barrier
	s_nop 0
	ds_read_b128 v[72:75], v146 offset:16384
	ds_read_b128 v[76:79], v146 offset:17408
	ds_read_b128 v[80:83], v143 offset:16384
	ds_read_b128 v[84:87], v143 offset:17408
	ds_read_b128 v[186:189], v142 offset:16384
	ds_read_b128 v[190:193], v142 offset:17408
	ds_read_b128 v[196:199], v141 offset:16384
	ds_read_b128 v[200:203], v141 offset:17408
	s_waitcnt vmcnt(4)
	s_barrier
	s_waitcnt lgkmcnt(0)
	s_waitcnt lgkmcnt(0)
	v_mfma_f32_16x16x32_bf16 v[60:63], v[132:135], v[72:75], v[60:63]
	v_mfma_f32_16x16x32_bf16 v[56:59], v[158:161], v[72:75], v[56:59]
	v_mfma_f32_16x16x32_bf16 v[44:47], v[132:135], v[186:189], v[44:47]
	v_mfma_f32_16x16x32_bf16 v[40:43], v[158:161], v[186:189], v[40:43]
	v_mfma_f32_16x16x32_bf16 v[60:63], v[136:139], v[76:79], v[60:63]
	v_mfma_f32_16x16x32_bf16 v[56:59], v[170:173], v[76:79], v[56:59]
	v_mfma_f32_16x16x32_bf16 v[52:55], v[132:135], v[80:83], v[52:55]
	v_mfma_f32_16x16x32_bf16 v[48:51], v[158:161], v[80:83], v[48:51]
	v_mfma_f32_16x16x32_bf16 v[44:47], v[136:139], v[190:193], v[44:47]
	v_mfma_f32_16x16x32_bf16 v[40:43], v[170:173], v[190:193], v[40:43]
	v_mfma_f32_16x16x32_bf16 v[36:39], v[132:135], v[196:199], v[36:39]
	v_mfma_f32_16x16x32_bf16 v[32:35], v[158:161], v[196:199], v[32:35]
	v_mfma_f32_16x16x32_bf16 v[204:207], v[136:139], v[84:87], v[52:55]
	v_mfma_f32_16x16x32_bf16 v[216:219], v[170:173], v[84:87], v[48:51]
	v_mfma_f32_16x16x32_bf16 v[132:135], v[136:139], v[200:203], v[36:39]
	v_mfma_f32_16x16x32_bf16 v[136:139], v[170:173], v[200:203], v[32:35]
	v_mfma_f32_16x16x32_bf16 v[28:31], v[96:99], v[72:75], v[28:31]
	v_mfma_f32_16x16x32_bf16 v[24:27], v[104:107], v[72:75], v[24:27]
	v_mfma_f32_16x16x32_bf16 v[12:15], v[96:99], v[186:189], v[12:15]
	v_mfma_f32_16x16x32_bf16 v[4:7], v[96:99], v[196:199], v[4:7]
	v_mfma_f32_16x16x32_bf16 v[28:31], v[100:103], v[76:79], v[28:31]
	v_mfma_f32_16x16x32_bf16 v[24:27], v[108:111], v[76:79], v[24:27]
	v_mfma_f32_16x16x32_bf16 v[20:23], v[96:99], v[80:83], v[20:23]
	v_mfma_f32_16x16x32_bf16 v[16:19], v[104:107], v[80:83], v[16:19]
	v_mfma_f32_16x16x32_bf16 v[12:15], v[100:103], v[190:193], v[12:15]
	v_mfma_f32_16x16x32_bf16 v[8:11], v[104:107], v[186:189], v[8:11]
	v_mfma_f32_16x16x32_bf16 v[4:7], v[100:103], v[200:203], v[4:7]
	v_mfma_f32_16x16x32_bf16 v[0:3], v[104:107], v[196:199], v[0:3]
	v_mfma_f32_16x16x32_bf16 v[158:161], v[100:103], v[84:87], v[20:23]
	v_mfma_f32_16x16x32_bf16 v[170:173], v[108:111], v[84:87], v[16:19]
	v_mfma_f32_16x16x32_bf16 v[186:189], v[108:111], v[190:193], v[8:11]
	v_mfma_f32_16x16x32_bf16 v[190:193], v[108:111], v[200:203], v[0:3]
	s_barrier
	s_nop 1
	ds_read_b128 v[0:3], v156
	ds_read_b128 v[8:11], v156 offset:1024
	ds_read_b128 v[196:199], v156 offset:2048
	ds_read_b128 v[200:203], v156 offset:3072
	ds_read_b128 v[16:19], v146 offset:32768
	ds_read_b128 v[20:23], v146 offset:33792
	ds_read_b128 v[32:35], v143 offset:32768
	ds_read_b128 v[36:39], v143 offset:33792
	ds_read_b128 v[48:51], v142 offset:32768
	ds_read_b128 v[52:55], v142 offset:33792
	ds_read_b128 v[220:223], v141 offset:32768
	ds_read_b128 v[224:227], v141 offset:33792
	s_waitcnt vmcnt(2)
	s_barrier
; #define WAIT_V(n) asm volatile("s_waitcnt vmcnt(" #n ")" ::: "memory")
; #define WAIT_L(n) asm volatile("s_waitcnt lgkmcnt(" #n ")" ::: "memory")
; #define BAR __builtin_amdgcn_s_barrier()
;     ...
;     { LDB(B0, 1, 0); LDA(At, 1, 0); WAIT_V(2); BAR; WAIT_L(0); MMA(0, 0, At, B0); BAR;
;       LDB(B1, 1, 1); WAIT_V(0); BAR; WAIT_L(0); MMA(0, 1, At, B1); BAR;
;       LDA(At, 1, 1); BAR; WAIT_L(0); MMA(1, 0, At, B0); MMA(1, 1, At, B1); BAR; }
;     if (wr == 0) BAR;
;     ...
;           if (MODE == 3) {
;             const long row = brow + rloc;
;             const float4 s0 = *(const float4*)(ssq + row * 8), s1 = *(const float4*)(ssq + row * 8 + 4);
;             rscale = rsqrtf((s0.x + s0.y + s0.z + s0.w + s1.x + s1.y + s1.z + s1.w) * (1.f / DM) + EPS);
	s_waitcnt lgkmcnt(0)
	s_waitcnt lgkmcnt(0)
	v_mfma_f32_16x16x32_bf16 v[72:75], v[0:3], v[16:19], v[124:127]
	v_mfma_f32_16x16x32_bf16 v[104:107], v[8:11], v[20:23], v[72:75]
	v_mfma_f32_16x16x32_bf16 v[72:75], v[196:199], v[16:19], v[120:123]
	v_mfma_f32_16x16x32_bf16 v[108:111], v[200:203], v[20:23], v[72:75]
	v_mfma_f32_16x16x32_bf16 v[72:75], v[0:3], v[32:35], v[116:119]
	v_mfma_f32_16x16x32_bf16 v[96:99], v[8:11], v[36:39], v[72:75]
	v_mfma_f32_16x16x32_bf16 v[72:75], v[196:199], v[32:35], v[112:115]
	v_mfma_f32_16x16x32_bf16 v[100:103], v[200:203], v[36:39], v[72:75]
	v_mfma_f32_16x16x32_bf16 v[72:75], v[0:3], v[48:51], v[128:131]
	v_mfma_f32_16x16x32_bf16 v[84:87], v[8:11], v[52:55], v[72:75]
	v_mfma_f32_16x16x32_bf16 v[72:75], v[196:199], v[48:51], v[166:169]
	v_mfma_f32_16x16x32_bf16 v[80:83], v[200:203], v[52:55], v[72:75]
	v_mfma_f32_16x16x32_bf16 v[72:75], v[0:3], v[220:223], v[208:211]
	v_mfma_f32_16x16x32_bf16 v[76:79], v[8:11], v[224:227], v[72:75]
	v_mfma_f32_16x16x32_bf16 v[72:75], v[196:199], v[220:223], v[212:215]
	v_mfma_f32_16x16x32_bf16 v[72:75], v[200:203], v[224:227], v[72:75]
	s_barrier
	ds_read_b128 v[128:131], v154
	ds_read_b128 v[166:169], v154 offset:1024
	ds_read_b128 v[208:211], v154 offset:2048
	ds_read_b128 v[154:157], v154 offset:3072
	s_waitcnt vmcnt(0)
	v_readlane_b32 s64, v248, 0
	v_readlane_b32 s65, v248, 1
	v_and_b32_e32 v249, 0xff, v194
	v_add_u32_e32 v249, s24, v249
	v_lshlrev_b32_e32 v249, 5, v249
	v_lshrrev_b32_e32 v250, 8, v194
	v_lshl_add_u32 v249, v250, 4, v249
	s_nop 1
	global_load_dwordx4 v[250:253], v249, s[64:65]
	s_barrier
	s_waitcnt lgkmcnt(0)
	s_waitcnt lgkmcnt(0)
	v_mfma_f32_16x16x32_bf16 v[92:95], v[128:131], v[16:19], v[92:95]
	v_mfma_f32_16x16x32_bf16 v[16:19], v[208:211], v[16:19], v[88:91]
	v_mfma_f32_16x16x32_bf16 v[124:127], v[154:157], v[20:23], v[16:19]
	v_mfma_f32_16x16x32_bf16 v[16:19], v[128:131], v[32:35], v[162:165]
	v_mfma_f32_16x16x32_bf16 v[112:115], v[166:169], v[36:39], v[16:19]
	v_mfma_f32_16x16x32_bf16 v[16:19], v[208:211], v[32:35], v[174:177]
	v_mfma_f32_16x16x32_bf16 v[116:119], v[154:157], v[36:39], v[16:19]
	v_mfma_f32_16x16x32_bf16 v[16:19], v[128:131], v[48:51], v[178:181]
	v_mfma_f32_16x16x32_bf16 v[120:123], v[166:169], v[20:23], v[92:95]
	v_mfma_f32_16x16x32_bf16 v[92:95], v[166:169], v[52:55], v[16:19]
	v_mfma_f32_16x16x32_bf16 v[16:19], v[208:211], v[48:51], v[182:185]
	v_mfma_f32_16x16x32_bf16 v[88:91], v[154:157], v[52:55], v[16:19]
	v_mfma_f32_16x16x32_bf16 v[16:19], v[128:131], v[220:223], v[68:71]
	v_mfma_f32_16x16x32_bf16 v[68:71], v[166:169], v[224:227], v[16:19]
	v_mfma_f32_16x16x32_bf16 v[16:19], v[208:211], v[220:223], v[64:67]
	v_mfma_f32_16x16x32_bf16 v[64:67], v[154:157], v[224:227], v[16:19]
	s_barrier
	ds_read_b128 v[162:165], v146 offset:49152
	ds_read_b128 v[174:177], v146 offset:50176
	ds_read_b128 v[178:181], v143 offset:49152
	ds_read_b128 v[182:185], v143 offset:50176
	ds_read_b128 v[212:215], v142 offset:49152
	ds_read_b128 v[220:223], v142 offset:50176
	ds_read_b128 v[224:227], v141 offset:49152
	ds_read_b128 v[140:143], v141 offset:50176
	s_barrier
	s_waitcnt lgkmcnt(0)
	s_waitcnt lgkmcnt(0)
	v_mfma_f32_16x16x32_bf16 v[16:19], v[0:3], v[162:165], v[60:63]
	v_mfma_f32_16x16x32_bf16 v[52:55], v[8:11], v[174:177], v[16:19]
	v_mfma_f32_16x16x32_bf16 v[16:19], v[196:199], v[162:165], v[56:59]
	v_mfma_f32_16x16x32_bf16 v[48:51], v[200:203], v[174:177], v[16:19]
	v_mfma_f32_16x16x32_bf16 v[16:19], v[0:3], v[178:181], v[204:207]
	v_mfma_f32_16x16x32_bf16 v[36:39], v[8:11], v[182:185], v[16:19]
	v_mfma_f32_16x16x32_bf16 v[16:19], v[196:199], v[178:181], v[216:219]
	v_mfma_f32_16x16x32_bf16 v[32:35], v[200:203], v[182:185], v[16:19]
	v_mfma_f32_16x16x32_bf16 v[16:19], v[0:3], v[212:215], v[44:47]
	v_mfma_f32_16x16x32_bf16 v[0:3], v[0:3], v[224:227], v[132:135]
	v_mfma_f32_16x16x32_bf16 v[20:23], v[8:11], v[220:223], v[16:19]
	v_mfma_f32_16x16x32_bf16 v[16:19], v[196:199], v[212:215], v[40:43]
	v_mfma_f32_16x16x32_bf16 v[8:11], v[8:11], v[140:143], v[0:3]
	v_mfma_f32_16x16x32_bf16 v[0:3], v[196:199], v[224:227], v[136:139]
	v_mfma_f32_16x16x32_bf16 v[16:19], v[200:203], v[220:223], v[16:19]
	v_mfma_f32_16x16x32_bf16 v[0:3], v[200:203], v[140:143], v[0:3]
	v_mfma_f32_16x16x32_bf16 v[24:27], v[208:211], v[162:165], v[24:27]
	v_mfma_f32_16x16x32_bf16 v[28:31], v[128:131], v[162:165], v[28:31]
	v_mfma_f32_16x16x32_bf16 v[56:59], v[154:157], v[174:177], v[24:27]
	v_mfma_f32_16x16x32_bf16 v[24:27], v[128:131], v[178:181], v[158:161]
	v_mfma_f32_16x16x32_bf16 v[12:15], v[128:131], v[212:215], v[12:15]
	v_mfma_f32_16x16x32_bf16 v[60:63], v[166:169], v[174:177], v[28:31]
	v_mfma_f32_16x16x32_bf16 v[44:47], v[166:169], v[182:185], v[24:27]
	v_mfma_f32_16x16x32_bf16 v[24:27], v[208:211], v[178:181], v[170:173]
	v_mfma_f32_16x16x32_bf16 v[28:31], v[166:169], v[220:223], v[12:15]
	v_mfma_f32_16x16x32_bf16 v[12:15], v[208:211], v[212:215], v[186:189]
	v_mfma_f32_16x16x32_bf16 v[4:7], v[128:131], v[224:227], v[4:7]
	v_mfma_f32_16x16x32_bf16 v[40:43], v[154:157], v[182:185], v[24:27]
	v_mfma_f32_16x16x32_bf16 v[24:27], v[154:157], v[220:223], v[12:15]
	v_mfma_f32_16x16x32_bf16 v[12:15], v[166:169], v[140:143], v[4:7]
	v_mfma_f32_16x16x32_bf16 v[4:7], v[208:211], v[224:227], v[190:193]
	v_mfma_f32_16x16x32_bf16 v[4:7], v[154:157], v[140:143], v[4:7]
	s_setprio 0
	v_cmp_gt_u32_e32 vcc, s34, v144
	s_barrier
	s_and_saveexec_b64 s[4:5], vcc
	s_cbranch_execz .LBB0_542
	s_barrier
	s_branch .LBB0_542

; #define WAIT_V(n) asm volatile("s_waitcnt vmcnt(" #n ")" ::: "memory")
; #define BAR __builtin_amdgcn_s_barrier()
;     ...
;   for (int vw = blockIdx.x; vw < nwg; vw += gridDim.x) {
;     int tid_ = threadIdx.x;
;     asm volatile("" : "+v"(tid_));
;     const int wid = tid_ >> 6, lane = tid_ & 63, wr = wid >> 2, wc = wid & 3, fr = lane & 15, fq = lane >> 4;
;     int brow, bcol;
;     TILE_COORDS(vw, brow, bcol);
;     f32x4 acc[2][2][4][2] = {};
;     bf16x8 At[4][2], B0[2][2], B1[2][2];
;     STAGE(SB(0, 0), Bt, bcol, 0); STAGE(SA(0, 0), A, brow, 0);
;     STAGE(SB(0, 1), Bt, bcol + HALF, 0); STAGE(SA(0, 1), A, brow + HALF, 0);
;     if (wr == 1) BAR;
;     WAIT_V(4); BAR;
;     STAGE(SB(1, 0), Bt, bcol, 1); STAGE(SA(1, 0), A, brow, 1); STAGE(SB(1, 1), Bt, bcol + HALF, 1);
;     WAIT_V(6); BAR;
.LBB0_653:
	s_add_i32 s14, s17, s14
	v_ashrrev_i32_e32 v0, 31, v128
	s_ashr_i32 s15, s14, 31
	v_lshrrev_b32_e32 v0, 26, v0
	s_lshr_b32 s15, s15, 27
	v_add_u32_e32 v0, v128, v0
	s_add_i32 s16, s14, s15
	v_ashrrev_i32_e32 v1, 6, v0
	v_bfe_i32 v0, v128, 27, 1
	s_and_b32 s15, s16, 0xffe0
	v_lshlrev_b32_e32 v20, 4, v128
	v_lshrrev_b32_e32 v0, 22, v0
	s_sub_i32 s14, s14, s15
	v_add_u32_e32 v0, v20, v0
	s_bfe_i32 s15, s14, 0x80000
	v_and_b32_e32 v0, 0xfffffc00, v0
	s_bfe_u32 s15, s15, 0x2000d
	v_sub_u32_e32 v0, v20, v0
	s_add_i32 s15, s14, s15
	v_lshrrev_b32_e32 v2, 4, v0
	s_bfe_i32 s17, s15, 0x80000
	s_and_b32 s15, s15, 0xfc
	v_bitop3_b32 v2, v2, v0, 32 bitop3:0x6c
	s_sub_i32 s14, s14, s15
	v_ashrrev_i32_e32 v3, 31, v2
	s_sext_i32_i16 s17, s17
	s_sext_i32_i8 s14, s14
	v_lshrrev_b32_e32 v3, 26, v3
	s_lshl_b32 s22, s14, 8
	s_lshl_b32 s14, s17, 6
	v_add_u32_e32 v3, v2, v3
	s_and_b32 s18, s14, 0xffffff00
	v_readlane_b32 s40, v248, 10
	v_lshlrev_b32_e32 v0, 3, v1
	v_ashrrev_i32_e32 v4, 6, v3
	v_and_b32_e32 v3, 0xc0, v3
	s_ashr_i32 s19, s18, 31
	v_readlane_b32 s41, v248, 11
	v_readlane_b32 s44, v248, 14
	v_readlane_b32 s45, v248, 15
	v_and_b32_e32 v0, -16, v0
	v_lshlrev_b32_e32 v1, 5, v1
	v_sub_u32_e32 v2, v2, v3
	s_lshl_b64 s[20:21], s[18:19], 12
	s_mov_b64 s[40:41], s[44:45]
	v_add_u32_e32 v0, v4, v0
	v_and_b32_e32 v1, 32, v1
	v_ashrrev_i16_sdwa v2, v142, sext(v2) dst_sel:DWORD dst_unused:UNUSED_PAD src0_sel:DWORD src1_sel:BYTE_0
	s_add_u32 s14, s40, s20
	v_add_u32_sdwa v2, v1, sext(v2) dst_sel:DWORD dst_unused:UNUSED_PAD src0_sel:DWORD src1_sel:WORD_0
	v_ashrrev_i32_e32 v1, 31, v0
	s_addc_u32 s15, s41, s21
	v_lshlrev_b64 v[0:1], 12, v[0:1]
	v_ashrrev_i32_e32 v3, 31, v2
	v_lshl_add_u64 v[4:5], s[14:15], 0, v[0:1]
	v_lshlrev_b64 v[2:3], 1, v[2:3]
	v_add_u32_e32 v21, 0x2000, v20
	v_lshl_add_u64 v[8:9], v[4:5], 0, v[2:3]
	v_ashrrev_i32_e32 v4, 31, v21
	v_lshrrev_b32_e32 v4, 22, v4
	v_add_u32_e32 v4, v21, v4
	v_ashrrev_i32_e32 v5, 10, v4
	v_mul_i32_i24_e32 v4, 0x400, v5
	v_sub_u32_e32 v4, v21, v4
	v_lshrrev_b32_e32 v6, 4, v4
	v_bitop3_b32 v6, v6, v4, 32 bitop3:0x6c
	v_ashrrev_i32_e32 v7, 31, v6
	v_lshrrev_b32_e32 v7, 26, v7
	v_add_u32_e32 v7, v6, v7
	v_lshlrev_b32_e32 v4, 3, v5
	v_ashrrev_i32_e32 v10, 6, v7
	v_and_b32_e32 v7, 0xc0, v7
	v_and_b32_e32 v4, -16, v4
	v_lshlrev_b32_e32 v5, 5, v5
	v_sub_u32_e32 v6, v6, v7
	v_add_u32_e32 v4, v10, v4
	v_and_b32_e32 v5, 32, v5
	v_ashrrev_i16_sdwa v6, v142, sext(v6) dst_sel:DWORD dst_unused:UNUSED_PAD src0_sel:DWORD src1_sel:BYTE_0
	v_add_u32_e32 v147, s26, v20
	v_add_u32_sdwa v6, v5, sext(v6) dst_sel:DWORD dst_unused:UNUSED_PAD src0_sel:DWORD src1_sel:WORD_0
	v_ashrrev_i32_e32 v5, 31, v4
	v_readfirstlane_b32 s17, v147
	v_lshlrev_b64 v[4:5], 12, v[4:5]
	v_add_u32_e32 v12, s26, v21
	s_mov_b32 m0, s17
	v_lshl_add_u64 v[10:11], s[14:15], 0, v[4:5]
	v_readfirstlane_b32 s14, v12
	global_load_lds_dwordx4 v[8:9], off
	s_mov_b32 m0, s14
	s_lshl_b32 s14, s16, 5
	s_and_b32 s14, s14, 0xfffffc00
	s_add_i32 s16, s22, s14
	s_ashr_i32 s17, s16, 31
	s_lshl_b64 s[22:23], s[16:17], 12
	v_ashrrev_i32_e32 v7, 31, v6
	s_add_u32 s14, s92, s22
	v_lshlrev_b64 v[6:7], 1, v[6:7]
	s_addc_u32 s15, s93, s23
	v_add_u32_e32 v152, 0, v20
	v_lshl_add_u64 v[10:11], v[10:11], 0, v[6:7]
	v_lshl_add_u64 v[12:13], s[14:15], 0, v[0:1]
	v_readfirstlane_b32 s17, v152
	v_add_u32_e32 v153, 0x2000, v152
	global_load_lds_dwordx4 v[10:11], off
	v_lshl_add_u64 v[12:13], v[12:13], 0, v[2:3]
	s_mov_b32 m0, s17
	v_lshl_add_u64 v[14:15], s[14:15], 0, v[4:5]
	v_readfirstlane_b32 s14, v153
	global_load_lds_dwordx4 v[12:13], off
	s_mov_b32 m0, s14
	s_or_b32 s14, s18, 0x80
	s_ashr_i32 s15, s14, 31
	s_lshl_b64 s[14:15], s[14:15], 12
	s_add_u32 s14, s40, s14
	s_addc_u32 s15, s41, s15
	v_add_u32_e32 v155, s27, v20
	v_lshl_add_u64 v[14:15], v[14:15], 0, v[6:7]
	v_lshl_add_u64 v[16:17], s[14:15], 0, v[0:1]
	v_readfirstlane_b32 s17, v155
	v_add_u32_e32 v21, s27, v21
	global_load_lds_dwordx4 v[14:15], off
	v_lshl_add_u64 v[16:17], v[16:17], 0, v[2:3]
	s_mov_b32 m0, s17
	v_lshl_add_u64 v[18:19], s[14:15], 0, v[4:5]
	v_readfirstlane_b32 s14, v21
	global_load_lds_dwordx4 v[16:17], off
	s_mov_b32 m0, s14
	s_or_b32 s14, s16, 0x80
	s_ashr_i32 s15, s14, 31
	s_lshl_b64 s[24:25], s[14:15], 12
	s_add_u32 s24, s92, s24
	s_addc_u32 s25, s93, s25
	v_add_u32_e32 v157, 0x4000, v152
	v_lshl_add_u64 v[18:19], v[18:19], 0, v[6:7]
	v_lshl_add_u64 v[22:23], s[24:25], 0, v[0:1]
	v_readfirstlane_b32 s15, v157
	v_add_u32_e32 v158, 0x6000, v152
	global_load_lds_dwordx4 v[18:19], off
	v_lshl_add_u64 v[130:131], v[22:23], 0, v[2:3]
	s_mov_b32 m0, s15
	v_lshl_add_u64 v[22:23], s[24:25], 0, v[4:5]
	v_readfirstlane_b32 s15, v158
	global_load_lds_dwordx4 v[130:131], off
	v_lshl_add_u64 v[132:133], v[22:23], 0, v[6:7]
	s_mov_b32 m0, s15
	v_ashrrev_i32_e32 v21, 8, v128
	global_load_lds_dwordx4 v[132:133], off
	v_mov_b64_e32 v[24:25], 0
	v_mov_b64_e32 v[26:27], 0
	v_mov_b64_e32 v[28:29], 0
	v_mov_b64_e32 v[30:31], 0
	v_mov_b64_e32 v[32:33], 0
	v_mov_b64_e32 v[34:35], 0
	v_mov_b64_e32 v[36:37], 0
	v_mov_b64_e32 v[38:39], 0
	v_mov_b64_e32 v[40:41], 0
	v_mov_b64_e32 v[42:43], 0
	v_mov_b64_e32 v[44:45], 0
	v_mov_b64_e32 v[46:47], 0
	v_mov_b64_e32 v[48:49], 0
	v_mov_b64_e32 v[50:51], 0
	v_mov_b64_e32 v[52:53], 0
	v_mov_b64_e32 v[54:55], 0
	v_mov_b64_e32 v[56:57], 0
	v_mov_b64_e32 v[58:59], 0
	v_mov_b64_e32 v[60:61], 0
	v_mov_b64_e32 v[62:63], 0
	v_mov_b64_e32 v[64:65], 0
	v_mov_b64_e32 v[66:67], 0
	v_mov_b64_e32 v[68:69], 0
	v_mov_b64_e32 v[70:71], 0
	v_mov_b64_e32 v[72:73], 0
	v_mov_b64_e32 v[74:75], 0
	v_mov_b64_e32 v[76:77], 0
	v_mov_b64_e32 v[78:79], 0
	v_mov_b64_e32 v[80:81], 0
	v_mov_b64_e32 v[82:83], 0
	v_mov_b64_e32 v[84:85], 0
	v_mov_b64_e32 v[86:87], 0
	v_mov_b64_e32 v[88:89], 0
	v_mov_b64_e32 v[90:91], 0
	v_mov_b64_e32 v[92:93], 0
	v_mov_b64_e32 v[94:95], 0
	v_mov_b64_e32 v[96:97], 0
	v_mov_b64_e32 v[98:99], 0
	v_mov_b64_e32 v[100:101], 0
	v_mov_b64_e32 v[102:103], 0
	v_mov_b64_e32 v[104:105], 0
	v_mov_b64_e32 v[106:107], 0
	v_mov_b64_e32 v[108:109], 0
	v_mov_b64_e32 v[110:111], 0
	v_mov_b64_e32 v[112:113], 0
	v_mov_b64_e32 v[114:115], 0
	v_mov_b64_e32 v[116:117], 0
	v_mov_b64_e32 v[118:119], 0
	v_mov_b64_e32 v[120:121], 0
	v_mov_b64_e32 v[122:123], 0
	v_mov_b64_e32 v[124:125], 0
	v_mov_b64_e32 v[126:127], 0
	v_cmp_eq_u32_e32 vcc, 1, v21
	v_readlane_b32 s42, v248, 12
	v_readlane_b32 s43, v248, 13
	v_readlane_b32 s46, v248, 16
	v_readlane_b32 s47, v248, 17
	v_readlane_b32 s48, v248, 18
	v_readlane_b32 s49, v248, 19
	v_readlane_b32 s50, v248, 20
	v_readlane_b32 s51, v248, 21
	v_readlane_b32 s52, v248, 22
	v_readlane_b32 s53, v248, 23
	v_readlane_b32 s54, v248, 24
	v_readlane_b32 s55, v248, 25
	s_and_saveexec_b64 s[24:25], vcc
	s_cbranch_execz .LBB0_655
	s_setprio 1
	s_barrier

; #define WAIT_V(n) asm volatile("s_waitcnt vmcnt(" #n ")" ::: "memory")
; #define WAIT_L(n) asm volatile("s_waitcnt lgkmcnt(" #n ")" ::: "memory")
; #define BAR __builtin_amdgcn_s_barrier()
; #define SCHED __builtin_amdgcn_sched_barrier(0)
;     ...
;     for (int t = 0; t < nt - 2; t += 2) {
;       LDB(B0, 0, 0); SCHED; LDA(At, 0, 0); STAGE(SA(1, 1), A, brow + HALF, t + 1);
;       WAIT_L(8); BAR; WAIT_L(0); MMA(0, 0, At, B0); BAR; SCHED;
;       LDB(B1, 0, 1); STAGE(SB(0, 0), Bt, bcol, t + 2);
;       BAR; WAIT_L(0); MMA(0, 1, At, B1); BAR;
;       LDA(At, 0, 1); STAGE(SA(0, 0), A, brow, t + 2);
;       BAR; WAIT_L(0); MMA(1, 0, At, B0); BAR; SCHED;
;       STAGE(SB(0, 1), Bt, bcol + HALF, t + 2);
;       WAIT_V(6); BAR; MMA(1, 1, At, B1); BAR;
.LBB0_656:
	v_add_u32_e32 v167, 0xc000, v152
	v_add_u32_e32 v168, 0xe000, v152
	v_add_u32_e32 v169, 0x2000, v147
	v_add_u32_e32 v169, 0x2000, v155
	ds_read_b128 v[170:173], v166
	ds_read_b128 v[174:177], v166 offset:1024
	ds_read_b128 v[178:181], v166 offset:2048
	ds_read_b128 v[182:185], v166 offset:3072
	ds_read_b128 v[186:189], v151
	ds_read_b128 v[190:193], v151 offset:1024
	ds_read_b128 v[196:199], v150
	ds_read_b128 v[200:203], v150 offset:1024
	ds_read_b128 v[204:207], v149
	ds_read_b128 v[208:211], v149 offset:1024
	ds_read_b128 v[212:215], v148
	ds_read_b128 v[216:219], v148 offset:1024
	ds_read_b128 v[220:223], v165
	ds_read_b128 v[224:227], v165 offset:1024
	ds_read_b128 v[228:231], v165 offset:2048
	ds_read_b128 v[232:235], v165 offset:3072
	v_add_u32_e32 v254, 0xc000, v152
	v_lshl_add_u64 v[250:251], v[138:139], 0, s[20:21]
	v_readfirstlane_b32 s17, v254
	v_lshl_add_u64 v[250:251], v[250:251], 0, s[2:3]
	s_mov_b32 m0, s17
	s_nop 0
	global_load_lds_dwordx4 v[250:251], off
	v_add_u32_e32 v254, 0xe000, v152
	v_lshl_add_u64 v[252:253], v[140:141], 0, s[20:21]
	v_readfirstlane_b32 s17, v254
	v_lshl_add_u64 v[252:253], v[252:253], 0, s[2:3]
	s_mov_b32 m0, s17
	s_nop 0
	global_load_lds_dwordx4 v[252:253], off
	s_waitcnt lgkmcnt(0)
	s_barrier
	v_mfma_f32_16x16x32_bf16 v[124:127], v[170:173], v[186:189], v[124:127]
	v_mfma_f32_16x16x32_bf16 v[120:123], v[178:181], v[186:189], v[120:123]
	v_mfma_f32_16x16x32_bf16 v[116:119], v[170:173], v[196:199], v[116:119]
	v_mfma_f32_16x16x32_bf16 v[112:115], v[178:181], v[196:199], v[112:115]
	v_mfma_f32_16x16x32_bf16 v[108:111], v[170:173], v[204:207], v[108:111]
	v_mfma_f32_16x16x32_bf16 v[104:107], v[178:181], v[204:207], v[104:107]
	v_mfma_f32_16x16x32_bf16 v[100:103], v[170:173], v[212:215], v[100:103]
	v_mfma_f32_16x16x32_bf16 v[96:99], v[178:181], v[212:215], v[96:99]
	v_mfma_f32_16x16x32_bf16 v[124:127], v[174:177], v[190:193], v[124:127]
	v_mfma_f32_16x16x32_bf16 v[120:123], v[182:185], v[190:193], v[120:123]
	v_mfma_f32_16x16x32_bf16 v[116:119], v[174:177], v[200:203], v[116:119]
	v_mfma_f32_16x16x32_bf16 v[112:115], v[182:185], v[200:203], v[112:115]
	v_mfma_f32_16x16x32_bf16 v[108:111], v[174:177], v[208:211], v[108:111]
	v_mfma_f32_16x16x32_bf16 v[104:107], v[182:185], v[208:211], v[104:107]
	v_mfma_f32_16x16x32_bf16 v[100:103], v[174:177], v[216:219], v[100:103]
	v_mfma_f32_16x16x32_bf16 v[96:99], v[182:185], v[216:219], v[96:99]
	v_mfma_f32_16x16x32_bf16 v[92:95], v[220:223], v[186:189], v[92:95]
	v_mfma_f32_16x16x32_bf16 v[88:91], v[228:231], v[186:189], v[88:91]
	v_mfma_f32_16x16x32_bf16 v[84:87], v[220:223], v[196:199], v[84:87]
	v_mfma_f32_16x16x32_bf16 v[80:83], v[228:231], v[196:199], v[80:83]
	v_mfma_f32_16x16x32_bf16 v[76:79], v[220:223], v[204:207], v[76:79]
	v_mfma_f32_16x16x32_bf16 v[72:75], v[228:231], v[204:207], v[72:75]
	v_mfma_f32_16x16x32_bf16 v[68:71], v[220:223], v[212:215], v[68:71]
	v_mfma_f32_16x16x32_bf16 v[64:67], v[228:231], v[212:215], v[64:67]
	v_mfma_f32_16x16x32_bf16 v[92:95], v[224:227], v[190:193], v[92:95]
	v_mfma_f32_16x16x32_bf16 v[88:91], v[232:235], v[190:193], v[88:91]
	v_mfma_f32_16x16x32_bf16 v[84:87], v[224:227], v[200:203], v[84:87]
	v_mfma_f32_16x16x32_bf16 v[80:83], v[232:235], v[200:203], v[80:83]
	v_mfma_f32_16x16x32_bf16 v[76:79], v[224:227], v[208:211], v[76:79]
	v_mfma_f32_16x16x32_bf16 v[72:75], v[232:235], v[208:211], v[72:75]
	v_mfma_f32_16x16x32_bf16 v[68:71], v[224:227], v[216:219], v[68:71]
	v_mfma_f32_16x16x32_bf16 v[64:67], v[232:235], v[216:219], v[64:67]
	s_barrier
	ds_read_b128 v[186:189], v151 offset:16384
	ds_read_b128 v[190:193], v151 offset:17408
	ds_read_b128 v[196:199], v150 offset:16384
	ds_read_b128 v[200:203], v150 offset:17408
	ds_read_b128 v[204:207], v149 offset:16384
	ds_read_b128 v[208:211], v149 offset:17408
	ds_read_b128 v[212:215], v148 offset:16384
	ds_read_b128 v[216:219], v148 offset:17408
	v_lshl_add_u64 v[250:251], v[134:135], 0, s[20:21]
	v_readfirstlane_b32 s17, v147
	v_lshl_add_u64 v[250:251], v[250:251], 0, s[4:5]
	s_mov_b32 m0, s17
	s_nop 0
	global_load_lds_dwordx4 v[250:251], off
	v_add_u32_e32 v254, 0x2000, v147
	v_lshl_add_u64 v[252:253], v[136:137], 0, s[20:21]
	v_readfirstlane_b32 s17, v254
	v_lshl_add_u64 v[252:253], v[252:253], 0, s[4:5]
	s_mov_b32 m0, s17
	s_nop 0
	global_load_lds_dwordx4 v[252:253], off
	v_lshl_add_u64 v[250:251], v[138:139], 0, s[20:21]
	v_readfirstlane_b32 s17, v152
	v_lshl_add_u64 v[250:251], v[250:251], 0, s[4:5]
	s_mov_b32 m0, s17
	s_nop 0
	global_load_lds_dwordx4 v[250:251], off
	v_lshl_add_u64 v[252:253], v[140:141], 0, s[20:21]
	v_readfirstlane_b32 s17, v153
	v_lshl_add_u64 v[252:253], v[252:253], 0, s[4:5]
	s_mov_b32 m0, s17
	s_nop 0
	global_load_lds_dwordx4 v[252:253], off
	v_lshl_add_u64 v[250:251], v[134:135], 0, s[20:21]
	v_readfirstlane_b32 s17, v155
	v_lshl_add_u64 v[250:251], v[250:251], 0, s[6:7]
	s_mov_b32 m0, s17
	s_nop 0
	global_load_lds_dwordx4 v[250:251], off
	v_add_u32_e32 v254, 0x2000, v155
	v_lshl_add_u64 v[252:253], v[136:137], 0, s[20:21]
	v_readfirstlane_b32 s17, v254
	v_lshl_add_u64 v[252:253], v[252:253], 0, s[6:7]
	s_mov_b32 m0, s17
	s_nop 0
	global_load_lds_dwordx4 v[252:253], off
	s_waitcnt vmcnt(6)
	s_waitcnt lgkmcnt(0)
	s_barrier
; #define WAIT_V(n) asm volatile("s_waitcnt vmcnt(" #n ")" ::: "memory")
; #define WAIT_L(n) asm volatile("s_waitcnt lgkmcnt(" #n ")" ::: "memory")
; #define BAR __builtin_amdgcn_s_barrier()
; #define SCHED __builtin_amdgcn_sched_barrier(0)
;     ...
;       WAIT_V(6); BAR; MMA(1, 1, At, B1); BAR;
;       LDB(B0, 1, 0); SCHED; LDA(At, 1, 0); STAGE(SA(0, 1), A, brow + HALF, t + 2);
;       WAIT_L(8); BAR; WAIT_L(0); MMA(0, 0, At, B0); BAR; SCHED;
;       LDB(B1, 1, 1); STAGE(SB(1, 0), Bt, bcol, t + 3);
;       BAR; WAIT_L(0); MMA(0, 1, At, B1); BAR;
;       LDA(At, 1, 1); STAGE(SA(1, 0), A, brow, t + 3);
;       BAR; WAIT_L(0); MMA(1, 0, At, B0); BAR; SCHED;
	v_mfma_f32_16x16x32_bf16 v[60:63], v[170:173], v[186:189], v[60:63]
	v_mfma_f32_16x16x32_bf16 v[56:59], v[178:181], v[186:189], v[56:59]
	v_mfma_f32_16x16x32_bf16 v[52:55], v[170:173], v[196:199], v[52:55]
	v_mfma_f32_16x16x32_bf16 v[48:51], v[178:181], v[196:199], v[48:51]
	v_mfma_f32_16x16x32_bf16 v[44:47], v[170:173], v[204:207], v[44:47]
	v_mfma_f32_16x16x32_bf16 v[40:43], v[178:181], v[204:207], v[40:43]
	v_mfma_f32_16x16x32_bf16 v[36:39], v[170:173], v[212:215], v[36:39]
	v_mfma_f32_16x16x32_bf16 v[32:35], v[178:181], v[212:215], v[32:35]
	v_mfma_f32_16x16x32_bf16 v[60:63], v[174:177], v[190:193], v[60:63]
	v_mfma_f32_16x16x32_bf16 v[56:59], v[182:185], v[190:193], v[56:59]
	v_mfma_f32_16x16x32_bf16 v[52:55], v[174:177], v[200:203], v[52:55]
	v_mfma_f32_16x16x32_bf16 v[48:51], v[182:185], v[200:203], v[48:51]
	v_mfma_f32_16x16x32_bf16 v[44:47], v[174:177], v[208:211], v[44:47]
	v_mfma_f32_16x16x32_bf16 v[40:43], v[182:185], v[208:211], v[40:43]
	v_mfma_f32_16x16x32_bf16 v[36:39], v[174:177], v[216:219], v[36:39]
	v_mfma_f32_16x16x32_bf16 v[32:35], v[182:185], v[216:219], v[32:35]
	v_mfma_f32_16x16x32_bf16 v[28:31], v[220:223], v[186:189], v[28:31]
	v_mfma_f32_16x16x32_bf16 v[24:27], v[228:231], v[186:189], v[24:27]
	v_mfma_f32_16x16x32_bf16 v[20:23], v[220:223], v[196:199], v[20:23]
	v_mfma_f32_16x16x32_bf16 v[16:19], v[228:231], v[196:199], v[16:19]
	v_mfma_f32_16x16x32_bf16 v[12:15], v[220:223], v[204:207], v[12:15]
	v_mfma_f32_16x16x32_bf16 v[8:11], v[228:231], v[204:207], v[8:11]
	v_mfma_f32_16x16x32_bf16 v[4:7], v[220:223], v[212:215], v[4:7]
	v_mfma_f32_16x16x32_bf16 v[0:3], v[228:231], v[212:215], v[0:3]
	v_mfma_f32_16x16x32_bf16 v[28:31], v[224:227], v[190:193], v[28:31]
	v_mfma_f32_16x16x32_bf16 v[24:27], v[232:235], v[190:193], v[24:27]
	v_mfma_f32_16x16x32_bf16 v[20:23], v[224:227], v[200:203], v[20:23]
	v_mfma_f32_16x16x32_bf16 v[16:19], v[232:235], v[200:203], v[16:19]
	v_mfma_f32_16x16x32_bf16 v[12:15], v[224:227], v[208:211], v[12:15]
	v_mfma_f32_16x16x32_bf16 v[8:11], v[232:235], v[208:211], v[8:11]
	v_mfma_f32_16x16x32_bf16 v[4:7], v[224:227], v[216:219], v[4:7]
	v_mfma_f32_16x16x32_bf16 v[0:3], v[232:235], v[216:219], v[0:3]
	s_barrier
	ds_read_b128 v[170:173], v156
	ds_read_b128 v[174:177], v156 offset:1024
	ds_read_b128 v[178:181], v156 offset:2048
	ds_read_b128 v[182:185], v156 offset:3072
	ds_read_b128 v[186:189], v151 offset:32768
	ds_read_b128 v[190:193], v151 offset:33792
	ds_read_b128 v[196:199], v150 offset:32768
	ds_read_b128 v[200:203], v150 offset:33792
	ds_read_b128 v[204:207], v149 offset:32768
	ds_read_b128 v[208:211], v149 offset:33792
	ds_read_b128 v[212:215], v148 offset:32768
	ds_read_b128 v[216:219], v148 offset:33792
	ds_read_b128 v[220:223], v154
	ds_read_b128 v[224:227], v154 offset:1024
	ds_read_b128 v[228:231], v154 offset:2048
	ds_read_b128 v[232:235], v154 offset:3072
	v_lshl_add_u64 v[250:251], v[138:139], 0, s[20:21]
	v_readfirstlane_b32 s17, v157
	v_lshl_add_u64 v[250:251], v[250:251], 0, s[6:7]
	s_mov_b32 m0, s17
	s_nop 0
	global_load_lds_dwordx4 v[250:251], off
	v_lshl_add_u64 v[252:253], v[140:141], 0, s[20:21]
	v_readfirstlane_b32 s17, v158
	v_lshl_add_u64 v[252:253], v[252:253], 0, s[6:7]
	s_mov_b32 m0, s17
	s_nop 0
	global_load_lds_dwordx4 v[252:253], off
	s_waitcnt lgkmcnt(0)
	s_barrier
	v_mfma_f32_16x16x32_bf16 v[124:127], v[170:173], v[186:189], v[124:127]
	v_mfma_f32_16x16x32_bf16 v[120:123], v[178:181], v[186:189], v[120:123]
	v_mfma_f32_16x16x32_bf16 v[116:119], v[170:173], v[196:199], v[116:119]
	v_mfma_f32_16x16x32_bf16 v[112:115], v[178:181], v[196:199], v[112:115]
	v_mfma_f32_16x16x32_bf16 v[108:111], v[170:173], v[204:207], v[108:111]
	v_mfma_f32_16x16x32_bf16 v[104:107], v[178:181], v[204:207], v[104:107]
	v_mfma_f32_16x16x32_bf16 v[100:103], v[170:173], v[212:215], v[100:103]
	v_mfma_f32_16x16x32_bf16 v[96:99], v[178:181], v[212:215], v[96:99]
	v_mfma_f32_16x16x32_bf16 v[124:127], v[174:177], v[190:193], v[124:127]
	v_mfma_f32_16x16x32_bf16 v[120:123], v[182:185], v[190:193], v[120:123]
	v_mfma_f32_16x16x32_bf16 v[116:119], v[174:177], v[200:203], v[116:119]
	v_mfma_f32_16x16x32_bf16 v[112:115], v[182:185], v[200:203], v[112:115]
	v_mfma_f32_16x16x32_bf16 v[108:111], v[174:177], v[208:211], v[108:111]
	v_mfma_f32_16x16x32_bf16 v[104:107], v[182:185], v[208:211], v[104:107]
	v_mfma_f32_16x16x32_bf16 v[100:103], v[174:177], v[216:219], v[100:103]
	v_mfma_f32_16x16x32_bf16 v[96:99], v[182:185], v[216:219], v[96:99]
	v_mfma_f32_16x16x32_bf16 v[92:95], v[220:223], v[186:189], v[92:95]
	v_mfma_f32_16x16x32_bf16 v[88:91], v[228:231], v[186:189], v[88:91]
	v_mfma_f32_16x16x32_bf16 v[84:87], v[220:223], v[196:199], v[84:87]
	v_mfma_f32_16x16x32_bf16 v[80:83], v[228:231], v[196:199], v[80:83]
	v_mfma_f32_16x16x32_bf16 v[76:79], v[220:223], v[204:207], v[76:79]
	v_mfma_f32_16x16x32_bf16 v[72:75], v[228:231], v[204:207], v[72:75]
	v_mfma_f32_16x16x32_bf16 v[68:71], v[220:223], v[212:215], v[68:71]
	v_mfma_f32_16x16x32_bf16 v[64:67], v[228:231], v[212:215], v[64:67]
	v_mfma_f32_16x16x32_bf16 v[92:95], v[224:227], v[190:193], v[92:95]
	v_mfma_f32_16x16x32_bf16 v[88:91], v[232:235], v[190:193], v[88:91]
	v_mfma_f32_16x16x32_bf16 v[84:87], v[224:227], v[200:203], v[84:87]
	v_mfma_f32_16x16x32_bf16 v[80:83], v[232:235], v[200:203], v[80:83]
	v_mfma_f32_16x16x32_bf16 v[76:79], v[224:227], v[208:211], v[76:79]
	v_mfma_f32_16x16x32_bf16 v[72:75], v[232:235], v[208:211], v[72:75]
	v_mfma_f32_16x16x32_bf16 v[68:71], v[224:227], v[216:219], v[68:71]
	v_mfma_f32_16x16x32_bf16 v[64:67], v[232:235], v[216:219], v[64:67]
	s_barrier
; #define WAIT_V(n) asm volatile("s_waitcnt vmcnt(" #n ")" ::: "memory")
; #define BAR __builtin_amdgcn_s_barrier()
;     ...
;       STAGE(SB(1, 1), Bt, bcol + HALF, t + 3);
;       WAIT_V(6); BAR; MMA(1, 1, At, B1); BAR;
;     }
;     { LDB(B0, 0, 0); LDA(At, 0, 0); STAGE(SA(1, 1), A, brow + HALF, nt - 1);
	ds_read_b128 v[186:189], v151 offset:49152
	ds_read_b128 v[190:193], v151 offset:50176
	ds_read_b128 v[196:199], v150 offset:49152
	ds_read_b128 v[200:203], v150 offset:50176
	ds_read_b128 v[204:207], v149 offset:49152
	ds_read_b128 v[208:211], v149 offset:50176
	ds_read_b128 v[212:215], v148 offset:49152
	ds_read_b128 v[216:219], v148 offset:50176
	v_lshl_add_u64 v[250:251], v[134:135], 0, s[20:21]
	v_readfirstlane_b32 s17, v159
	v_lshl_add_u64 v[250:251], v[250:251], 0, s[8:9]
	s_mov_b32 m0, s17
	s_nop 0
	global_load_lds_dwordx4 v[250:251], off
	v_lshl_add_u64 v[252:253], v[136:137], 0, s[20:21]
	v_readfirstlane_b32 s17, v160
	v_lshl_add_u64 v[252:253], v[252:253], 0, s[8:9]
	s_mov_b32 m0, s17
	s_nop 0
	global_load_lds_dwordx4 v[252:253], off
	v_lshl_add_u64 v[250:251], v[138:139], 0, s[20:21]
	v_readfirstlane_b32 s17, v161
	v_lshl_add_u64 v[250:251], v[250:251], 0, s[8:9]
	s_mov_b32 m0, s17
	s_nop 0
	global_load_lds_dwordx4 v[250:251], off
	v_lshl_add_u64 v[252:253], v[140:141], 0, s[20:21]
	v_readfirstlane_b32 s17, v162
	v_lshl_add_u64 v[252:253], v[252:253], 0, s[8:9]
	s_mov_b32 m0, s17
	s_nop 0
	global_load_lds_dwordx4 v[252:253], off
	v_lshl_add_u64 v[250:251], v[134:135], 0, s[20:21]
	v_readfirstlane_b32 s17, v163
	v_lshl_add_u64 v[250:251], v[250:251], 0, s[10:11]
	s_mov_b32 m0, s17
	s_nop 0
	global_load_lds_dwordx4 v[250:251], off
	v_lshl_add_u64 v[252:253], v[136:137], 0, s[20:21]
	v_readfirstlane_b32 s17, v164
	v_lshl_add_u64 v[252:253], v[252:253], 0, s[10:11]
	s_mov_b32 m0, s17
	s_nop 0
	global_load_lds_dwordx4 v[252:253], off
	s_waitcnt vmcnt(6)
	s_waitcnt lgkmcnt(0)
	s_barrier
	v_mfma_f32_16x16x32_bf16 v[60:63], v[170:173], v[186:189], v[60:63]
	v_mfma_f32_16x16x32_bf16 v[56:59], v[178:181], v[186:189], v[56:59]
	v_mfma_f32_16x16x32_bf16 v[52:55], v[170:173], v[196:199], v[52:55]
	v_mfma_f32_16x16x32_bf16 v[48:51], v[178:181], v[196:199], v[48:51]
	v_mfma_f32_16x16x32_bf16 v[44:47], v[170:173], v[204:207], v[44:47]
	v_mfma_f32_16x16x32_bf16 v[40:43], v[178:181], v[204:207], v[40:43]
	v_mfma_f32_16x16x32_bf16 v[36:39], v[170:173], v[212:215], v[36:39]
	v_mfma_f32_16x16x32_bf16 v[32:35], v[178:181], v[212:215], v[32:35]
	v_mfma_f32_16x16x32_bf16 v[60:63], v[174:177], v[190:193], v[60:63]
	v_mfma_f32_16x16x32_bf16 v[56:59], v[182:185], v[190:193], v[56:59]
	v_mfma_f32_16x16x32_bf16 v[52:55], v[174:177], v[200:203], v[52:55]
	v_mfma_f32_16x16x32_bf16 v[48:51], v[182:185], v[200:203], v[48:51]
	v_mfma_f32_16x16x32_bf16 v[44:47], v[174:177], v[208:211], v[44:47]
	v_mfma_f32_16x16x32_bf16 v[40:43], v[182:185], v[208:211], v[40:43]
	v_mfma_f32_16x16x32_bf16 v[36:39], v[174:177], v[216:219], v[36:39]
	v_mfma_f32_16x16x32_bf16 v[32:35], v[182:185], v[216:219], v[32:35]
	v_mfma_f32_16x16x32_bf16 v[28:31], v[220:223], v[186:189], v[28:31]
	v_mfma_f32_16x16x32_bf16 v[24:27], v[228:231], v[186:189], v[24:27]
	v_mfma_f32_16x16x32_bf16 v[20:23], v[220:223], v[196:199], v[20:23]
	v_mfma_f32_16x16x32_bf16 v[16:19], v[228:231], v[196:199], v[16:19]
	v_mfma_f32_16x16x32_bf16 v[12:15], v[220:223], v[204:207], v[12:15]
	v_mfma_f32_16x16x32_bf16 v[8:11], v[228:231], v[204:207], v[8:11]
	v_mfma_f32_16x16x32_bf16 v[4:7], v[220:223], v[212:215], v[4:7]
	v_mfma_f32_16x16x32_bf16 v[0:3], v[228:231], v[212:215], v[0:3]
	v_mfma_f32_16x16x32_bf16 v[28:31], v[224:227], v[190:193], v[28:31]
	v_mfma_f32_16x16x32_bf16 v[24:27], v[232:235], v[190:193], v[24:27]
	v_mfma_f32_16x16x32_bf16 v[20:23], v[224:227], v[200:203], v[20:23]
	v_mfma_f32_16x16x32_bf16 v[16:19], v[232:235], v[200:203], v[16:19]
	v_mfma_f32_16x16x32_bf16 v[12:15], v[224:227], v[208:211], v[12:15]
	v_mfma_f32_16x16x32_bf16 v[8:11], v[232:235], v[208:211], v[8:11]
	v_mfma_f32_16x16x32_bf16 v[4:7], v[224:227], v[216:219], v[4:7]
	v_mfma_f32_16x16x32_bf16 v[0:3], v[232:235], v[216:219], v[0:3]
	s_add_i32 s15, s15, 2
	s_add_u32 s20, s20, 0x100
	s_addc_u32 s21, s21, 0
	s_cmp_gt_u32 s15, 27
	s_barrier
	s_cbranch_scc0 .LBB0_656
	v_readfirstlane_b32 s15, v167
	v_lshl_add_u64 v[130:131], v[130:131], 0, s[12:13]
	s_mov_b32 m0, s15
	v_readfirstlane_b32 s15, v168
	ds_read_b128 v[134:137], v166
	ds_read_b128 v[138:141], v166 offset:1024
	ds_read_b128 v[158:161], v166 offset:2048
	ds_read_b128 v[170:173], v166 offset:3072
	ds_read_b128 v[174:177], v151
	ds_read_b128 v[178:181], v151 offset:1024
	ds_read_b128 v[182:185], v150
	ds_read_b128 v[186:189], v150 offset:1024
	ds_read_b128 v[190:193], v149
	ds_read_b128 v[196:199], v149 offset:1024
	ds_read_b128 v[200:203], v148
	ds_read_b128 v[204:207], v148 offset:1024
	global_load_lds_dwordx4 v[130:131], off
	v_lshl_add_u64 v[130:131], v[132:133], 0, s[12:13]
	s_mov_b32 m0, s15
	s_nop 0
	global_load_lds_dwordx4 v[130:131], off
	s_barrier
	s_waitcnt lgkmcnt(0)
	s_waitcnt lgkmcnt(0)
	v_mfma_f32_16x16x32_bf16 v[124:127], v[134:137], v[174:177], v[124:127]
	v_mfma_f32_16x16x32_bf16 v[120:123], v[158:161], v[174:177], v[120:123]
	v_mfma_f32_16x16x32_bf16 v[116:119], v[134:137], v[182:185], v[116:119]
	v_mfma_f32_16x16x32_bf16 v[112:115], v[158:161], v[182:185], v[112:115]
	v_mfma_f32_16x16x32_bf16 v[108:111], v[134:137], v[190:193], v[108:111]
	v_mfma_f32_16x16x32_bf16 v[104:107], v[158:161], v[190:193], v[104:107]
	v_mfma_f32_16x16x32_bf16 v[100:103], v[134:137], v[200:203], v[100:103]
	v_mfma_f32_16x16x32_bf16 v[96:99], v[158:161], v[200:203], v[96:99]
	v_mfma_f32_16x16x32_bf16 v[124:127], v[138:141], v[178:181], v[124:127]
	v_mfma_f32_16x16x32_bf16 v[120:123], v[170:173], v[178:181], v[120:123]
	v_mfma_f32_16x16x32_bf16 v[116:119], v[138:141], v[186:189], v[116:119]
	v_mfma_f32_16x16x32_bf16 v[112:115], v[170:173], v[186:189], v[112:115]
	v_mfma_f32_16x16x32_bf16 v[108:111], v[138:141], v[196:199], v[108:111]
	v_mfma_f32_16x16x32_bf16 v[104:107], v[170:173], v[196:199], v[104:107]
	v_mfma_f32_16x16x32_bf16 v[100:103], v[138:141], v[204:207], v[100:103]
	v_mfma_f32_16x16x32_bf16 v[96:99], v[170:173], v[204:207], v[96:99]
	s_barrier
; #define WAIT_V(n) asm volatile("s_waitcnt vmcnt(" #n ")" ::: "memory")
; #define WAIT_L(n) asm volatile("s_waitcnt lgkmcnt(" #n ")" ::: "memory")
; #define BAR __builtin_amdgcn_s_barrier()
;     ...
;     { LDB(B0, 0, 0); LDA(At, 0, 0); STAGE(SA(1, 1), A, brow + HALF, nt - 1);
;       BAR; WAIT_L(0); MMA(0, 0, At, B0); BAR;
;       LDB(B1, 0, 1); BAR; WAIT_L(0); MMA(0, 1, At, B1); BAR;
;       LDA(At, 0, 1); WAIT_V(4); BAR; WAIT_L(0); MMA(1, 0, At, B0); MMA(1, 1, At, B1); BAR; }
	ds_read_b128 v[130:133], v165
	ds_read_b128 v[166:169], v165 offset:1024
	ds_read_b128 v[208:211], v165 offset:2048
	ds_read_b128 v[162:165], v165 offset:3072
	s_barrier
	s_waitcnt lgkmcnt(0)
	s_waitcnt lgkmcnt(0)
	v_mfma_f32_16x16x32_bf16 v[92:95], v[130:133], v[174:177], v[92:95]
	v_mfma_f32_16x16x32_bf16 v[88:91], v[208:211], v[174:177], v[88:91]
	v_mfma_f32_16x16x32_bf16 v[84:87], v[130:133], v[182:185], v[84:87]
	v_mfma_f32_16x16x32_bf16 v[80:83], v[208:211], v[182:185], v[80:83]
	v_mfma_f32_16x16x32_bf16 v[76:79], v[130:133], v[190:193], v[76:79]
	v_mfma_f32_16x16x32_bf16 v[72:75], v[208:211], v[190:193], v[72:75]
	v_mfma_f32_16x16x32_bf16 v[68:71], v[130:133], v[200:203], v[68:71]
	v_mfma_f32_16x16x32_bf16 v[64:67], v[208:211], v[200:203], v[64:67]
	v_mfma_f32_16x16x32_bf16 v[212:215], v[166:169], v[178:181], v[92:95]
	v_mfma_f32_16x16x32_bf16 v[174:177], v[162:165], v[178:181], v[88:91]
	v_mfma_f32_16x16x32_bf16 v[178:181], v[166:169], v[186:189], v[84:87]
	v_mfma_f32_16x16x32_bf16 v[182:185], v[162:165], v[186:189], v[80:83]
	v_mfma_f32_16x16x32_bf16 v[186:189], v[166:169], v[196:199], v[76:79]
	v_mfma_f32_16x16x32_bf16 v[190:193], v[162:165], v[196:199], v[72:75]
	v_mfma_f32_16x16x32_bf16 v[196:199], v[166:169], v[204:207], v[68:71]
	v_mfma_f32_16x16x32_bf16 v[200:203], v[162:165], v[204:207], v[64:67]
	s_barrier
	s_nop 0
	ds_read_b128 v[64:67], v151 offset:16384
	ds_read_b128 v[68:71], v151 offset:17408
	ds_read_b128 v[72:75], v150 offset:16384
	ds_read_b128 v[76:79], v150 offset:17408
	ds_read_b128 v[80:83], v149 offset:16384
	ds_read_b128 v[84:87], v149 offset:17408
	ds_read_b128 v[88:91], v148 offset:16384
	ds_read_b128 v[92:95], v148 offset:17408
	s_waitcnt vmcnt(4)
	s_barrier
	s_waitcnt lgkmcnt(0)
	s_waitcnt lgkmcnt(0)
	v_mfma_f32_16x16x32_bf16 v[60:63], v[134:137], v[64:67], v[60:63]
	v_mfma_f32_16x16x32_bf16 v[56:59], v[158:161], v[64:67], v[56:59]
	v_mfma_f32_16x16x32_bf16 v[52:55], v[134:137], v[72:75], v[52:55]
	v_mfma_f32_16x16x32_bf16 v[48:51], v[158:161], v[72:75], v[48:51]
	v_mfma_f32_16x16x32_bf16 v[44:47], v[134:137], v[80:83], v[44:47]
	v_mfma_f32_16x16x32_bf16 v[40:43], v[158:161], v[80:83], v[40:43]
	v_mfma_f32_16x16x32_bf16 v[36:39], v[134:137], v[88:91], v[36:39]
	v_mfma_f32_16x16x32_bf16 v[32:35], v[158:161], v[88:91], v[32:35]
	v_mfma_f32_16x16x32_bf16 v[60:63], v[138:141], v[68:71], v[60:63]
	v_mfma_f32_16x16x32_bf16 v[56:59], v[170:173], v[68:71], v[56:59]
	v_mfma_f32_16x16x32_bf16 v[52:55], v[138:141], v[76:79], v[52:55]
	v_mfma_f32_16x16x32_bf16 v[48:51], v[170:173], v[76:79], v[48:51]
	v_mfma_f32_16x16x32_bf16 v[44:47], v[138:141], v[84:87], v[44:47]
	v_mfma_f32_16x16x32_bf16 v[40:43], v[170:173], v[84:87], v[40:43]
	v_mfma_f32_16x16x32_bf16 v[36:39], v[138:141], v[92:95], v[36:39]
	v_mfma_f32_16x16x32_bf16 v[32:35], v[170:173], v[92:95], v[32:35]
	v_mfma_f32_16x16x32_bf16 v[28:31], v[130:133], v[64:67], v[28:31]
	v_mfma_f32_16x16x32_bf16 v[24:27], v[208:211], v[64:67], v[24:27]
	v_mfma_f32_16x16x32_bf16 v[20:23], v[130:133], v[72:75], v[20:23]
	v_mfma_f32_16x16x32_bf16 v[16:19], v[208:211], v[72:75], v[16:19]
	v_mfma_f32_16x16x32_bf16 v[12:15], v[130:133], v[80:83], v[12:15]
	v_mfma_f32_16x16x32_bf16 v[8:11], v[208:211], v[80:83], v[8:11]
	v_mfma_f32_16x16x32_bf16 v[4:7], v[130:133], v[88:91], v[4:7]
	v_mfma_f32_16x16x32_bf16 v[0:3], v[208:211], v[88:91], v[0:3]
	v_mfma_f32_16x16x32_bf16 v[134:137], v[166:169], v[68:71], v[28:31]
	v_mfma_f32_16x16x32_bf16 v[138:141], v[162:165], v[68:71], v[24:27]
	v_mfma_f32_16x16x32_bf16 v[158:161], v[166:169], v[76:79], v[20:23]
	v_mfma_f32_16x16x32_bf16 v[170:173], v[162:165], v[76:79], v[16:19]
	v_mfma_f32_16x16x32_bf16 v[204:207], v[166:169], v[84:87], v[12:15]
	v_mfma_f32_16x16x32_bf16 v[216:219], v[162:165], v[84:87], v[8:11]
	v_mfma_f32_16x16x32_bf16 v[130:133], v[166:169], v[92:95], v[4:7]
	v_mfma_f32_16x16x32_bf16 v[162:165], v[162:165], v[92:95], v[0:3]
	s_barrier
	ds_read_b128 v[12:15], v156
	ds_read_b128 v[28:31], v156 offset:1024
	ds_read_b128 v[166:169], v156 offset:2048
	ds_read_b128 v[208:211], v156 offset:3072
	ds_read_b128 v[0:3], v151 offset:32768
	ds_read_b128 v[4:7], v151 offset:33792
	ds_read_b128 v[8:11], v150 offset:32768
	ds_read_b128 v[16:19], v150 offset:33792
	ds_read_b128 v[20:23], v149 offset:32768
	ds_read_b128 v[24:27], v149 offset:33792
	ds_read_b128 v[220:223], v148 offset:32768
	ds_read_b128 v[224:227], v148 offset:33792
	s_waitcnt vmcnt(2)
	s_barrier
; #define WAIT_V(n) asm volatile("s_waitcnt vmcnt(" #n ")" ::: "memory")
; #define WAIT_L(n) asm volatile("s_waitcnt lgkmcnt(" #n ")" ::: "memory")
; #define BAR __builtin_amdgcn_s_barrier()
;     ...
;     { LDB(B0, 1, 0); LDA(At, 1, 0); WAIT_V(2); BAR; WAIT_L(0); MMA(0, 0, At, B0); BAR;
;       LDB(B1, 1, 1); WAIT_V(0); BAR; WAIT_L(0); MMA(0, 1, At, B1); BAR;
;       LDA(At, 1, 1); BAR; WAIT_L(0); MMA(1, 0, At, B0); MMA(1, 1, At, B1); BAR; }
;     if (wr == 0) BAR;
	s_waitcnt lgkmcnt(0)
	s_waitcnt lgkmcnt(0)
	v_mfma_f32_16x16x32_bf16 v[68:71], v[166:169], v[0:3], v[120:123]
	v_mfma_f32_16x16x32_bf16 v[72:75], v[166:169], v[8:11], v[112:115]
	v_mfma_f32_16x16x32_bf16 v[76:79], v[166:169], v[20:23], v[104:107]
	v_mfma_f32_16x16x32_bf16 v[64:67], v[12:15], v[0:3], v[124:127]
	v_mfma_f32_16x16x32_bf16 v[80:83], v[208:211], v[4:7], v[68:71]
	v_mfma_f32_16x16x32_bf16 v[68:71], v[12:15], v[8:11], v[116:119]
	v_mfma_f32_16x16x32_bf16 v[84:87], v[208:211], v[16:19], v[72:75]
	v_mfma_f32_16x16x32_bf16 v[72:75], v[12:15], v[20:23], v[108:111]
	v_mfma_f32_16x16x32_bf16 v[88:91], v[208:211], v[24:27], v[76:79]
	v_mfma_f32_16x16x32_bf16 v[76:79], v[12:15], v[220:223], v[100:103]
	v_mfma_f32_16x16x32_bf16 v[92:95], v[166:169], v[220:223], v[96:99]
	v_mfma_f32_16x16x32_bf16 v[64:67], v[28:31], v[4:7], v[64:67]
	v_mfma_f32_16x16x32_bf16 v[68:71], v[28:31], v[16:19], v[68:71]
	v_mfma_f32_16x16x32_bf16 v[72:75], v[28:31], v[24:27], v[72:75]
	v_mfma_f32_16x16x32_bf16 v[76:79], v[28:31], v[224:227], v[76:79]
	v_mfma_f32_16x16x32_bf16 v[92:95], v[208:211], v[224:227], v[92:95]
	s_barrier
	ds_read_b128 v[228:231], v154
	ds_read_b128 v[232:235], v154 offset:1024
	ds_read_b128 v[236:239], v154 offset:2048
	ds_read_b128 v[152:155], v154 offset:3072
	s_waitcnt vmcnt(0)
	s_barrier
	s_waitcnt lgkmcnt(0)
	s_waitcnt lgkmcnt(0)
	v_mfma_f32_16x16x32_bf16 v[96:99], v[228:231], v[0:3], v[212:215]
	v_mfma_f32_16x16x32_bf16 v[0:3], v[236:239], v[0:3], v[174:177]
	v_mfma_f32_16x16x32_bf16 v[112:115], v[152:155], v[4:7], v[0:3]
	v_mfma_f32_16x16x32_bf16 v[0:3], v[228:231], v[8:11], v[178:181]
	v_mfma_f32_16x16x32_bf16 v[100:103], v[232:235], v[16:19], v[0:3]
	v_mfma_f32_16x16x32_bf16 v[0:3], v[236:239], v[8:11], v[182:185]
	v_mfma_f32_16x16x32_bf16 v[116:119], v[152:155], v[16:19], v[0:3]
	v_mfma_f32_16x16x32_bf16 v[0:3], v[228:231], v[20:23], v[186:189]
	v_mfma_f32_16x16x32_bf16 v[104:107], v[232:235], v[24:27], v[0:3]
	v_mfma_f32_16x16x32_bf16 v[0:3], v[236:239], v[20:23], v[190:193]
	v_mfma_f32_16x16x32_bf16 v[120:123], v[152:155], v[24:27], v[0:3]
	v_mfma_f32_16x16x32_bf16 v[0:3], v[228:231], v[220:223], v[196:199]
	v_mfma_f32_16x16x32_bf16 v[108:111], v[232:235], v[224:227], v[0:3]
	v_mfma_f32_16x16x32_bf16 v[0:3], v[236:239], v[220:223], v[200:203]
	v_mfma_f32_16x16x32_bf16 v[96:99], v[232:235], v[4:7], v[96:99]
	v_mfma_f32_16x16x32_bf16 v[124:127], v[152:155], v[224:227], v[0:3]
	s_barrier
	ds_read_b128 v[174:177], v151 offset:49152
	ds_read_b128 v[178:181], v151 offset:50176
	ds_read_b128 v[182:185], v150 offset:49152
	ds_read_b128 v[186:189], v150 offset:50176
	ds_read_b128 v[190:193], v149 offset:49152
	ds_read_b128 v[196:199], v149 offset:50176
	ds_read_b128 v[200:203], v148 offset:49152
	ds_read_b128 v[148:151], v148 offset:50176
	s_barrier
	s_waitcnt lgkmcnt(0)
	s_waitcnt lgkmcnt(0)
	v_mfma_f32_16x16x32_bf16 v[4:7], v[166:169], v[174:177], v[56:59]
	v_mfma_f32_16x16x32_bf16 v[8:11], v[166:169], v[182:185], v[48:51]
	v_mfma_f32_16x16x32_bf16 v[0:3], v[12:15], v[174:177], v[60:63]
	v_mfma_f32_16x16x32_bf16 v[16:19], v[208:211], v[178:181], v[4:7]
	v_mfma_f32_16x16x32_bf16 v[4:7], v[12:15], v[182:185], v[52:55]
	v_mfma_f32_16x16x32_bf16 v[20:23], v[208:211], v[186:189], v[8:11]
	v_mfma_f32_16x16x32_bf16 v[8:11], v[12:15], v[190:193], v[44:47]
	v_mfma_f32_16x16x32_bf16 v[12:15], v[12:15], v[200:203], v[36:39]
	v_mfma_f32_16x16x32_bf16 v[0:3], v[28:31], v[178:181], v[0:3]
	v_mfma_f32_16x16x32_bf16 v[4:7], v[28:31], v[186:189], v[4:7]
	v_mfma_f32_16x16x32_bf16 v[8:11], v[28:31], v[196:199], v[8:11]
	v_mfma_f32_16x16x32_bf16 v[24:27], v[166:169], v[190:193], v[40:43]
	v_mfma_f32_16x16x32_bf16 v[12:15], v[28:31], v[148:151], v[12:15]
	v_mfma_f32_16x16x32_bf16 v[28:31], v[166:169], v[200:203], v[32:35]
	v_mfma_f32_16x16x32_bf16 v[24:27], v[208:211], v[196:199], v[24:27]
	v_mfma_f32_16x16x32_bf16 v[28:31], v[208:211], v[148:151], v[28:31]
	v_mfma_f32_16x16x32_bf16 v[36:39], v[236:239], v[174:177], v[138:141]
	v_mfma_f32_16x16x32_bf16 v[40:43], v[236:239], v[182:185], v[170:173]
	v_mfma_f32_16x16x32_bf16 v[44:47], v[236:239], v[190:193], v[216:219]
	v_mfma_f32_16x16x32_bf16 v[32:35], v[228:231], v[174:177], v[134:137]
	v_mfma_f32_16x16x32_bf16 v[48:51], v[152:155], v[178:181], v[36:39]
	v_mfma_f32_16x16x32_bf16 v[36:39], v[228:231], v[182:185], v[158:161]
	v_mfma_f32_16x16x32_bf16 v[52:55], v[152:155], v[186:189], v[40:43]
	v_mfma_f32_16x16x32_bf16 v[40:43], v[228:231], v[190:193], v[204:207]
	v_mfma_f32_16x16x32_bf16 v[56:59], v[152:155], v[196:199], v[44:47]
	v_mfma_f32_16x16x32_bf16 v[44:47], v[228:231], v[200:203], v[130:133]
	v_mfma_f32_16x16x32_bf16 v[60:63], v[236:239], v[200:203], v[162:165]
	v_mfma_f32_16x16x32_bf16 v[32:35], v[232:235], v[178:181], v[32:35]
	v_mfma_f32_16x16x32_bf16 v[36:39], v[232:235], v[186:189], v[36:39]
	v_mfma_f32_16x16x32_bf16 v[40:43], v[232:235], v[196:199], v[40:43]
	v_mfma_f32_16x16x32_bf16 v[44:47], v[232:235], v[148:151], v[44:47]
	v_mfma_f32_16x16x32_bf16 v[60:63], v[152:155], v[148:151], v[60:63]
	s_setprio 0
	v_cmp_gt_u32_e32 vcc, s31, v128
	s_barrier
	s_and_saveexec_b64 s[20:21], vcc
	s_cbranch_execz .LBB0_648
	s_barrier
	s_branch .LBB0_648
